# decode V loop rewritten (25 row loads in flight), P3 decode+conv desynchronised across workgroups, adaLN mod unit loops rewritten (loads in flight)
# speedup vs baseline: 1.0293x; 1.0293x over previous
; DI float silu(float x) { return x / (1.0f + __expf(-x)); }
; DI void p0_mod_unit(const Params& p, int u, LAS unsigned char* ldsb) {
;     ...
;     const int l = u / 96, rem = u % 96, nb = rem >> 1, bh = rem & 1;
;     const float* aw = l ? p.in[17] : p.in[10]; const float* ab = l ? p.in[18] : p.in[11];
;     float* MOD = (float*)(p.ws + WS_MOD);
;     for (int idx = tid; idx < 18 * 1024; idx += NTHREADS) { const int i = idx >> 10, k = idx & 1023, bi = bh * 18 + i;
;         const float c = bi < 4 ? p.in[2][bi * 1024 + k] : p.in[3][(bi - 4) * 1024 + k]; lds[idx] = silu(c); }
.LBB0_20:
	s_mul_hi_i32 s6, s86, 0x2aaaaaab
	s_lshr_b32 s7, s6, 31
	s_ashr_i32 s87, s6, 4
	s_add_i32 s87, s87, s7
	s_mul_i32 s6, s87, 0x60
	s_sub_i32 s89, s86, s6
	v_mov_b32_e32 v167, v226
	s_and_b32 s88, s89, 1
	s_mul_i32 s88, s88, 18
	v_cmp_gt_i32_e32 vcc, s3, v167
	s_and_saveexec_b64 s[6:7], vcc
	s_cbranch_execz .LBB0_27
	v_lshl_add_u32 v40, v167, 2, 0
	v_add_u32_e32 v41, 0x10000, v40
	s_waitcnt lgkmcnt(0)
	s_add_i32 s18, s88, 0
	s_cmp_lt_i32 s18, 4
	s_cselect_b32 s16, s72, s74
	s_cselect_b32 s17, s73, s75
	s_cselect_b32 s19, 0, 4
	s_sub_i32 s18, s18, s19
	s_lshl_b32 s18, s18, 12
	s_add_u32 s16, s16, s18
	s_addc_u32 s17, s17, 0
	global_load_dword v0, v40, s[16:17]
	global_load_dword v1, v40, s[16:17] offset:2048
	s_add_i32 s18, s88, 1
	s_cmp_lt_i32 s18, 4
	s_cselect_b32 s16, s72, s74
	s_cselect_b32 s17, s73, s75
	s_cselect_b32 s19, 0, 4
	s_sub_i32 s18, s18, s19
	s_lshl_b32 s18, s18, 12
	s_add_u32 s16, s16, s18
	s_addc_u32 s17, s17, 0
	global_load_dword v2, v40, s[16:17]
	global_load_dword v3, v40, s[16:17] offset:2048
	s_add_i32 s18, s88, 2
	s_cmp_lt_i32 s18, 4
	s_cselect_b32 s16, s72, s74
	s_cselect_b32 s17, s73, s75
	s_cselect_b32 s19, 0, 4
	s_sub_i32 s18, s18, s19
	s_lshl_b32 s18, s18, 12
	s_add_u32 s16, s16, s18
	s_addc_u32 s17, s17, 0
	global_load_dword v4, v40, s[16:17]
	global_load_dword v5, v40, s[16:17] offset:2048
	s_add_i32 s18, s88, 3
	s_cmp_lt_i32 s18, 4
	s_cselect_b32 s16, s72, s74
	s_cselect_b32 s17, s73, s75
	s_cselect_b32 s19, 0, 4
	s_sub_i32 s18, s18, s19
	s_lshl_b32 s18, s18, 12
	s_add_u32 s16, s16, s18
	s_addc_u32 s17, s17, 0
	global_load_dword v6, v40, s[16:17]
	global_load_dword v7, v40, s[16:17] offset:2048
	s_add_i32 s18, s88, 4
	s_cmp_lt_i32 s18, 4
	s_cselect_b32 s16, s72, s74
	s_cselect_b32 s17, s73, s75
	s_cselect_b32 s19, 0, 4
	s_sub_i32 s18, s18, s19
	s_lshl_b32 s18, s18, 12
	s_add_u32 s16, s16, s18
	s_addc_u32 s17, s17, 0
	global_load_dword v8, v40, s[16:17]
	global_load_dword v9, v40, s[16:17] offset:2048
	s_add_i32 s18, s88, 5
	s_cmp_lt_i32 s18, 4
	s_cselect_b32 s16, s72, s74
	s_cselect_b32 s17, s73, s75
	s_cselect_b32 s19, 0, 4
	s_sub_i32 s18, s18, s19
	s_lshl_b32 s18, s18, 12
	s_add_u32 s16, s16, s18
	s_addc_u32 s17, s17, 0
	global_load_dword v10, v40, s[16:17]
	global_load_dword v11, v40, s[16:17] offset:2048
	s_add_i32 s18, s88, 6
	s_cmp_lt_i32 s18, 4
	s_cselect_b32 s16, s72, s74
	s_cselect_b32 s17, s73, s75
	s_cselect_b32 s19, 0, 4
	s_sub_i32 s18, s18, s19
	s_lshl_b32 s18, s18, 12
	s_add_u32 s16, s16, s18
	s_addc_u32 s17, s17, 0
	global_load_dword v12, v40, s[16:17]
	global_load_dword v13, v40, s[16:17] offset:2048
	s_add_i32 s18, s88, 7
	s_cmp_lt_i32 s18, 4
	s_cselect_b32 s16, s72, s74
	s_cselect_b32 s17, s73, s75
	s_cselect_b32 s19, 0, 4
	s_sub_i32 s18, s18, s19
	s_lshl_b32 s18, s18, 12
	s_add_u32 s16, s16, s18
	s_addc_u32 s17, s17, 0
	global_load_dword v14, v40, s[16:17]
	global_load_dword v15, v40, s[16:17] offset:2048
	s_add_i32 s18, s88, 8
	s_cmp_lt_i32 s18, 4
	s_cselect_b32 s16, s72, s74
	s_cselect_b32 s17, s73, s75
	s_cselect_b32 s19, 0, 4
	s_sub_i32 s18, s18, s19
	s_lshl_b32 s18, s18, 12
	s_add_u32 s16, s16, s18
	s_addc_u32 s17, s17, 0
	global_load_dword v16, v40, s[16:17]
	global_load_dword v17, v40, s[16:17] offset:2048
	s_add_i32 s18, s88, 9
	s_cmp_lt_i32 s18, 4
	s_cselect_b32 s16, s72, s74
	s_cselect_b32 s17, s73, s75
	s_cselect_b32 s19, 0, 4
	s_sub_i32 s18, s18, s19
	s_lshl_b32 s18, s18, 12
	s_add_u32 s16, s16, s18
	s_addc_u32 s17, s17, 0
	global_load_dword v18, v40, s[16:17]
	global_load_dword v19, v40, s[16:17] offset:2048
	s_add_i32 s18, s88, 10
	s_cmp_lt_i32 s18, 4
	s_cselect_b32 s16, s72, s74
	s_cselect_b32 s17, s73, s75
	s_cselect_b32 s19, 0, 4
	s_sub_i32 s18, s18, s19
	s_lshl_b32 s18, s18, 12
	s_add_u32 s16, s16, s18
	s_addc_u32 s17, s17, 0
	global_load_dword v20, v40, s[16:17]
	global_load_dword v21, v40, s[16:17] offset:2048
	s_add_i32 s18, s88, 11
	s_cmp_lt_i32 s18, 4
	s_cselect_b32 s16, s72, s74
	s_cselect_b32 s17, s73, s75
	s_cselect_b32 s19, 0, 4
	s_sub_i32 s18, s18, s19
	s_lshl_b32 s18, s18, 12
	s_add_u32 s16, s16, s18
	s_addc_u32 s17, s17, 0
	global_load_dword v22, v40, s[16:17]
	global_load_dword v23, v40, s[16:17] offset:2048
	s_add_i32 s18, s88, 12
	s_cmp_lt_i32 s18, 4
	s_cselect_b32 s16, s72, s74
	s_cselect_b32 s17, s73, s75
	s_cselect_b32 s19, 0, 4
	s_sub_i32 s18, s18, s19
	s_lshl_b32 s18, s18, 12
	s_add_u32 s16, s16, s18
	s_addc_u32 s17, s17, 0
	global_load_dword v24, v40, s[16:17]
	global_load_dword v25, v40, s[16:17] offset:2048
	s_add_i32 s18, s88, 13
	s_cmp_lt_i32 s18, 4
	s_cselect_b32 s16, s72, s74
	s_cselect_b32 s17, s73, s75
	s_cselect_b32 s19, 0, 4
	s_sub_i32 s18, s18, s19
	s_lshl_b32 s18, s18, 12
	s_add_u32 s16, s16, s18
	s_addc_u32 s17, s17, 0
	global_load_dword v26, v40, s[16:17]
	global_load_dword v27, v40, s[16:17] offset:2048
	s_add_i32 s18, s88, 14
	s_cmp_lt_i32 s18, 4
	s_cselect_b32 s16, s72, s74
	s_cselect_b32 s17, s73, s75
	s_cselect_b32 s19, 0, 4
	s_sub_i32 s18, s18, s19
	s_lshl_b32 s18, s18, 12
	s_add_u32 s16, s16, s18
	s_addc_u32 s17, s17, 0
	global_load_dword v28, v40, s[16:17]
	global_load_dword v29, v40, s[16:17] offset:2048
	s_add_i32 s18, s88, 15
	s_cmp_lt_i32 s18, 4
	s_cselect_b32 s16, s72, s74
	s_cselect_b32 s17, s73, s75
	s_cselect_b32 s19, 0, 4
	s_sub_i32 s18, s18, s19
	s_lshl_b32 s18, s18, 12
	s_add_u32 s16, s16, s18
	s_addc_u32 s17, s17, 0
	global_load_dword v30, v40, s[16:17]
	global_load_dword v31, v40, s[16:17] offset:2048
	s_add_i32 s18, s88, 16
	s_cmp_lt_i32 s18, 4
	s_cselect_b32 s16, s72, s74
	s_cselect_b32 s17, s73, s75
	s_cselect_b32 s19, 0, 4
	s_sub_i32 s18, s18, s19
	s_lshl_b32 s18, s18, 12
	s_add_u32 s16, s16, s18
	s_addc_u32 s17, s17, 0
	global_load_dword v32, v40, s[16:17]
	global_load_dword v33, v40, s[16:17] offset:2048
	s_add_i32 s18, s88, 17
	s_cmp_lt_i32 s18, 4
	s_cselect_b32 s16, s72, s74
	s_cselect_b32 s17, s73, s75
	s_cselect_b32 s19, 0, 4
	s_sub_i32 s18, s18, s19
	s_lshl_b32 s18, s18, 12
	s_add_u32 s16, s16, s18
	s_addc_u32 s17, s17, 0
	global_load_dword v34, v40, s[16:17]
	global_load_dword v35, v40, s[16:17] offset:2048
	s_waitcnt vmcnt(35)
; DI float silu(float x) { return x / (1.0f + __expf(-x)); }
; DI void p0_mod_unit(const Params& p, int u, LAS unsigned char* ldsb) {
;     ...
;         const float c = bi < 4 ? p.in[2][bi * 1024 + k] : p.in[3][(bi - 4) * 1024 + k]; lds[idx] = silu(c); }
	v_mul_f32_e32 v42, 0xbfb8aa3b, v0
	v_exp_f32_e32 v42, v42
	s_nop 0
	v_add_f32_e32 v42, 1.0, v42
	v_div_scale_f32 v43, s[10:11], v42, v42, v0
	v_rcp_f32_e32 v45, v43
	v_div_scale_f32 v46, vcc, v0, v42, v0
	v_fma_f32 v47, -v43, v45, 1.0
	v_fmac_f32_e32 v45, v47, v45
	v_mul_f32_e32 v47, v46, v45
	v_fma_f32 v48, -v43, v47, v46
	v_fmac_f32_e32 v47, v48, v45
	v_fma_f32 v43, -v43, v47, v46
	v_div_fmas_f32 v43, v43, v45, v47
	v_div_fixup_f32 v44, v43, v42, v0
	ds_write_b32 v40, v44 offset:0
	s_waitcnt vmcnt(34)
	v_mul_f32_e32 v42, 0xbfb8aa3b, v1
	v_exp_f32_e32 v42, v42
	s_nop 0
	v_add_f32_e32 v42, 1.0, v42
	v_div_scale_f32 v43, s[10:11], v42, v42, v1
	v_rcp_f32_e32 v45, v43
	v_div_scale_f32 v46, vcc, v1, v42, v1
	v_fma_f32 v47, -v43, v45, 1.0
	v_fmac_f32_e32 v45, v47, v45
	v_mul_f32_e32 v47, v46, v45
	v_fma_f32 v48, -v43, v47, v46
	v_fmac_f32_e32 v47, v48, v45
	v_fma_f32 v43, -v43, v47, v46
	v_div_fmas_f32 v43, v43, v45, v47
	v_div_fixup_f32 v44, v43, v42, v1
	ds_write_b32 v40, v44 offset:2048
	s_waitcnt vmcnt(33)
	v_mul_f32_e32 v42, 0xbfb8aa3b, v2
	v_exp_f32_e32 v42, v42
	s_nop 0
	v_add_f32_e32 v42, 1.0, v42
	v_div_scale_f32 v43, s[10:11], v42, v42, v2
	v_rcp_f32_e32 v45, v43
	v_div_scale_f32 v46, vcc, v2, v42, v2
	v_fma_f32 v47, -v43, v45, 1.0
	v_fmac_f32_e32 v45, v47, v45
	v_mul_f32_e32 v47, v46, v45
	v_fma_f32 v48, -v43, v47, v46
	v_fmac_f32_e32 v47, v48, v45
	v_fma_f32 v43, -v43, v47, v46
	v_div_fmas_f32 v43, v43, v45, v47
	v_div_fixup_f32 v44, v43, v42, v2
	ds_write_b32 v40, v44 offset:4096
	s_waitcnt vmcnt(32)
	v_mul_f32_e32 v42, 0xbfb8aa3b, v3
	v_exp_f32_e32 v42, v42
	s_nop 0
	v_add_f32_e32 v42, 1.0, v42
	v_div_scale_f32 v43, s[10:11], v42, v42, v3
	v_rcp_f32_e32 v45, v43
	v_div_scale_f32 v46, vcc, v3, v42, v3
	v_fma_f32 v47, -v43, v45, 1.0
	v_fmac_f32_e32 v45, v47, v45
	v_mul_f32_e32 v47, v46, v45
	v_fma_f32 v48, -v43, v47, v46
	v_fmac_f32_e32 v47, v48, v45
	v_fma_f32 v43, -v43, v47, v46
	v_div_fmas_f32 v43, v43, v45, v47
	v_div_fixup_f32 v44, v43, v42, v3
	ds_write_b32 v40, v44 offset:6144
	s_waitcnt vmcnt(31)
	v_mul_f32_e32 v42, 0xbfb8aa3b, v4
	v_exp_f32_e32 v42, v42
	s_nop 0
	v_add_f32_e32 v42, 1.0, v42
	v_div_scale_f32 v43, s[10:11], v42, v42, v4
	v_rcp_f32_e32 v45, v43
	v_div_scale_f32 v46, vcc, v4, v42, v4
	v_fma_f32 v47, -v43, v45, 1.0
	v_fmac_f32_e32 v45, v47, v45
	v_mul_f32_e32 v47, v46, v45
	v_fma_f32 v48, -v43, v47, v46
	v_fmac_f32_e32 v47, v48, v45
	v_fma_f32 v43, -v43, v47, v46
	v_div_fmas_f32 v43, v43, v45, v47
	v_div_fixup_f32 v44, v43, v42, v4
	ds_write_b32 v40, v44 offset:8192
	s_waitcnt vmcnt(30)
	v_mul_f32_e32 v42, 0xbfb8aa3b, v5
	v_exp_f32_e32 v42, v42
	s_nop 0
	v_add_f32_e32 v42, 1.0, v42
	v_div_scale_f32 v43, s[10:11], v42, v42, v5
	v_rcp_f32_e32 v45, v43
	v_div_scale_f32 v46, vcc, v5, v42, v5
	v_fma_f32 v47, -v43, v45, 1.0
	v_fmac_f32_e32 v45, v47, v45
	v_mul_f32_e32 v47, v46, v45
	v_fma_f32 v48, -v43, v47, v46
	v_fmac_f32_e32 v47, v48, v45
	v_fma_f32 v43, -v43, v47, v46
	v_div_fmas_f32 v43, v43, v45, v47
	v_div_fixup_f32 v44, v43, v42, v5
	ds_write_b32 v40, v44 offset:10240
	s_waitcnt vmcnt(29)
	v_mul_f32_e32 v42, 0xbfb8aa3b, v6
	v_exp_f32_e32 v42, v42
	s_nop 0
	v_add_f32_e32 v42, 1.0, v42
	v_div_scale_f32 v43, s[10:11], v42, v42, v6
	v_rcp_f32_e32 v45, v43
	v_div_scale_f32 v46, vcc, v6, v42, v6
	v_fma_f32 v47, -v43, v45, 1.0
	v_fmac_f32_e32 v45, v47, v45
	v_mul_f32_e32 v47, v46, v45
	v_fma_f32 v48, -v43, v47, v46
	v_fmac_f32_e32 v47, v48, v45
	v_fma_f32 v43, -v43, v47, v46
	v_div_fmas_f32 v43, v43, v45, v47
	v_div_fixup_f32 v44, v43, v42, v6
	ds_write_b32 v40, v44 offset:12288
	s_waitcnt vmcnt(28)
	v_mul_f32_e32 v42, 0xbfb8aa3b, v7
	v_exp_f32_e32 v42, v42
	s_nop 0
	v_add_f32_e32 v42, 1.0, v42
	v_div_scale_f32 v43, s[10:11], v42, v42, v7
	v_rcp_f32_e32 v45, v43
	v_div_scale_f32 v46, vcc, v7, v42, v7
	v_fma_f32 v47, -v43, v45, 1.0
	v_fmac_f32_e32 v45, v47, v45
	v_mul_f32_e32 v47, v46, v45
	v_fma_f32 v48, -v43, v47, v46
	v_fmac_f32_e32 v47, v48, v45
	v_fma_f32 v43, -v43, v47, v46
	v_div_fmas_f32 v43, v43, v45, v47
	v_div_fixup_f32 v44, v43, v42, v7
	ds_write_b32 v40, v44 offset:14336
	s_waitcnt vmcnt(27)
	v_mul_f32_e32 v42, 0xbfb8aa3b, v8
	v_exp_f32_e32 v42, v42
	s_nop 0
	v_add_f32_e32 v42, 1.0, v42
	v_div_scale_f32 v43, s[10:11], v42, v42, v8
	v_rcp_f32_e32 v45, v43
	v_div_scale_f32 v46, vcc, v8, v42, v8
	v_fma_f32 v47, -v43, v45, 1.0
	v_fmac_f32_e32 v45, v47, v45
	v_mul_f32_e32 v47, v46, v45
	v_fma_f32 v48, -v43, v47, v46
	v_fmac_f32_e32 v47, v48, v45
	v_fma_f32 v43, -v43, v47, v46
	v_div_fmas_f32 v43, v43, v45, v47
	v_div_fixup_f32 v44, v43, v42, v8
	ds_write_b32 v40, v44 offset:16384
	s_waitcnt vmcnt(26)
	v_mul_f32_e32 v42, 0xbfb8aa3b, v9
	v_exp_f32_e32 v42, v42
	s_nop 0
	v_add_f32_e32 v42, 1.0, v42
	v_div_scale_f32 v43, s[10:11], v42, v42, v9
	v_rcp_f32_e32 v45, v43
	v_div_scale_f32 v46, vcc, v9, v42, v9
	v_fma_f32 v47, -v43, v45, 1.0
	v_fmac_f32_e32 v45, v47, v45
	v_mul_f32_e32 v47, v46, v45
	v_fma_f32 v48, -v43, v47, v46
	v_fmac_f32_e32 v47, v48, v45
	v_fma_f32 v43, -v43, v47, v46
	v_div_fmas_f32 v43, v43, v45, v47
	v_div_fixup_f32 v44, v43, v42, v9
	ds_write_b32 v40, v44 offset:18432
	s_waitcnt vmcnt(25)
	v_mul_f32_e32 v42, 0xbfb8aa3b, v10
	v_exp_f32_e32 v42, v42
	s_nop 0
	v_add_f32_e32 v42, 1.0, v42
	v_div_scale_f32 v43, s[10:11], v42, v42, v10
	v_rcp_f32_e32 v45, v43
	v_div_scale_f32 v46, vcc, v10, v42, v10
	v_fma_f32 v47, -v43, v45, 1.0
	v_fmac_f32_e32 v45, v47, v45
	v_mul_f32_e32 v47, v46, v45
	v_fma_f32 v48, -v43, v47, v46
	v_fmac_f32_e32 v47, v48, v45
	v_fma_f32 v43, -v43, v47, v46
	v_div_fmas_f32 v43, v43, v45, v47
	v_div_fixup_f32 v44, v43, v42, v10
	ds_write_b32 v40, v44 offset:20480
	s_waitcnt vmcnt(24)
; DI float silu(float x) { return x / (1.0f + __expf(-x)); }
; DI void p0_mod_unit(const Params& p, int u, LAS unsigned char* ldsb) {
;     ...
;         const float c = bi < 4 ? p.in[2][bi * 1024 + k] : p.in[3][(bi - 4) * 1024 + k]; lds[idx] = silu(c); }
	v_mul_f32_e32 v42, 0xbfb8aa3b, v11
	v_exp_f32_e32 v42, v42
	s_nop 0
	v_add_f32_e32 v42, 1.0, v42
	v_div_scale_f32 v43, s[10:11], v42, v42, v11
	v_rcp_f32_e32 v45, v43
	v_div_scale_f32 v46, vcc, v11, v42, v11
	v_fma_f32 v47, -v43, v45, 1.0
	v_fmac_f32_e32 v45, v47, v45
	v_mul_f32_e32 v47, v46, v45
	v_fma_f32 v48, -v43, v47, v46
	v_fmac_f32_e32 v47, v48, v45
	v_fma_f32 v43, -v43, v47, v46
	v_div_fmas_f32 v43, v43, v45, v47
	v_div_fixup_f32 v44, v43, v42, v11
	ds_write_b32 v40, v44 offset:22528
	s_waitcnt vmcnt(23)
	v_mul_f32_e32 v42, 0xbfb8aa3b, v12
	v_exp_f32_e32 v42, v42
	s_nop 0
	v_add_f32_e32 v42, 1.0, v42
	v_div_scale_f32 v43, s[10:11], v42, v42, v12
	v_rcp_f32_e32 v45, v43
	v_div_scale_f32 v46, vcc, v12, v42, v12
	v_fma_f32 v47, -v43, v45, 1.0
	v_fmac_f32_e32 v45, v47, v45
	v_mul_f32_e32 v47, v46, v45
	v_fma_f32 v48, -v43, v47, v46
	v_fmac_f32_e32 v47, v48, v45
	v_fma_f32 v43, -v43, v47, v46
	v_div_fmas_f32 v43, v43, v45, v47
	v_div_fixup_f32 v44, v43, v42, v12
	ds_write_b32 v40, v44 offset:24576
	s_waitcnt vmcnt(22)
	v_mul_f32_e32 v42, 0xbfb8aa3b, v13
	v_exp_f32_e32 v42, v42
	s_nop 0
	v_add_f32_e32 v42, 1.0, v42
	v_div_scale_f32 v43, s[10:11], v42, v42, v13
	v_rcp_f32_e32 v45, v43
	v_div_scale_f32 v46, vcc, v13, v42, v13
	v_fma_f32 v47, -v43, v45, 1.0
	v_fmac_f32_e32 v45, v47, v45
	v_mul_f32_e32 v47, v46, v45
	v_fma_f32 v48, -v43, v47, v46
	v_fmac_f32_e32 v47, v48, v45
	v_fma_f32 v43, -v43, v47, v46
	v_div_fmas_f32 v43, v43, v45, v47
	v_div_fixup_f32 v44, v43, v42, v13
	ds_write_b32 v40, v44 offset:26624
	s_waitcnt vmcnt(21)
	v_mul_f32_e32 v42, 0xbfb8aa3b, v14
	v_exp_f32_e32 v42, v42
	s_nop 0
	v_add_f32_e32 v42, 1.0, v42
	v_div_scale_f32 v43, s[10:11], v42, v42, v14
	v_rcp_f32_e32 v45, v43
	v_div_scale_f32 v46, vcc, v14, v42, v14
	v_fma_f32 v47, -v43, v45, 1.0
	v_fmac_f32_e32 v45, v47, v45
	v_mul_f32_e32 v47, v46, v45
	v_fma_f32 v48, -v43, v47, v46
	v_fmac_f32_e32 v47, v48, v45
	v_fma_f32 v43, -v43, v47, v46
	v_div_fmas_f32 v43, v43, v45, v47
	v_div_fixup_f32 v44, v43, v42, v14
	ds_write_b32 v40, v44 offset:28672
	s_waitcnt vmcnt(20)
	v_mul_f32_e32 v42, 0xbfb8aa3b, v15
	v_exp_f32_e32 v42, v42
	s_nop 0
	v_add_f32_e32 v42, 1.0, v42
	v_div_scale_f32 v43, s[10:11], v42, v42, v15
	v_rcp_f32_e32 v45, v43
	v_div_scale_f32 v46, vcc, v15, v42, v15
	v_fma_f32 v47, -v43, v45, 1.0
	v_fmac_f32_e32 v45, v47, v45
	v_mul_f32_e32 v47, v46, v45
	v_fma_f32 v48, -v43, v47, v46
	v_fmac_f32_e32 v47, v48, v45
	v_fma_f32 v43, -v43, v47, v46
	v_div_fmas_f32 v43, v43, v45, v47
	v_div_fixup_f32 v44, v43, v42, v15
	ds_write_b32 v40, v44 offset:30720
	s_waitcnt vmcnt(19)
	v_mul_f32_e32 v42, 0xbfb8aa3b, v16
	v_exp_f32_e32 v42, v42
	s_nop 0
	v_add_f32_e32 v42, 1.0, v42
	v_div_scale_f32 v43, s[10:11], v42, v42, v16
	v_rcp_f32_e32 v45, v43
	v_div_scale_f32 v46, vcc, v16, v42, v16
	v_fma_f32 v47, -v43, v45, 1.0
	v_fmac_f32_e32 v45, v47, v45
	v_mul_f32_e32 v47, v46, v45
	v_fma_f32 v48, -v43, v47, v46
	v_fmac_f32_e32 v47, v48, v45
	v_fma_f32 v43, -v43, v47, v46
	v_div_fmas_f32 v43, v43, v45, v47
	v_div_fixup_f32 v44, v43, v42, v16
	ds_write_b32 v40, v44 offset:32768
	s_waitcnt vmcnt(18)
	v_mul_f32_e32 v42, 0xbfb8aa3b, v17
	v_exp_f32_e32 v42, v42
	s_nop 0
	v_add_f32_e32 v42, 1.0, v42
	v_div_scale_f32 v43, s[10:11], v42, v42, v17
	v_rcp_f32_e32 v45, v43
	v_div_scale_f32 v46, vcc, v17, v42, v17
	v_fma_f32 v47, -v43, v45, 1.0
	v_fmac_f32_e32 v45, v47, v45
	v_mul_f32_e32 v47, v46, v45
	v_fma_f32 v48, -v43, v47, v46
	v_fmac_f32_e32 v47, v48, v45
	v_fma_f32 v43, -v43, v47, v46
	v_div_fmas_f32 v43, v43, v45, v47
	v_div_fixup_f32 v44, v43, v42, v17
	ds_write_b32 v40, v44 offset:34816
	s_waitcnt vmcnt(17)
	v_mul_f32_e32 v42, 0xbfb8aa3b, v18
	v_exp_f32_e32 v42, v42
	s_nop 0
	v_add_f32_e32 v42, 1.0, v42
	v_div_scale_f32 v43, s[10:11], v42, v42, v18
	v_rcp_f32_e32 v45, v43
	v_div_scale_f32 v46, vcc, v18, v42, v18
	v_fma_f32 v47, -v43, v45, 1.0
	v_fmac_f32_e32 v45, v47, v45
	v_mul_f32_e32 v47, v46, v45
	v_fma_f32 v48, -v43, v47, v46
	v_fmac_f32_e32 v47, v48, v45
	v_fma_f32 v43, -v43, v47, v46
	v_div_fmas_f32 v43, v43, v45, v47
	v_div_fixup_f32 v44, v43, v42, v18
	ds_write_b32 v40, v44 offset:36864
	s_waitcnt vmcnt(16)
	v_mul_f32_e32 v42, 0xbfb8aa3b, v19
	v_exp_f32_e32 v42, v42
	s_nop 0
	v_add_f32_e32 v42, 1.0, v42
	v_div_scale_f32 v43, s[10:11], v42, v42, v19
	v_rcp_f32_e32 v45, v43
	v_div_scale_f32 v46, vcc, v19, v42, v19
	v_fma_f32 v47, -v43, v45, 1.0
	v_fmac_f32_e32 v45, v47, v45
	v_mul_f32_e32 v47, v46, v45
	v_fma_f32 v48, -v43, v47, v46
	v_fmac_f32_e32 v47, v48, v45
	v_fma_f32 v43, -v43, v47, v46
	v_div_fmas_f32 v43, v43, v45, v47
	v_div_fixup_f32 v44, v43, v42, v19
	ds_write_b32 v40, v44 offset:38912
	s_waitcnt vmcnt(15)
	v_mul_f32_e32 v42, 0xbfb8aa3b, v20
	v_exp_f32_e32 v42, v42
	s_nop 0
	v_add_f32_e32 v42, 1.0, v42
	v_div_scale_f32 v43, s[10:11], v42, v42, v20
	v_rcp_f32_e32 v45, v43
	v_div_scale_f32 v46, vcc, v20, v42, v20
	v_fma_f32 v47, -v43, v45, 1.0
	v_fmac_f32_e32 v45, v47, v45
	v_mul_f32_e32 v47, v46, v45
	v_fma_f32 v48, -v43, v47, v46
	v_fmac_f32_e32 v47, v48, v45
	v_fma_f32 v43, -v43, v47, v46
	v_div_fmas_f32 v43, v43, v45, v47
	v_div_fixup_f32 v44, v43, v42, v20
	ds_write_b32 v40, v44 offset:40960
	s_waitcnt vmcnt(14)
	v_mul_f32_e32 v42, 0xbfb8aa3b, v21
	v_exp_f32_e32 v42, v42
	s_nop 0
	v_add_f32_e32 v42, 1.0, v42
	v_div_scale_f32 v43, s[10:11], v42, v42, v21
	v_rcp_f32_e32 v45, v43
	v_div_scale_f32 v46, vcc, v21, v42, v21
	v_fma_f32 v47, -v43, v45, 1.0
	v_fmac_f32_e32 v45, v47, v45
	v_mul_f32_e32 v47, v46, v45
	v_fma_f32 v48, -v43, v47, v46
	v_fmac_f32_e32 v47, v48, v45
	v_fma_f32 v43, -v43, v47, v46
	v_div_fmas_f32 v43, v43, v45, v47
	v_div_fixup_f32 v44, v43, v42, v21
	ds_write_b32 v40, v44 offset:43008
	s_waitcnt vmcnt(13)
; DI float silu(float x) { return x / (1.0f + __expf(-x)); }
; DI void p0_mod_unit(const Params& p, int u, LAS unsigned char* ldsb) {
;     ...
;         const float c = bi < 4 ? p.in[2][bi * 1024 + k] : p.in[3][(bi - 4) * 1024 + k]; lds[idx] = silu(c); }
	v_mul_f32_e32 v42, 0xbfb8aa3b, v22
	v_exp_f32_e32 v42, v42
	s_nop 0
	v_add_f32_e32 v42, 1.0, v42
	v_div_scale_f32 v43, s[10:11], v42, v42, v22
	v_rcp_f32_e32 v45, v43
	v_div_scale_f32 v46, vcc, v22, v42, v22
	v_fma_f32 v47, -v43, v45, 1.0
	v_fmac_f32_e32 v45, v47, v45
	v_mul_f32_e32 v47, v46, v45
	v_fma_f32 v48, -v43, v47, v46
	v_fmac_f32_e32 v47, v48, v45
	v_fma_f32 v43, -v43, v47, v46
	v_div_fmas_f32 v43, v43, v45, v47
	v_div_fixup_f32 v44, v43, v42, v22
	ds_write_b32 v40, v44 offset:45056
	s_waitcnt vmcnt(12)
	v_mul_f32_e32 v42, 0xbfb8aa3b, v23
	v_exp_f32_e32 v42, v42
	s_nop 0
	v_add_f32_e32 v42, 1.0, v42
	v_div_scale_f32 v43, s[10:11], v42, v42, v23
	v_rcp_f32_e32 v45, v43
	v_div_scale_f32 v46, vcc, v23, v42, v23
	v_fma_f32 v47, -v43, v45, 1.0
	v_fmac_f32_e32 v45, v47, v45
	v_mul_f32_e32 v47, v46, v45
	v_fma_f32 v48, -v43, v47, v46
	v_fmac_f32_e32 v47, v48, v45
	v_fma_f32 v43, -v43, v47, v46
	v_div_fmas_f32 v43, v43, v45, v47
	v_div_fixup_f32 v44, v43, v42, v23
	ds_write_b32 v40, v44 offset:47104
	s_waitcnt vmcnt(11)
	v_mul_f32_e32 v42, 0xbfb8aa3b, v24
	v_exp_f32_e32 v42, v42
	s_nop 0
	v_add_f32_e32 v42, 1.0, v42
	v_div_scale_f32 v43, s[10:11], v42, v42, v24
	v_rcp_f32_e32 v45, v43
	v_div_scale_f32 v46, vcc, v24, v42, v24
	v_fma_f32 v47, -v43, v45, 1.0
	v_fmac_f32_e32 v45, v47, v45
	v_mul_f32_e32 v47, v46, v45
	v_fma_f32 v48, -v43, v47, v46
	v_fmac_f32_e32 v47, v48, v45
	v_fma_f32 v43, -v43, v47, v46
	v_div_fmas_f32 v43, v43, v45, v47
	v_div_fixup_f32 v44, v43, v42, v24
	ds_write_b32 v40, v44 offset:49152
	s_waitcnt vmcnt(10)
	v_mul_f32_e32 v42, 0xbfb8aa3b, v25
	v_exp_f32_e32 v42, v42
	s_nop 0
	v_add_f32_e32 v42, 1.0, v42
	v_div_scale_f32 v43, s[10:11], v42, v42, v25
	v_rcp_f32_e32 v45, v43
	v_div_scale_f32 v46, vcc, v25, v42, v25
	v_fma_f32 v47, -v43, v45, 1.0
	v_fmac_f32_e32 v45, v47, v45
	v_mul_f32_e32 v47, v46, v45
	v_fma_f32 v48, -v43, v47, v46
	v_fmac_f32_e32 v47, v48, v45
	v_fma_f32 v43, -v43, v47, v46
	v_div_fmas_f32 v43, v43, v45, v47
	v_div_fixup_f32 v44, v43, v42, v25
	ds_write_b32 v40, v44 offset:51200
	s_waitcnt vmcnt(9)
	v_mul_f32_e32 v42, 0xbfb8aa3b, v26
	v_exp_f32_e32 v42, v42
	s_nop 0
	v_add_f32_e32 v42, 1.0, v42
	v_div_scale_f32 v43, s[10:11], v42, v42, v26
	v_rcp_f32_e32 v45, v43
	v_div_scale_f32 v46, vcc, v26, v42, v26
	v_fma_f32 v47, -v43, v45, 1.0
	v_fmac_f32_e32 v45, v47, v45
	v_mul_f32_e32 v47, v46, v45
	v_fma_f32 v48, -v43, v47, v46
	v_fmac_f32_e32 v47, v48, v45
	v_fma_f32 v43, -v43, v47, v46
	v_div_fmas_f32 v43, v43, v45, v47
	v_div_fixup_f32 v44, v43, v42, v26
	ds_write_b32 v40, v44 offset:53248
	s_waitcnt vmcnt(8)
	v_mul_f32_e32 v42, 0xbfb8aa3b, v27
	v_exp_f32_e32 v42, v42
	s_nop 0
	v_add_f32_e32 v42, 1.0, v42
	v_div_scale_f32 v43, s[10:11], v42, v42, v27
	v_rcp_f32_e32 v45, v43
	v_div_scale_f32 v46, vcc, v27, v42, v27
	v_fma_f32 v47, -v43, v45, 1.0
	v_fmac_f32_e32 v45, v47, v45
	v_mul_f32_e32 v47, v46, v45
	v_fma_f32 v48, -v43, v47, v46
	v_fmac_f32_e32 v47, v48, v45
	v_fma_f32 v43, -v43, v47, v46
	v_div_fmas_f32 v43, v43, v45, v47
	v_div_fixup_f32 v44, v43, v42, v27
	ds_write_b32 v40, v44 offset:55296
	s_waitcnt vmcnt(7)
	v_mul_f32_e32 v42, 0xbfb8aa3b, v28
	v_exp_f32_e32 v42, v42
	s_nop 0
	v_add_f32_e32 v42, 1.0, v42
	v_div_scale_f32 v43, s[10:11], v42, v42, v28
	v_rcp_f32_e32 v45, v43
	v_div_scale_f32 v46, vcc, v28, v42, v28
	v_fma_f32 v47, -v43, v45, 1.0
	v_fmac_f32_e32 v45, v47, v45
	v_mul_f32_e32 v47, v46, v45
	v_fma_f32 v48, -v43, v47, v46
	v_fmac_f32_e32 v47, v48, v45
	v_fma_f32 v43, -v43, v47, v46
	v_div_fmas_f32 v43, v43, v45, v47
	v_div_fixup_f32 v44, v43, v42, v28
	ds_write_b32 v40, v44 offset:57344
	s_waitcnt vmcnt(6)
	v_mul_f32_e32 v42, 0xbfb8aa3b, v29
	v_exp_f32_e32 v42, v42
	s_nop 0
	v_add_f32_e32 v42, 1.0, v42
	v_div_scale_f32 v43, s[10:11], v42, v42, v29
	v_rcp_f32_e32 v45, v43
	v_div_scale_f32 v46, vcc, v29, v42, v29
	v_fma_f32 v47, -v43, v45, 1.0
	v_fmac_f32_e32 v45, v47, v45
	v_mul_f32_e32 v47, v46, v45
	v_fma_f32 v48, -v43, v47, v46
	v_fmac_f32_e32 v47, v48, v45
	v_fma_f32 v43, -v43, v47, v46
	v_div_fmas_f32 v43, v43, v45, v47
	v_div_fixup_f32 v44, v43, v42, v29
	ds_write_b32 v40, v44 offset:59392
	s_waitcnt vmcnt(5)
	v_mul_f32_e32 v42, 0xbfb8aa3b, v30
	v_exp_f32_e32 v42, v42
	s_nop 0
	v_add_f32_e32 v42, 1.0, v42
	v_div_scale_f32 v43, s[10:11], v42, v42, v30
	v_rcp_f32_e32 v45, v43
	v_div_scale_f32 v46, vcc, v30, v42, v30
	v_fma_f32 v47, -v43, v45, 1.0
	v_fmac_f32_e32 v45, v47, v45
	v_mul_f32_e32 v47, v46, v45
	v_fma_f32 v48, -v43, v47, v46
	v_fmac_f32_e32 v47, v48, v45
	v_fma_f32 v43, -v43, v47, v46
	v_div_fmas_f32 v43, v43, v45, v47
	v_div_fixup_f32 v44, v43, v42, v30
	ds_write_b32 v40, v44 offset:61440
	s_waitcnt vmcnt(4)
	v_mul_f32_e32 v42, 0xbfb8aa3b, v31
	v_exp_f32_e32 v42, v42
	s_nop 0
	v_add_f32_e32 v42, 1.0, v42
	v_div_scale_f32 v43, s[10:11], v42, v42, v31
	v_rcp_f32_e32 v45, v43
	v_div_scale_f32 v46, vcc, v31, v42, v31
	v_fma_f32 v47, -v43, v45, 1.0
	v_fmac_f32_e32 v45, v47, v45
	v_mul_f32_e32 v47, v46, v45
	v_fma_f32 v48, -v43, v47, v46
	v_fmac_f32_e32 v47, v48, v45
	v_fma_f32 v43, -v43, v47, v46
	v_div_fmas_f32 v43, v43, v45, v47
	v_div_fixup_f32 v44, v43, v42, v31
	ds_write_b32 v40, v44 offset:63488
	s_waitcnt vmcnt(3)
	v_mul_f32_e32 v42, 0xbfb8aa3b, v32
	v_exp_f32_e32 v42, v42
	s_nop 0
	v_add_f32_e32 v42, 1.0, v42
	v_div_scale_f32 v43, s[10:11], v42, v42, v32
	v_rcp_f32_e32 v45, v43
	v_div_scale_f32 v46, vcc, v32, v42, v32
	v_fma_f32 v47, -v43, v45, 1.0
	v_fmac_f32_e32 v45, v47, v45
	v_mul_f32_e32 v47, v46, v45
	v_fma_f32 v48, -v43, v47, v46
	v_fmac_f32_e32 v47, v48, v45
	v_fma_f32 v43, -v43, v47, v46
	v_div_fmas_f32 v43, v43, v45, v47
	v_div_fixup_f32 v44, v43, v42, v32
	ds_write_b32 v41, v44 offset:0
	s_waitcnt vmcnt(2)
; DI float silu(float x) { return x / (1.0f + __expf(-x)); }
; DI void p0_mod_unit(const Params& p, int u, LAS unsigned char* ldsb) {
;     ...
;         const float c = bi < 4 ? p.in[2][bi * 1024 + k] : p.in[3][(bi - 4) * 1024 + k]; lds[idx] = silu(c); }
;     __syncthreads();
;     float acc[18];
; #pragma unroll
;     for (int i = 0; i < 18; ++i) acc[i] = 0.f;
;     const int n = nb * 64 + lane;
;     const float* wp = aw + (size_t)(wid * 128) * 3072 + n;
; #pragma unroll 2
;     for (int k = 0; k < 128; k += 4) {
;         const float w0 = wp[(size_t)(k + 0) * 3072], w1 = wp[(size_t)(k + 1) * 3072], w2 = wp[(size_t)(k + 2) * 3072], w3 = wp[(size_t)(k + 3) * 3072];
	v_mul_f32_e32 v42, 0xbfb8aa3b, v33
	v_exp_f32_e32 v42, v42
	s_nop 0
	v_add_f32_e32 v42, 1.0, v42
	v_div_scale_f32 v43, s[10:11], v42, v42, v33
	v_rcp_f32_e32 v45, v43
	v_div_scale_f32 v46, vcc, v33, v42, v33
	v_fma_f32 v47, -v43, v45, 1.0
	v_fmac_f32_e32 v45, v47, v45
	v_mul_f32_e32 v47, v46, v45
	v_fma_f32 v48, -v43, v47, v46
	v_fmac_f32_e32 v47, v48, v45
	v_fma_f32 v43, -v43, v47, v46
	v_div_fmas_f32 v43, v43, v45, v47
	v_div_fixup_f32 v44, v43, v42, v33
	ds_write_b32 v41, v44 offset:2048
	s_waitcnt vmcnt(1)
	v_mul_f32_e32 v42, 0xbfb8aa3b, v34
	v_exp_f32_e32 v42, v42
	s_nop 0
	v_add_f32_e32 v42, 1.0, v42
	v_div_scale_f32 v43, s[10:11], v42, v42, v34
	v_rcp_f32_e32 v45, v43
	v_div_scale_f32 v46, vcc, v34, v42, v34
	v_fma_f32 v47, -v43, v45, 1.0
	v_fmac_f32_e32 v45, v47, v45
	v_mul_f32_e32 v47, v46, v45
	v_fma_f32 v48, -v43, v47, v46
	v_fmac_f32_e32 v47, v48, v45
	v_fma_f32 v43, -v43, v47, v46
	v_div_fmas_f32 v43, v43, v45, v47
	v_div_fixup_f32 v44, v43, v42, v34
	ds_write_b32 v41, v44 offset:4096
	s_waitcnt vmcnt(0)
	v_mul_f32_e32 v42, 0xbfb8aa3b, v35
	v_exp_f32_e32 v42, v42
	s_nop 0
	v_add_f32_e32 v42, 1.0, v42
	v_div_scale_f32 v43, s[10:11], v42, v42, v35
	v_rcp_f32_e32 v45, v43
	v_div_scale_f32 v46, vcc, v35, v42, v35
	v_fma_f32 v47, -v43, v45, 1.0
	v_fmac_f32_e32 v45, v47, v45
	v_mul_f32_e32 v47, v46, v45
	v_fma_f32 v48, -v43, v47, v46
	v_fmac_f32_e32 v47, v48, v45
	v_fma_f32 v43, -v43, v47, v46
	v_div_fmas_f32 v43, v43, v45, v47
	v_div_fixup_f32 v44, v43, v42, v35
	ds_write_b32 v41, v44 offset:6144
.LBB0_27:
	s_or_b64 exec, exec, s[6:7]
	s_add_i32 s6, s86, 0x5f
	s_cmpk_lt_u32 s6, 0xbf
	s_cselect_b64 s[6:7], -1, 0
	s_and_b64 s[8:9], s[6:7], exec
	s_waitcnt lgkmcnt(0)
	s_cselect_b32 s9, s57, s39
	s_cselect_b32 s8, s56, s38
	s_lshl_b32 s10, s89, 5
	v_mov_b32_e32 v0, s10
	v_bfi_b32 v0, s14, v0, v167
	v_ashrrev_i32_e32 v168, 6, v167
	v_ashrrev_i32_e32 v1, 31, v0
	v_lshlrev_b32_e32 v2, 7, v168
	v_lshlrev_b64 v[130:131], 2, v[0:1]
	v_mad_i64_i32 v[0:1], s[10:11], v2, s15, v[130:131]
	v_lshl_add_u64 v[0:1], s[8:9], 0, v[0:1]
	v_mov_b32_e32 v132, 0
	v_and_b32_e32 v169, 63, v167
	v_lshl_add_u32 v170, v168, 9, 0
	v_lshl_add_u64 v[134:135], v[0:1], 0, s[0:1]
	s_mov_b32 s8, -4
	v_mov_b32_e32 v133, v132
	v_mov_b32_e32 v136, v132
	v_mov_b32_e32 v137, v132
	v_mov_b32_e32 v138, v132
	v_mov_b32_e32 v139, v132
	v_mov_b32_e32 v140, v132
	v_mov_b32_e32 v141, v132
	v_mov_b32_e32 v142, v132
	v_mov_b32_e32 v143, v132
	v_mov_b32_e32 v144, v132
	v_mov_b32_e32 v145, v132
	v_mov_b32_e32 v146, v132
	v_mov_b32_e32 v147, v132
	v_mov_b32_e32 v148, v132
	v_mov_b32_e32 v149, v132
	v_mov_b32_e32 v150, v132
	v_mov_b32_e32 v151, v132
	s_barrier
	s_mov_b32 s8, 0xfffeb000
	s_mov_b32 s9, -1
	s_mov_b32 s10, 0x3000
	s_mov_b32 s11, 0
	v_lshl_add_u64 v[134:135], v[134:135], 0, s[8:9]
	v_add_u32_e32 v171, 0x10000, v170
	global_load_dword v0, v[134:135], off
	v_lshl_add_u64 v[134:135], v[134:135], 0, s[10:11]
	global_load_dword v1, v[134:135], off
	v_lshl_add_u64 v[134:135], v[134:135], 0, s[10:11]
	global_load_dword v2, v[134:135], off
	v_lshl_add_u64 v[134:135], v[134:135], 0, s[10:11]
	global_load_dword v3, v[134:135], off
	v_lshl_add_u64 v[134:135], v[134:135], 0, s[10:11]
	global_load_dword v4, v[134:135], off
	v_lshl_add_u64 v[134:135], v[134:135], 0, s[10:11]
	global_load_dword v5, v[134:135], off
	v_lshl_add_u64 v[134:135], v[134:135], 0, s[10:11]
	global_load_dword v6, v[134:135], off
	v_lshl_add_u64 v[134:135], v[134:135], 0, s[10:11]
	global_load_dword v7, v[134:135], off
	v_lshl_add_u64 v[134:135], v[134:135], 0, s[10:11]
	global_load_dword v8, v[134:135], off
	v_lshl_add_u64 v[134:135], v[134:135], 0, s[10:11]
	global_load_dword v9, v[134:135], off
	v_lshl_add_u64 v[134:135], v[134:135], 0, s[10:11]
	global_load_dword v10, v[134:135], off
	v_lshl_add_u64 v[134:135], v[134:135], 0, s[10:11]
	global_load_dword v11, v[134:135], off
	v_lshl_add_u64 v[134:135], v[134:135], 0, s[10:11]
	global_load_dword v12, v[134:135], off
	v_lshl_add_u64 v[134:135], v[134:135], 0, s[10:11]
	global_load_dword v13, v[134:135], off
	v_lshl_add_u64 v[134:135], v[134:135], 0, s[10:11]
	global_load_dword v14, v[134:135], off
	v_lshl_add_u64 v[134:135], v[134:135], 0, s[10:11]
	global_load_dword v15, v[134:135], off
	v_lshl_add_u64 v[134:135], v[134:135], 0, s[10:11]
	global_load_dword v16, v[134:135], off
	v_lshl_add_u64 v[134:135], v[134:135], 0, s[10:11]
	global_load_dword v17, v[134:135], off
	v_lshl_add_u64 v[134:135], v[134:135], 0, s[10:11]
	global_load_dword v18, v[134:135], off
	v_lshl_add_u64 v[134:135], v[134:135], 0, s[10:11]
	global_load_dword v19, v[134:135], off
	v_lshl_add_u64 v[134:135], v[134:135], 0, s[10:11]
	global_load_dword v20, v[134:135], off
	v_lshl_add_u64 v[134:135], v[134:135], 0, s[10:11]
	global_load_dword v21, v[134:135], off
	v_lshl_add_u64 v[134:135], v[134:135], 0, s[10:11]
	global_load_dword v22, v[134:135], off
	v_lshl_add_u64 v[134:135], v[134:135], 0, s[10:11]
	global_load_dword v23, v[134:135], off
	v_lshl_add_u64 v[134:135], v[134:135], 0, s[10:11]
	global_load_dword v24, v[134:135], off
	v_lshl_add_u64 v[134:135], v[134:135], 0, s[10:11]
	global_load_dword v25, v[134:135], off
	v_lshl_add_u64 v[134:135], v[134:135], 0, s[10:11]
	global_load_dword v26, v[134:135], off
	v_lshl_add_u64 v[134:135], v[134:135], 0, s[10:11]
	global_load_dword v27, v[134:135], off
	v_lshl_add_u64 v[134:135], v[134:135], 0, s[10:11]
	global_load_dword v28, v[134:135], off
	v_lshl_add_u64 v[134:135], v[134:135], 0, s[10:11]
	global_load_dword v29, v[134:135], off
	v_lshl_add_u64 v[134:135], v[134:135], 0, s[10:11]
	global_load_dword v30, v[134:135], off
; DI void p0_mod_unit(const Params& p, int u, LAS unsigned char* ldsb) {
;     ...
;     const int n = nb * 64 + lane;
;     const float* wp = aw + (size_t)(wid * 128) * 3072 + n;
; #pragma unroll 2
;     for (int k = 0; k < 128; k += 4) {
;         const float w0 = wp[(size_t)(k + 0) * 3072], w1 = wp[(size_t)(k + 1) * 3072], w2 = wp[(size_t)(k + 2) * 3072], w3 = wp[(size_t)(k + 3) * 3072];
	v_lshl_add_u64 v[134:135], v[134:135], 0, s[10:11]
	global_load_dword v31, v[134:135], off
	v_lshl_add_u64 v[134:135], v[134:135], 0, s[10:11]
	global_load_dword v32, v[134:135], off
	v_lshl_add_u64 v[134:135], v[134:135], 0, s[10:11]
	global_load_dword v33, v[134:135], off
	v_lshl_add_u64 v[134:135], v[134:135], 0, s[10:11]
	global_load_dword v34, v[134:135], off
	v_lshl_add_u64 v[134:135], v[134:135], 0, s[10:11]
	global_load_dword v35, v[134:135], off
	v_lshl_add_u64 v[134:135], v[134:135], 0, s[10:11]
	global_load_dword v36, v[134:135], off
	v_lshl_add_u64 v[134:135], v[134:135], 0, s[10:11]
	global_load_dword v37, v[134:135], off
	v_lshl_add_u64 v[134:135], v[134:135], 0, s[10:11]
	global_load_dword v38, v[134:135], off
	v_lshl_add_u64 v[134:135], v[134:135], 0, s[10:11]
	global_load_dword v39, v[134:135], off
	v_lshl_add_u64 v[134:135], v[134:135], 0, s[10:11]
	global_load_dword v40, v[134:135], off
	v_lshl_add_u64 v[134:135], v[134:135], 0, s[10:11]
	global_load_dword v41, v[134:135], off
	v_lshl_add_u64 v[134:135], v[134:135], 0, s[10:11]
	global_load_dword v42, v[134:135], off
	v_lshl_add_u64 v[134:135], v[134:135], 0, s[10:11]
	global_load_dword v43, v[134:135], off
	v_lshl_add_u64 v[134:135], v[134:135], 0, s[10:11]
	global_load_dword v44, v[134:135], off
	v_lshl_add_u64 v[134:135], v[134:135], 0, s[10:11]
	global_load_dword v45, v[134:135], off
	v_lshl_add_u64 v[134:135], v[134:135], 0, s[10:11]
	global_load_dword v46, v[134:135], off
	v_lshl_add_u64 v[134:135], v[134:135], 0, s[10:11]
	global_load_dword v47, v[134:135], off
	v_lshl_add_u64 v[134:135], v[134:135], 0, s[10:11]
	global_load_dword v48, v[134:135], off
	v_lshl_add_u64 v[134:135], v[134:135], 0, s[10:11]
	global_load_dword v49, v[134:135], off
	v_lshl_add_u64 v[134:135], v[134:135], 0, s[10:11]
	global_load_dword v50, v[134:135], off
	v_lshl_add_u64 v[134:135], v[134:135], 0, s[10:11]
	global_load_dword v51, v[134:135], off
	v_lshl_add_u64 v[134:135], v[134:135], 0, s[10:11]
	global_load_dword v52, v[134:135], off
	v_lshl_add_u64 v[134:135], v[134:135], 0, s[10:11]
	global_load_dword v53, v[134:135], off
	v_lshl_add_u64 v[134:135], v[134:135], 0, s[10:11]
	global_load_dword v54, v[134:135], off
	v_lshl_add_u64 v[134:135], v[134:135], 0, s[10:11]
	global_load_dword v55, v[134:135], off
	v_lshl_add_u64 v[134:135], v[134:135], 0, s[10:11]
	global_load_dword v56, v[134:135], off
	v_lshl_add_u64 v[134:135], v[134:135], 0, s[10:11]
	global_load_dword v57, v[134:135], off
	v_lshl_add_u64 v[134:135], v[134:135], 0, s[10:11]
	global_load_dword v58, v[134:135], off
	v_lshl_add_u64 v[134:135], v[134:135], 0, s[10:11]
	global_load_dword v59, v[134:135], off
	v_lshl_add_u64 v[134:135], v[134:135], 0, s[10:11]
	global_load_dword v60, v[134:135], off
	v_lshl_add_u64 v[134:135], v[134:135], 0, s[10:11]
	global_load_dword v61, v[134:135], off
	v_lshl_add_u64 v[134:135], v[134:135], 0, s[10:11]
	global_load_dword v62, v[134:135], off
	v_lshl_add_u64 v[134:135], v[134:135], 0, s[10:11]
	global_load_dword v63, v[134:135], off
	v_lshl_add_u64 v[134:135], v[134:135], 0, s[10:11]
	global_load_dword v64, v[134:135], off
	v_lshl_add_u64 v[134:135], v[134:135], 0, s[10:11]
	global_load_dword v65, v[134:135], off
	v_lshl_add_u64 v[134:135], v[134:135], 0, s[10:11]
	global_load_dword v66, v[134:135], off
	v_lshl_add_u64 v[134:135], v[134:135], 0, s[10:11]
	global_load_dword v67, v[134:135], off
	v_lshl_add_u64 v[134:135], v[134:135], 0, s[10:11]
	global_load_dword v68, v[134:135], off
	v_lshl_add_u64 v[134:135], v[134:135], 0, s[10:11]
	global_load_dword v69, v[134:135], off
	v_lshl_add_u64 v[134:135], v[134:135], 0, s[10:11]
	global_load_dword v70, v[134:135], off
	v_lshl_add_u64 v[134:135], v[134:135], 0, s[10:11]
	global_load_dword v71, v[134:135], off
	v_lshl_add_u64 v[134:135], v[134:135], 0, s[10:11]
	global_load_dword v72, v[134:135], off
	v_lshl_add_u64 v[134:135], v[134:135], 0, s[10:11]
	global_load_dword v73, v[134:135], off
	v_lshl_add_u64 v[134:135], v[134:135], 0, s[10:11]
	global_load_dword v74, v[134:135], off
	v_lshl_add_u64 v[134:135], v[134:135], 0, s[10:11]
	global_load_dword v75, v[134:135], off
	v_lshl_add_u64 v[134:135], v[134:135], 0, s[10:11]
	global_load_dword v76, v[134:135], off
	v_lshl_add_u64 v[134:135], v[134:135], 0, s[10:11]
	global_load_dword v77, v[134:135], off
	v_lshl_add_u64 v[134:135], v[134:135], 0, s[10:11]
	global_load_dword v78, v[134:135], off
	v_lshl_add_u64 v[134:135], v[134:135], 0, s[10:11]
	global_load_dword v79, v[134:135], off
	v_lshl_add_u64 v[134:135], v[134:135], 0, s[10:11]
	global_load_dword v80, v[134:135], off
	v_lshl_add_u64 v[134:135], v[134:135], 0, s[10:11]
	global_load_dword v81, v[134:135], off
	v_lshl_add_u64 v[134:135], v[134:135], 0, s[10:11]
	global_load_dword v82, v[134:135], off
	v_lshl_add_u64 v[134:135], v[134:135], 0, s[10:11]
	global_load_dword v83, v[134:135], off
	v_lshl_add_u64 v[134:135], v[134:135], 0, s[10:11]
	global_load_dword v84, v[134:135], off
	v_lshl_add_u64 v[134:135], v[134:135], 0, s[10:11]
	global_load_dword v85, v[134:135], off
	v_lshl_add_u64 v[134:135], v[134:135], 0, s[10:11]
	global_load_dword v86, v[134:135], off
	v_lshl_add_u64 v[134:135], v[134:135], 0, s[10:11]
	global_load_dword v87, v[134:135], off
	v_lshl_add_u64 v[134:135], v[134:135], 0, s[10:11]
	global_load_dword v88, v[134:135], off
	v_lshl_add_u64 v[134:135], v[134:135], 0, s[10:11]
	global_load_dword v89, v[134:135], off
	v_lshl_add_u64 v[134:135], v[134:135], 0, s[10:11]
	global_load_dword v90, v[134:135], off
	v_lshl_add_u64 v[134:135], v[134:135], 0, s[10:11]
	global_load_dword v91, v[134:135], off
	v_lshl_add_u64 v[134:135], v[134:135], 0, s[10:11]
; #define LAS __attribute__((address_space(3)))
; DI void p0_mod_unit(const Params& p, int u, LAS unsigned char* ldsb) {
;     ...
;     float acc[18];
; #pragma unroll
;     for (int i = 0; i < 18; ++i) acc[i] = 0.f;
;     const int n = nb * 64 + lane;
;     const float* wp = aw + (size_t)(wid * 128) * 3072 + n;
; #pragma unroll 2
;     for (int k = 0; k < 128; k += 4) {
;         const float w0 = wp[(size_t)(k + 0) * 3072], w1 = wp[(size_t)(k + 1) * 3072], w2 = wp[(size_t)(k + 2) * 3072], w3 = wp[(size_t)(k + 3) * 3072];
; #pragma unroll
;         for (int i = 0; i < 18; ++i) { const f32x4 s = *(const LAS f32x4*)(lds + i * 1024 + wid * 128 + k); acc[i] += s.x * w0 + s.y * w1 + s.z * w2 + s.w * w3; }
	global_load_dword v92, v[134:135], off
	v_lshl_add_u64 v[134:135], v[134:135], 0, s[10:11]
	global_load_dword v93, v[134:135], off
	v_lshl_add_u64 v[134:135], v[134:135], 0, s[10:11]
	global_load_dword v94, v[134:135], off
	v_lshl_add_u64 v[134:135], v[134:135], 0, s[10:11]
	global_load_dword v95, v[134:135], off
	v_lshl_add_u64 v[134:135], v[134:135], 0, s[10:11]
	global_load_dword v96, v[134:135], off
	v_lshl_add_u64 v[134:135], v[134:135], 0, s[10:11]
	global_load_dword v97, v[134:135], off
	v_lshl_add_u64 v[134:135], v[134:135], 0, s[10:11]
	global_load_dword v98, v[134:135], off
	v_lshl_add_u64 v[134:135], v[134:135], 0, s[10:11]
	global_load_dword v99, v[134:135], off
	v_lshl_add_u64 v[134:135], v[134:135], 0, s[10:11]
	global_load_dword v100, v[134:135], off
	v_lshl_add_u64 v[134:135], v[134:135], 0, s[10:11]
	global_load_dword v101, v[134:135], off
	v_lshl_add_u64 v[134:135], v[134:135], 0, s[10:11]
	global_load_dword v102, v[134:135], off
	v_lshl_add_u64 v[134:135], v[134:135], 0, s[10:11]
	global_load_dword v103, v[134:135], off
	v_lshl_add_u64 v[134:135], v[134:135], 0, s[10:11]
	global_load_dword v104, v[134:135], off
	v_lshl_add_u64 v[134:135], v[134:135], 0, s[10:11]
	global_load_dword v105, v[134:135], off
	v_lshl_add_u64 v[134:135], v[134:135], 0, s[10:11]
	global_load_dword v106, v[134:135], off
	v_lshl_add_u64 v[134:135], v[134:135], 0, s[10:11]
	global_load_dword v107, v[134:135], off
	v_lshl_add_u64 v[134:135], v[134:135], 0, s[10:11]
	global_load_dword v108, v[134:135], off
	v_lshl_add_u64 v[134:135], v[134:135], 0, s[10:11]
	global_load_dword v109, v[134:135], off
	v_lshl_add_u64 v[134:135], v[134:135], 0, s[10:11]
	global_load_dword v110, v[134:135], off
	v_lshl_add_u64 v[134:135], v[134:135], 0, s[10:11]
	global_load_dword v111, v[134:135], off
	v_lshl_add_u64 v[134:135], v[134:135], 0, s[10:11]
	global_load_dword v112, v[134:135], off
	v_lshl_add_u64 v[134:135], v[134:135], 0, s[10:11]
	global_load_dword v113, v[134:135], off
	v_lshl_add_u64 v[134:135], v[134:135], 0, s[10:11]
	global_load_dword v114, v[134:135], off
	v_lshl_add_u64 v[134:135], v[134:135], 0, s[10:11]
	global_load_dword v115, v[134:135], off
	v_lshl_add_u64 v[134:135], v[134:135], 0, s[10:11]
	global_load_dword v116, v[134:135], off
	v_lshl_add_u64 v[134:135], v[134:135], 0, s[10:11]
	global_load_dword v117, v[134:135], off
	v_lshl_add_u64 v[134:135], v[134:135], 0, s[10:11]
	global_load_dword v118, v[134:135], off
	v_lshl_add_u64 v[134:135], v[134:135], 0, s[10:11]
	global_load_dword v119, v[134:135], off
	v_lshl_add_u64 v[134:135], v[134:135], 0, s[10:11]
	global_load_dword v120, v[134:135], off
	v_lshl_add_u64 v[134:135], v[134:135], 0, s[10:11]
	global_load_dword v121, v[134:135], off
	v_lshl_add_u64 v[134:135], v[134:135], 0, s[10:11]
	global_load_dword v122, v[134:135], off
	v_lshl_add_u64 v[134:135], v[134:135], 0, s[10:11]
	global_load_dword v123, v[134:135], off
	v_lshl_add_u64 v[134:135], v[134:135], 0, s[10:11]
	global_load_dword v124, v[134:135], off
	v_lshl_add_u64 v[134:135], v[134:135], 0, s[10:11]
	global_load_dword v125, v[134:135], off
	v_lshl_add_u64 v[134:135], v[134:135], 0, s[10:11]
	global_load_dword v126, v[134:135], off
	v_lshl_add_u64 v[134:135], v[134:135], 0, s[10:11]
	global_load_dword v127, v[134:135], off
	v_mov_b32_e32 v136, 0
	v_mov_b32_e32 v137, 0
	v_mov_b32_e32 v138, 0
	v_mov_b32_e32 v139, 0
	v_mov_b32_e32 v140, 0
	v_mov_b32_e32 v141, 0
	v_mov_b32_e32 v142, 0
	v_mov_b32_e32 v143, 0
	v_mov_b32_e32 v144, 0
	v_mov_b32_e32 v145, 0
	v_mov_b32_e32 v146, 0
	v_mov_b32_e32 v147, 0
	v_mov_b32_e32 v148, 0
	v_mov_b32_e32 v149, 0
	v_mov_b32_e32 v150, 0
	v_mov_b32_e32 v151, 0
	v_mov_b32_e32 v152, 0
	v_mov_b32_e32 v153, 0
	v_mov_b32_e32 v154, 0
	v_mov_b32_e32 v155, 0
	v_mov_b32_e32 v156, 0
	v_mov_b32_e32 v157, 0
	v_mov_b32_e32 v158, 0
	v_mov_b32_e32 v159, 0
	v_mov_b32_e32 v160, 0
	v_mov_b32_e32 v161, 0
	v_mov_b32_e32 v162, 0
	v_mov_b32_e32 v163, 0
	v_mov_b32_e32 v164, 0
	v_mov_b32_e32 v165, 0
	v_mov_b32_e32 v172, 0
	v_mov_b32_e32 v173, 0
	v_mov_b32_e32 v174, 0
	v_mov_b32_e32 v175, 0
	v_mov_b32_e32 v176, 0
	v_mov_b32_e32 v177, 0
	ds_read_b128 v[178:181], v170 offset:0
	ds_read_b128 v[182:185], v170 offset:4096
	ds_read_b128 v[186:189], v170 offset:8192
	ds_read_b128 v[190:193], v170 offset:12288
	ds_read_b128 v[194:197], v170 offset:16384
	ds_read_b128 v[198:201], v170 offset:20480
	ds_read_b128 v[202:205], v170 offset:24576
	ds_read_b128 v[206:209], v170 offset:28672
	ds_read_b128 v[210:213], v170 offset:32768
	ds_read_b128 v[214:217], v170 offset:36864
	ds_read_b128 v[218:221], v170 offset:40960
	ds_read_b128 v[222:225], v170 offset:45056
	s_waitcnt lgkmcnt(6)
	s_waitcnt vmcnt(63)
	v_pk_fma_f32 v[136:137], v[178:179], v[0:1], v[136:137]
	v_pk_fma_f32 v[136:137], v[180:181], v[2:3], v[136:137]
	v_pk_fma_f32 v[138:139], v[182:183], v[0:1], v[138:139]
	v_pk_fma_f32 v[138:139], v[184:185], v[2:3], v[138:139]
	v_pk_fma_f32 v[140:141], v[186:187], v[0:1], v[140:141]
	v_pk_fma_f32 v[140:141], v[188:189], v[2:3], v[140:141]
	v_pk_fma_f32 v[142:143], v[190:191], v[0:1], v[142:143]
	v_pk_fma_f32 v[142:143], v[192:193], v[2:3], v[142:143]
	v_pk_fma_f32 v[144:145], v[194:195], v[0:1], v[144:145]
	v_pk_fma_f32 v[144:145], v[196:197], v[2:3], v[144:145]
	v_pk_fma_f32 v[146:147], v[198:199], v[0:1], v[146:147]
	v_pk_fma_f32 v[146:147], v[200:201], v[2:3], v[146:147]
	ds_read_b128 v[178:181], v170 offset:49152
	ds_read_b128 v[182:185], v170 offset:53248
	ds_read_b128 v[186:189], v170 offset:57344
	ds_read_b128 v[190:193], v170 offset:61440
	ds_read_b128 v[194:197], v171 offset:0
	ds_read_b128 v[198:201], v171 offset:4096
	s_waitcnt lgkmcnt(6)
; #define LAS __attribute__((address_space(3)))
; DI void p0_mod_unit(const Params& p, int u, LAS unsigned char* ldsb) {
;     ...
;     for (int k = 0; k < 128; k += 4) {
;         const float w0 = wp[(size_t)(k + 0) * 3072], w1 = wp[(size_t)(k + 1) * 3072], w2 = wp[(size_t)(k + 2) * 3072], w3 = wp[(size_t)(k + 3) * 3072];
; #pragma unroll
;         for (int i = 0; i < 18; ++i) { const f32x4 s = *(const LAS f32x4*)(lds + i * 1024 + wid * 128 + k); acc[i] += s.x * w0 + s.y * w1 + s.z * w2 + s.w * w3; }
	v_pk_fma_f32 v[148:149], v[202:203], v[0:1], v[148:149]
	v_pk_fma_f32 v[148:149], v[204:205], v[2:3], v[148:149]
	v_pk_fma_f32 v[150:151], v[206:207], v[0:1], v[150:151]
	v_pk_fma_f32 v[150:151], v[208:209], v[2:3], v[150:151]
	v_pk_fma_f32 v[152:153], v[210:211], v[0:1], v[152:153]
	v_pk_fma_f32 v[152:153], v[212:213], v[2:3], v[152:153]
	v_pk_fma_f32 v[154:155], v[214:215], v[0:1], v[154:155]
	v_pk_fma_f32 v[154:155], v[216:217], v[2:3], v[154:155]
	v_pk_fma_f32 v[156:157], v[218:219], v[0:1], v[156:157]
	v_pk_fma_f32 v[156:157], v[220:221], v[2:3], v[156:157]
	v_pk_fma_f32 v[158:159], v[222:223], v[0:1], v[158:159]
	v_pk_fma_f32 v[158:159], v[224:225], v[2:3], v[158:159]
	ds_read_b128 v[202:205], v170 offset:16
	ds_read_b128 v[206:209], v170 offset:4112
	ds_read_b128 v[210:213], v170 offset:8208
	ds_read_b128 v[214:217], v170 offset:12304
	ds_read_b128 v[218:221], v170 offset:16400
	ds_read_b128 v[222:225], v170 offset:20496
	s_waitcnt lgkmcnt(6)
	v_pk_fma_f32 v[160:161], v[178:179], v[0:1], v[160:161]
	v_pk_fma_f32 v[160:161], v[180:181], v[2:3], v[160:161]
	v_pk_fma_f32 v[162:163], v[182:183], v[0:1], v[162:163]
	v_pk_fma_f32 v[162:163], v[184:185], v[2:3], v[162:163]
	v_pk_fma_f32 v[164:165], v[186:187], v[0:1], v[164:165]
	v_pk_fma_f32 v[164:165], v[188:189], v[2:3], v[164:165]
	v_pk_fma_f32 v[172:173], v[190:191], v[0:1], v[172:173]
	v_pk_fma_f32 v[172:173], v[192:193], v[2:3], v[172:173]
	v_pk_fma_f32 v[174:175], v[194:195], v[0:1], v[174:175]
	v_pk_fma_f32 v[174:175], v[196:197], v[2:3], v[174:175]
	v_pk_fma_f32 v[176:177], v[198:199], v[0:1], v[176:177]
	v_pk_fma_f32 v[176:177], v[200:201], v[2:3], v[176:177]
	ds_read_b128 v[178:181], v170 offset:24592
	ds_read_b128 v[182:185], v170 offset:28688
	ds_read_b128 v[186:189], v170 offset:32784
	ds_read_b128 v[190:193], v170 offset:36880
	ds_read_b128 v[194:197], v170 offset:40976
	ds_read_b128 v[198:201], v170 offset:45072
	s_waitcnt lgkmcnt(6)
	s_waitcnt vmcnt(63)
	v_pk_fma_f32 v[136:137], v[202:203], v[4:5], v[136:137]
	v_pk_fma_f32 v[136:137], v[204:205], v[6:7], v[136:137]
	v_pk_fma_f32 v[138:139], v[206:207], v[4:5], v[138:139]
	v_pk_fma_f32 v[138:139], v[208:209], v[6:7], v[138:139]
	v_pk_fma_f32 v[140:141], v[210:211], v[4:5], v[140:141]
	v_pk_fma_f32 v[140:141], v[212:213], v[6:7], v[140:141]
	v_pk_fma_f32 v[142:143], v[214:215], v[4:5], v[142:143]
	v_pk_fma_f32 v[142:143], v[216:217], v[6:7], v[142:143]
	v_pk_fma_f32 v[144:145], v[218:219], v[4:5], v[144:145]
	v_pk_fma_f32 v[144:145], v[220:221], v[6:7], v[144:145]
	v_pk_fma_f32 v[146:147], v[222:223], v[4:5], v[146:147]
	v_pk_fma_f32 v[146:147], v[224:225], v[6:7], v[146:147]
	ds_read_b128 v[202:205], v170 offset:49168
	ds_read_b128 v[206:209], v170 offset:53264
	ds_read_b128 v[210:213], v170 offset:57360
	ds_read_b128 v[214:217], v170 offset:61456
	ds_read_b128 v[218:221], v171 offset:16
	ds_read_b128 v[222:225], v171 offset:4112
	s_waitcnt lgkmcnt(6)
	v_pk_fma_f32 v[148:149], v[178:179], v[4:5], v[148:149]
	v_pk_fma_f32 v[148:149], v[180:181], v[6:7], v[148:149]
	v_pk_fma_f32 v[150:151], v[182:183], v[4:5], v[150:151]
	v_pk_fma_f32 v[150:151], v[184:185], v[6:7], v[150:151]
	v_pk_fma_f32 v[152:153], v[186:187], v[4:5], v[152:153]
	v_pk_fma_f32 v[152:153], v[188:189], v[6:7], v[152:153]
	v_pk_fma_f32 v[154:155], v[190:191], v[4:5], v[154:155]
	v_pk_fma_f32 v[154:155], v[192:193], v[6:7], v[154:155]
	v_pk_fma_f32 v[156:157], v[194:195], v[4:5], v[156:157]
	v_pk_fma_f32 v[156:157], v[196:197], v[6:7], v[156:157]
	v_pk_fma_f32 v[158:159], v[198:199], v[4:5], v[158:159]
	v_pk_fma_f32 v[158:159], v[200:201], v[6:7], v[158:159]
	ds_read_b128 v[178:181], v170 offset:32
	ds_read_b128 v[182:185], v170 offset:4128
	ds_read_b128 v[186:189], v170 offset:8224
	ds_read_b128 v[190:193], v170 offset:12320
	ds_read_b128 v[194:197], v170 offset:16416
	ds_read_b128 v[198:201], v170 offset:20512
	s_waitcnt lgkmcnt(6)
	v_pk_fma_f32 v[160:161], v[202:203], v[4:5], v[160:161]
	v_pk_fma_f32 v[160:161], v[204:205], v[6:7], v[160:161]
	v_pk_fma_f32 v[162:163], v[206:207], v[4:5], v[162:163]
	v_pk_fma_f32 v[162:163], v[208:209], v[6:7], v[162:163]
	v_pk_fma_f32 v[164:165], v[210:211], v[4:5], v[164:165]
	v_pk_fma_f32 v[164:165], v[212:213], v[6:7], v[164:165]
	v_pk_fma_f32 v[172:173], v[214:215], v[4:5], v[172:173]
	v_pk_fma_f32 v[172:173], v[216:217], v[6:7], v[172:173]
	v_pk_fma_f32 v[174:175], v[218:219], v[4:5], v[174:175]
	v_pk_fma_f32 v[174:175], v[220:221], v[6:7], v[174:175]
	v_pk_fma_f32 v[176:177], v[222:223], v[4:5], v[176:177]
	v_pk_fma_f32 v[176:177], v[224:225], v[6:7], v[176:177]
	ds_read_b128 v[202:205], v170 offset:24608
	ds_read_b128 v[206:209], v170 offset:28704
	ds_read_b128 v[210:213], v170 offset:32800
	ds_read_b128 v[214:217], v170 offset:36896
	ds_read_b128 v[218:221], v170 offset:40992
	ds_read_b128 v[222:225], v170 offset:45088
	s_waitcnt lgkmcnt(6)
	s_waitcnt vmcnt(63)
	v_pk_fma_f32 v[136:137], v[178:179], v[8:9], v[136:137]
	v_pk_fma_f32 v[136:137], v[180:181], v[10:11], v[136:137]
	v_pk_fma_f32 v[138:139], v[182:183], v[8:9], v[138:139]
	v_pk_fma_f32 v[138:139], v[184:185], v[10:11], v[138:139]
	v_pk_fma_f32 v[140:141], v[186:187], v[8:9], v[140:141]
	v_pk_fma_f32 v[140:141], v[188:189], v[10:11], v[140:141]
	v_pk_fma_f32 v[142:143], v[190:191], v[8:9], v[142:143]
	v_pk_fma_f32 v[142:143], v[192:193], v[10:11], v[142:143]
	v_pk_fma_f32 v[144:145], v[194:195], v[8:9], v[144:145]
	v_pk_fma_f32 v[144:145], v[196:197], v[10:11], v[144:145]
	v_pk_fma_f32 v[146:147], v[198:199], v[8:9], v[146:147]
	v_pk_fma_f32 v[146:147], v[200:201], v[10:11], v[146:147]
	ds_read_b128 v[178:181], v170 offset:49184
	ds_read_b128 v[182:185], v170 offset:53280
	ds_read_b128 v[186:189], v170 offset:57376
	ds_read_b128 v[190:193], v170 offset:61472
	ds_read_b128 v[194:197], v171 offset:32
	ds_read_b128 v[198:201], v171 offset:4128
	s_waitcnt lgkmcnt(6)
; #define LAS __attribute__((address_space(3)))
; DI void p0_mod_unit(const Params& p, int u, LAS unsigned char* ldsb) {
;     ...
;     for (int k = 0; k < 128; k += 4) {
;         const float w0 = wp[(size_t)(k + 0) * 3072], w1 = wp[(size_t)(k + 1) * 3072], w2 = wp[(size_t)(k + 2) * 3072], w3 = wp[(size_t)(k + 3) * 3072];
; #pragma unroll
;         for (int i = 0; i < 18; ++i) { const f32x4 s = *(const LAS f32x4*)(lds + i * 1024 + wid * 128 + k); acc[i] += s.x * w0 + s.y * w1 + s.z * w2 + s.w * w3; }
	v_pk_fma_f32 v[148:149], v[202:203], v[8:9], v[148:149]
	v_pk_fma_f32 v[148:149], v[204:205], v[10:11], v[148:149]
	v_pk_fma_f32 v[150:151], v[206:207], v[8:9], v[150:151]
	v_pk_fma_f32 v[150:151], v[208:209], v[10:11], v[150:151]
	v_pk_fma_f32 v[152:153], v[210:211], v[8:9], v[152:153]
	v_pk_fma_f32 v[152:153], v[212:213], v[10:11], v[152:153]
	v_pk_fma_f32 v[154:155], v[214:215], v[8:9], v[154:155]
	v_pk_fma_f32 v[154:155], v[216:217], v[10:11], v[154:155]
	v_pk_fma_f32 v[156:157], v[218:219], v[8:9], v[156:157]
	v_pk_fma_f32 v[156:157], v[220:221], v[10:11], v[156:157]
	v_pk_fma_f32 v[158:159], v[222:223], v[8:9], v[158:159]
	v_pk_fma_f32 v[158:159], v[224:225], v[10:11], v[158:159]
	ds_read_b128 v[202:205], v170 offset:48
	ds_read_b128 v[206:209], v170 offset:4144
	ds_read_b128 v[210:213], v170 offset:8240
	ds_read_b128 v[214:217], v170 offset:12336
	ds_read_b128 v[218:221], v170 offset:16432
	ds_read_b128 v[222:225], v170 offset:20528
	s_waitcnt lgkmcnt(6)
	v_pk_fma_f32 v[160:161], v[178:179], v[8:9], v[160:161]
	v_pk_fma_f32 v[160:161], v[180:181], v[10:11], v[160:161]
	v_pk_fma_f32 v[162:163], v[182:183], v[8:9], v[162:163]
	v_pk_fma_f32 v[162:163], v[184:185], v[10:11], v[162:163]
	v_pk_fma_f32 v[164:165], v[186:187], v[8:9], v[164:165]
	v_pk_fma_f32 v[164:165], v[188:189], v[10:11], v[164:165]
	v_pk_fma_f32 v[172:173], v[190:191], v[8:9], v[172:173]
	v_pk_fma_f32 v[172:173], v[192:193], v[10:11], v[172:173]
	v_pk_fma_f32 v[174:175], v[194:195], v[8:9], v[174:175]
	v_pk_fma_f32 v[174:175], v[196:197], v[10:11], v[174:175]
	v_pk_fma_f32 v[176:177], v[198:199], v[8:9], v[176:177]
	v_pk_fma_f32 v[176:177], v[200:201], v[10:11], v[176:177]
	ds_read_b128 v[178:181], v170 offset:24624
	ds_read_b128 v[182:185], v170 offset:28720
	ds_read_b128 v[186:189], v170 offset:32816
	ds_read_b128 v[190:193], v170 offset:36912
	ds_read_b128 v[194:197], v170 offset:41008
	ds_read_b128 v[198:201], v170 offset:45104
	s_waitcnt lgkmcnt(6)
	s_waitcnt vmcnt(63)
	v_pk_fma_f32 v[136:137], v[202:203], v[12:13], v[136:137]
	v_pk_fma_f32 v[136:137], v[204:205], v[14:15], v[136:137]
	v_pk_fma_f32 v[138:139], v[206:207], v[12:13], v[138:139]
	v_pk_fma_f32 v[138:139], v[208:209], v[14:15], v[138:139]
	v_pk_fma_f32 v[140:141], v[210:211], v[12:13], v[140:141]
	v_pk_fma_f32 v[140:141], v[212:213], v[14:15], v[140:141]
	v_pk_fma_f32 v[142:143], v[214:215], v[12:13], v[142:143]
	v_pk_fma_f32 v[142:143], v[216:217], v[14:15], v[142:143]
	v_pk_fma_f32 v[144:145], v[218:219], v[12:13], v[144:145]
	v_pk_fma_f32 v[144:145], v[220:221], v[14:15], v[144:145]
	v_pk_fma_f32 v[146:147], v[222:223], v[12:13], v[146:147]
	v_pk_fma_f32 v[146:147], v[224:225], v[14:15], v[146:147]
	ds_read_b128 v[202:205], v170 offset:49200
	ds_read_b128 v[206:209], v170 offset:53296
	ds_read_b128 v[210:213], v170 offset:57392
	ds_read_b128 v[214:217], v170 offset:61488
	ds_read_b128 v[218:221], v171 offset:48
	ds_read_b128 v[222:225], v171 offset:4144
	s_waitcnt lgkmcnt(6)
	v_pk_fma_f32 v[148:149], v[178:179], v[12:13], v[148:149]
	v_pk_fma_f32 v[148:149], v[180:181], v[14:15], v[148:149]
	v_pk_fma_f32 v[150:151], v[182:183], v[12:13], v[150:151]
	v_pk_fma_f32 v[150:151], v[184:185], v[14:15], v[150:151]
	v_pk_fma_f32 v[152:153], v[186:187], v[12:13], v[152:153]
	v_pk_fma_f32 v[152:153], v[188:189], v[14:15], v[152:153]
	v_pk_fma_f32 v[154:155], v[190:191], v[12:13], v[154:155]
	v_pk_fma_f32 v[154:155], v[192:193], v[14:15], v[154:155]
	v_pk_fma_f32 v[156:157], v[194:195], v[12:13], v[156:157]
	v_pk_fma_f32 v[156:157], v[196:197], v[14:15], v[156:157]
	v_pk_fma_f32 v[158:159], v[198:199], v[12:13], v[158:159]
	v_pk_fma_f32 v[158:159], v[200:201], v[14:15], v[158:159]
	ds_read_b128 v[178:181], v170 offset:64
	ds_read_b128 v[182:185], v170 offset:4160
	ds_read_b128 v[186:189], v170 offset:8256
	ds_read_b128 v[190:193], v170 offset:12352
	ds_read_b128 v[194:197], v170 offset:16448
	ds_read_b128 v[198:201], v170 offset:20544
	s_waitcnt lgkmcnt(6)
	v_pk_fma_f32 v[160:161], v[202:203], v[12:13], v[160:161]
	v_pk_fma_f32 v[160:161], v[204:205], v[14:15], v[160:161]
	v_pk_fma_f32 v[162:163], v[206:207], v[12:13], v[162:163]
	v_pk_fma_f32 v[162:163], v[208:209], v[14:15], v[162:163]
	v_pk_fma_f32 v[164:165], v[210:211], v[12:13], v[164:165]
	v_pk_fma_f32 v[164:165], v[212:213], v[14:15], v[164:165]
	v_pk_fma_f32 v[172:173], v[214:215], v[12:13], v[172:173]
	v_pk_fma_f32 v[172:173], v[216:217], v[14:15], v[172:173]
	v_pk_fma_f32 v[174:175], v[218:219], v[12:13], v[174:175]
	v_pk_fma_f32 v[174:175], v[220:221], v[14:15], v[174:175]
	v_pk_fma_f32 v[176:177], v[222:223], v[12:13], v[176:177]
	v_pk_fma_f32 v[176:177], v[224:225], v[14:15], v[176:177]
	ds_read_b128 v[202:205], v170 offset:24640
	ds_read_b128 v[206:209], v170 offset:28736
	ds_read_b128 v[210:213], v170 offset:32832
	ds_read_b128 v[214:217], v170 offset:36928
	ds_read_b128 v[218:221], v170 offset:41024
	ds_read_b128 v[222:225], v170 offset:45120
	s_waitcnt lgkmcnt(6)
	s_waitcnt vmcnt(63)
	v_pk_fma_f32 v[136:137], v[178:179], v[16:17], v[136:137]
	v_pk_fma_f32 v[136:137], v[180:181], v[18:19], v[136:137]
	v_pk_fma_f32 v[138:139], v[182:183], v[16:17], v[138:139]
	v_pk_fma_f32 v[138:139], v[184:185], v[18:19], v[138:139]
	v_pk_fma_f32 v[140:141], v[186:187], v[16:17], v[140:141]
	v_pk_fma_f32 v[140:141], v[188:189], v[18:19], v[140:141]
	v_pk_fma_f32 v[142:143], v[190:191], v[16:17], v[142:143]
	v_pk_fma_f32 v[142:143], v[192:193], v[18:19], v[142:143]
	v_pk_fma_f32 v[144:145], v[194:195], v[16:17], v[144:145]
	v_pk_fma_f32 v[144:145], v[196:197], v[18:19], v[144:145]
	v_pk_fma_f32 v[146:147], v[198:199], v[16:17], v[146:147]
	v_pk_fma_f32 v[146:147], v[200:201], v[18:19], v[146:147]
	ds_read_b128 v[178:181], v170 offset:49216
	ds_read_b128 v[182:185], v170 offset:53312
	ds_read_b128 v[186:189], v170 offset:57408
	ds_read_b128 v[190:193], v170 offset:61504
	ds_read_b128 v[194:197], v171 offset:64
	ds_read_b128 v[198:201], v171 offset:4160
	s_waitcnt lgkmcnt(6)
; #define LAS __attribute__((address_space(3)))
; DI void p0_mod_unit(const Params& p, int u, LAS unsigned char* ldsb) {
;     ...
;     for (int k = 0; k < 128; k += 4) {
;         const float w0 = wp[(size_t)(k + 0) * 3072], w1 = wp[(size_t)(k + 1) * 3072], w2 = wp[(size_t)(k + 2) * 3072], w3 = wp[(size_t)(k + 3) * 3072];
; #pragma unroll
;         for (int i = 0; i < 18; ++i) { const f32x4 s = *(const LAS f32x4*)(lds + i * 1024 + wid * 128 + k); acc[i] += s.x * w0 + s.y * w1 + s.z * w2 + s.w * w3; }
	v_pk_fma_f32 v[148:149], v[202:203], v[16:17], v[148:149]
	v_pk_fma_f32 v[148:149], v[204:205], v[18:19], v[148:149]
	v_pk_fma_f32 v[150:151], v[206:207], v[16:17], v[150:151]
	v_pk_fma_f32 v[150:151], v[208:209], v[18:19], v[150:151]
	v_pk_fma_f32 v[152:153], v[210:211], v[16:17], v[152:153]
	v_pk_fma_f32 v[152:153], v[212:213], v[18:19], v[152:153]
	v_pk_fma_f32 v[154:155], v[214:215], v[16:17], v[154:155]
	v_pk_fma_f32 v[154:155], v[216:217], v[18:19], v[154:155]
	v_pk_fma_f32 v[156:157], v[218:219], v[16:17], v[156:157]
	v_pk_fma_f32 v[156:157], v[220:221], v[18:19], v[156:157]
	v_pk_fma_f32 v[158:159], v[222:223], v[16:17], v[158:159]
	v_pk_fma_f32 v[158:159], v[224:225], v[18:19], v[158:159]
	ds_read_b128 v[202:205], v170 offset:80
	ds_read_b128 v[206:209], v170 offset:4176
	ds_read_b128 v[210:213], v170 offset:8272
	ds_read_b128 v[214:217], v170 offset:12368
	ds_read_b128 v[218:221], v170 offset:16464
	ds_read_b128 v[222:225], v170 offset:20560
	s_waitcnt lgkmcnt(6)
	v_pk_fma_f32 v[160:161], v[178:179], v[16:17], v[160:161]
	v_pk_fma_f32 v[160:161], v[180:181], v[18:19], v[160:161]
	v_pk_fma_f32 v[162:163], v[182:183], v[16:17], v[162:163]
	v_pk_fma_f32 v[162:163], v[184:185], v[18:19], v[162:163]
	v_pk_fma_f32 v[164:165], v[186:187], v[16:17], v[164:165]
	v_pk_fma_f32 v[164:165], v[188:189], v[18:19], v[164:165]
	v_pk_fma_f32 v[172:173], v[190:191], v[16:17], v[172:173]
	v_pk_fma_f32 v[172:173], v[192:193], v[18:19], v[172:173]
	v_pk_fma_f32 v[174:175], v[194:195], v[16:17], v[174:175]
	v_pk_fma_f32 v[174:175], v[196:197], v[18:19], v[174:175]
	v_pk_fma_f32 v[176:177], v[198:199], v[16:17], v[176:177]
	v_pk_fma_f32 v[176:177], v[200:201], v[18:19], v[176:177]
	ds_read_b128 v[178:181], v170 offset:24656
	ds_read_b128 v[182:185], v170 offset:28752
	ds_read_b128 v[186:189], v170 offset:32848
	ds_read_b128 v[190:193], v170 offset:36944
	ds_read_b128 v[194:197], v170 offset:41040
	ds_read_b128 v[198:201], v170 offset:45136
	s_waitcnt lgkmcnt(6)
	s_waitcnt vmcnt(63)
	v_pk_fma_f32 v[136:137], v[202:203], v[20:21], v[136:137]
	v_pk_fma_f32 v[136:137], v[204:205], v[22:23], v[136:137]
	v_pk_fma_f32 v[138:139], v[206:207], v[20:21], v[138:139]
	v_pk_fma_f32 v[138:139], v[208:209], v[22:23], v[138:139]
	v_pk_fma_f32 v[140:141], v[210:211], v[20:21], v[140:141]
	v_pk_fma_f32 v[140:141], v[212:213], v[22:23], v[140:141]
	v_pk_fma_f32 v[142:143], v[214:215], v[20:21], v[142:143]
	v_pk_fma_f32 v[142:143], v[216:217], v[22:23], v[142:143]
	v_pk_fma_f32 v[144:145], v[218:219], v[20:21], v[144:145]
	v_pk_fma_f32 v[144:145], v[220:221], v[22:23], v[144:145]
	v_pk_fma_f32 v[146:147], v[222:223], v[20:21], v[146:147]
	v_pk_fma_f32 v[146:147], v[224:225], v[22:23], v[146:147]
	ds_read_b128 v[202:205], v170 offset:49232
	ds_read_b128 v[206:209], v170 offset:53328
	ds_read_b128 v[210:213], v170 offset:57424
	ds_read_b128 v[214:217], v170 offset:61520
	ds_read_b128 v[218:221], v171 offset:80
	ds_read_b128 v[222:225], v171 offset:4176
	s_waitcnt lgkmcnt(6)
	v_pk_fma_f32 v[148:149], v[178:179], v[20:21], v[148:149]
	v_pk_fma_f32 v[148:149], v[180:181], v[22:23], v[148:149]
	v_pk_fma_f32 v[150:151], v[182:183], v[20:21], v[150:151]
	v_pk_fma_f32 v[150:151], v[184:185], v[22:23], v[150:151]
	v_pk_fma_f32 v[152:153], v[186:187], v[20:21], v[152:153]
	v_pk_fma_f32 v[152:153], v[188:189], v[22:23], v[152:153]
	v_pk_fma_f32 v[154:155], v[190:191], v[20:21], v[154:155]
	v_pk_fma_f32 v[154:155], v[192:193], v[22:23], v[154:155]
	v_pk_fma_f32 v[156:157], v[194:195], v[20:21], v[156:157]
	v_pk_fma_f32 v[156:157], v[196:197], v[22:23], v[156:157]
	v_pk_fma_f32 v[158:159], v[198:199], v[20:21], v[158:159]
	v_pk_fma_f32 v[158:159], v[200:201], v[22:23], v[158:159]
	ds_read_b128 v[178:181], v170 offset:96
	ds_read_b128 v[182:185], v170 offset:4192
	ds_read_b128 v[186:189], v170 offset:8288
	ds_read_b128 v[190:193], v170 offset:12384
	ds_read_b128 v[194:197], v170 offset:16480
	ds_read_b128 v[198:201], v170 offset:20576
	s_waitcnt lgkmcnt(6)
	v_pk_fma_f32 v[160:161], v[202:203], v[20:21], v[160:161]
	v_pk_fma_f32 v[160:161], v[204:205], v[22:23], v[160:161]
	v_pk_fma_f32 v[162:163], v[206:207], v[20:21], v[162:163]
	v_pk_fma_f32 v[162:163], v[208:209], v[22:23], v[162:163]
	v_pk_fma_f32 v[164:165], v[210:211], v[20:21], v[164:165]
	v_pk_fma_f32 v[164:165], v[212:213], v[22:23], v[164:165]
	v_pk_fma_f32 v[172:173], v[214:215], v[20:21], v[172:173]
	v_pk_fma_f32 v[172:173], v[216:217], v[22:23], v[172:173]
	v_pk_fma_f32 v[174:175], v[218:219], v[20:21], v[174:175]
	v_pk_fma_f32 v[174:175], v[220:221], v[22:23], v[174:175]
	v_pk_fma_f32 v[176:177], v[222:223], v[20:21], v[176:177]
	v_pk_fma_f32 v[176:177], v[224:225], v[22:23], v[176:177]
	ds_read_b128 v[202:205], v170 offset:24672
	ds_read_b128 v[206:209], v170 offset:28768
	ds_read_b128 v[210:213], v170 offset:32864
	ds_read_b128 v[214:217], v170 offset:36960
	ds_read_b128 v[218:221], v170 offset:41056
	ds_read_b128 v[222:225], v170 offset:45152
	s_waitcnt lgkmcnt(6)
	s_waitcnt vmcnt(63)
	v_pk_fma_f32 v[136:137], v[178:179], v[24:25], v[136:137]
	v_pk_fma_f32 v[136:137], v[180:181], v[26:27], v[136:137]
	v_pk_fma_f32 v[138:139], v[182:183], v[24:25], v[138:139]
	v_pk_fma_f32 v[138:139], v[184:185], v[26:27], v[138:139]
	v_pk_fma_f32 v[140:141], v[186:187], v[24:25], v[140:141]
	v_pk_fma_f32 v[140:141], v[188:189], v[26:27], v[140:141]
	v_pk_fma_f32 v[142:143], v[190:191], v[24:25], v[142:143]
	v_pk_fma_f32 v[142:143], v[192:193], v[26:27], v[142:143]
	v_pk_fma_f32 v[144:145], v[194:195], v[24:25], v[144:145]
	v_pk_fma_f32 v[144:145], v[196:197], v[26:27], v[144:145]
	v_pk_fma_f32 v[146:147], v[198:199], v[24:25], v[146:147]
	v_pk_fma_f32 v[146:147], v[200:201], v[26:27], v[146:147]
	ds_read_b128 v[178:181], v170 offset:49248
	ds_read_b128 v[182:185], v170 offset:53344
	ds_read_b128 v[186:189], v170 offset:57440
	ds_read_b128 v[190:193], v170 offset:61536
	ds_read_b128 v[194:197], v171 offset:96
	ds_read_b128 v[198:201], v171 offset:4192
	s_waitcnt lgkmcnt(6)
; #define LAS __attribute__((address_space(3)))
; DI void p0_mod_unit(const Params& p, int u, LAS unsigned char* ldsb) {
;     ...
;     for (int k = 0; k < 128; k += 4) {
;         const float w0 = wp[(size_t)(k + 0) * 3072], w1 = wp[(size_t)(k + 1) * 3072], w2 = wp[(size_t)(k + 2) * 3072], w3 = wp[(size_t)(k + 3) * 3072];
; #pragma unroll
;         for (int i = 0; i < 18; ++i) { const f32x4 s = *(const LAS f32x4*)(lds + i * 1024 + wid * 128 + k); acc[i] += s.x * w0 + s.y * w1 + s.z * w2 + s.w * w3; }
	v_pk_fma_f32 v[148:149], v[202:203], v[24:25], v[148:149]
	v_pk_fma_f32 v[148:149], v[204:205], v[26:27], v[148:149]
	v_pk_fma_f32 v[150:151], v[206:207], v[24:25], v[150:151]
	v_pk_fma_f32 v[150:151], v[208:209], v[26:27], v[150:151]
	v_pk_fma_f32 v[152:153], v[210:211], v[24:25], v[152:153]
	v_pk_fma_f32 v[152:153], v[212:213], v[26:27], v[152:153]
	v_pk_fma_f32 v[154:155], v[214:215], v[24:25], v[154:155]
	v_pk_fma_f32 v[154:155], v[216:217], v[26:27], v[154:155]
	v_pk_fma_f32 v[156:157], v[218:219], v[24:25], v[156:157]
	v_pk_fma_f32 v[156:157], v[220:221], v[26:27], v[156:157]
	v_pk_fma_f32 v[158:159], v[222:223], v[24:25], v[158:159]
	v_pk_fma_f32 v[158:159], v[224:225], v[26:27], v[158:159]
	ds_read_b128 v[202:205], v170 offset:112
	ds_read_b128 v[206:209], v170 offset:4208
	ds_read_b128 v[210:213], v170 offset:8304
	ds_read_b128 v[214:217], v170 offset:12400
	ds_read_b128 v[218:221], v170 offset:16496
	ds_read_b128 v[222:225], v170 offset:20592
	s_waitcnt lgkmcnt(6)
	v_pk_fma_f32 v[160:161], v[178:179], v[24:25], v[160:161]
	v_pk_fma_f32 v[160:161], v[180:181], v[26:27], v[160:161]
	v_pk_fma_f32 v[162:163], v[182:183], v[24:25], v[162:163]
	v_pk_fma_f32 v[162:163], v[184:185], v[26:27], v[162:163]
	v_pk_fma_f32 v[164:165], v[186:187], v[24:25], v[164:165]
	v_pk_fma_f32 v[164:165], v[188:189], v[26:27], v[164:165]
	v_pk_fma_f32 v[172:173], v[190:191], v[24:25], v[172:173]
	v_pk_fma_f32 v[172:173], v[192:193], v[26:27], v[172:173]
	v_pk_fma_f32 v[174:175], v[194:195], v[24:25], v[174:175]
	v_pk_fma_f32 v[174:175], v[196:197], v[26:27], v[174:175]
	v_pk_fma_f32 v[176:177], v[198:199], v[24:25], v[176:177]
	v_pk_fma_f32 v[176:177], v[200:201], v[26:27], v[176:177]
	ds_read_b128 v[178:181], v170 offset:24688
	ds_read_b128 v[182:185], v170 offset:28784
	ds_read_b128 v[186:189], v170 offset:32880
	ds_read_b128 v[190:193], v170 offset:36976
	ds_read_b128 v[194:197], v170 offset:41072
	ds_read_b128 v[198:201], v170 offset:45168
	s_waitcnt lgkmcnt(6)
	s_waitcnt vmcnt(63)
	v_pk_fma_f32 v[136:137], v[202:203], v[28:29], v[136:137]
	v_pk_fma_f32 v[136:137], v[204:205], v[30:31], v[136:137]
	v_pk_fma_f32 v[138:139], v[206:207], v[28:29], v[138:139]
	v_pk_fma_f32 v[138:139], v[208:209], v[30:31], v[138:139]
	v_pk_fma_f32 v[140:141], v[210:211], v[28:29], v[140:141]
	v_pk_fma_f32 v[140:141], v[212:213], v[30:31], v[140:141]
	v_pk_fma_f32 v[142:143], v[214:215], v[28:29], v[142:143]
	v_pk_fma_f32 v[142:143], v[216:217], v[30:31], v[142:143]
	v_pk_fma_f32 v[144:145], v[218:219], v[28:29], v[144:145]
	v_pk_fma_f32 v[144:145], v[220:221], v[30:31], v[144:145]
	v_pk_fma_f32 v[146:147], v[222:223], v[28:29], v[146:147]
	v_pk_fma_f32 v[146:147], v[224:225], v[30:31], v[146:147]
	ds_read_b128 v[202:205], v170 offset:49264
	ds_read_b128 v[206:209], v170 offset:53360
	ds_read_b128 v[210:213], v170 offset:57456
	ds_read_b128 v[214:217], v170 offset:61552
	ds_read_b128 v[218:221], v171 offset:112
	ds_read_b128 v[222:225], v171 offset:4208
	s_waitcnt lgkmcnt(6)
	v_pk_fma_f32 v[148:149], v[178:179], v[28:29], v[148:149]
	v_pk_fma_f32 v[148:149], v[180:181], v[30:31], v[148:149]
	v_pk_fma_f32 v[150:151], v[182:183], v[28:29], v[150:151]
	v_pk_fma_f32 v[150:151], v[184:185], v[30:31], v[150:151]
	v_pk_fma_f32 v[152:153], v[186:187], v[28:29], v[152:153]
	v_pk_fma_f32 v[152:153], v[188:189], v[30:31], v[152:153]
	v_pk_fma_f32 v[154:155], v[190:191], v[28:29], v[154:155]
	v_pk_fma_f32 v[154:155], v[192:193], v[30:31], v[154:155]
	v_pk_fma_f32 v[156:157], v[194:195], v[28:29], v[156:157]
	v_pk_fma_f32 v[156:157], v[196:197], v[30:31], v[156:157]
	v_pk_fma_f32 v[158:159], v[198:199], v[28:29], v[158:159]
	v_pk_fma_f32 v[158:159], v[200:201], v[30:31], v[158:159]
	ds_read_b128 v[178:181], v170 offset:128
	ds_read_b128 v[182:185], v170 offset:4224
	ds_read_b128 v[186:189], v170 offset:8320
	ds_read_b128 v[190:193], v170 offset:12416
	ds_read_b128 v[194:197], v170 offset:16512
	ds_read_b128 v[198:201], v170 offset:20608
	s_waitcnt lgkmcnt(6)
	v_pk_fma_f32 v[160:161], v[202:203], v[28:29], v[160:161]
	v_pk_fma_f32 v[160:161], v[204:205], v[30:31], v[160:161]
	v_pk_fma_f32 v[162:163], v[206:207], v[28:29], v[162:163]
	v_pk_fma_f32 v[162:163], v[208:209], v[30:31], v[162:163]
	v_pk_fma_f32 v[164:165], v[210:211], v[28:29], v[164:165]
	v_pk_fma_f32 v[164:165], v[212:213], v[30:31], v[164:165]
	v_pk_fma_f32 v[172:173], v[214:215], v[28:29], v[172:173]
	v_pk_fma_f32 v[172:173], v[216:217], v[30:31], v[172:173]
	v_pk_fma_f32 v[174:175], v[218:219], v[28:29], v[174:175]
	v_pk_fma_f32 v[174:175], v[220:221], v[30:31], v[174:175]
	v_pk_fma_f32 v[176:177], v[222:223], v[28:29], v[176:177]
	v_pk_fma_f32 v[176:177], v[224:225], v[30:31], v[176:177]
	ds_read_b128 v[202:205], v170 offset:24704
	ds_read_b128 v[206:209], v170 offset:28800
	ds_read_b128 v[210:213], v170 offset:32896
	ds_read_b128 v[214:217], v170 offset:36992
	ds_read_b128 v[218:221], v170 offset:41088
	ds_read_b128 v[222:225], v170 offset:45184
	s_waitcnt lgkmcnt(6)
	s_waitcnt vmcnt(63)
	v_pk_fma_f32 v[136:137], v[178:179], v[32:33], v[136:137]
	v_pk_fma_f32 v[136:137], v[180:181], v[34:35], v[136:137]
	v_pk_fma_f32 v[138:139], v[182:183], v[32:33], v[138:139]
	v_pk_fma_f32 v[138:139], v[184:185], v[34:35], v[138:139]
	v_pk_fma_f32 v[140:141], v[186:187], v[32:33], v[140:141]
	v_pk_fma_f32 v[140:141], v[188:189], v[34:35], v[140:141]
	v_pk_fma_f32 v[142:143], v[190:191], v[32:33], v[142:143]
	v_pk_fma_f32 v[142:143], v[192:193], v[34:35], v[142:143]
	v_pk_fma_f32 v[144:145], v[194:195], v[32:33], v[144:145]
	v_pk_fma_f32 v[144:145], v[196:197], v[34:35], v[144:145]
	v_pk_fma_f32 v[146:147], v[198:199], v[32:33], v[146:147]
	v_pk_fma_f32 v[146:147], v[200:201], v[34:35], v[146:147]
	ds_read_b128 v[178:181], v170 offset:49280
	ds_read_b128 v[182:185], v170 offset:53376
	ds_read_b128 v[186:189], v170 offset:57472
	ds_read_b128 v[190:193], v170 offset:61568
	ds_read_b128 v[194:197], v171 offset:128
	ds_read_b128 v[198:201], v171 offset:4224
	s_waitcnt lgkmcnt(6)
; #define LAS __attribute__((address_space(3)))
; DI void p0_mod_unit(const Params& p, int u, LAS unsigned char* ldsb) {
;     ...
;     for (int k = 0; k < 128; k += 4) {
;         const float w0 = wp[(size_t)(k + 0) * 3072], w1 = wp[(size_t)(k + 1) * 3072], w2 = wp[(size_t)(k + 2) * 3072], w3 = wp[(size_t)(k + 3) * 3072];
; #pragma unroll
;         for (int i = 0; i < 18; ++i) { const f32x4 s = *(const LAS f32x4*)(lds + i * 1024 + wid * 128 + k); acc[i] += s.x * w0 + s.y * w1 + s.z * w2 + s.w * w3; }
	v_pk_fma_f32 v[148:149], v[202:203], v[32:33], v[148:149]
	v_pk_fma_f32 v[148:149], v[204:205], v[34:35], v[148:149]
	v_pk_fma_f32 v[150:151], v[206:207], v[32:33], v[150:151]
	v_pk_fma_f32 v[150:151], v[208:209], v[34:35], v[150:151]
	v_pk_fma_f32 v[152:153], v[210:211], v[32:33], v[152:153]
	v_pk_fma_f32 v[152:153], v[212:213], v[34:35], v[152:153]
	v_pk_fma_f32 v[154:155], v[214:215], v[32:33], v[154:155]
	v_pk_fma_f32 v[154:155], v[216:217], v[34:35], v[154:155]
	v_pk_fma_f32 v[156:157], v[218:219], v[32:33], v[156:157]
	v_pk_fma_f32 v[156:157], v[220:221], v[34:35], v[156:157]
	v_pk_fma_f32 v[158:159], v[222:223], v[32:33], v[158:159]
	v_pk_fma_f32 v[158:159], v[224:225], v[34:35], v[158:159]
	ds_read_b128 v[202:205], v170 offset:144
	ds_read_b128 v[206:209], v170 offset:4240
	ds_read_b128 v[210:213], v170 offset:8336
	ds_read_b128 v[214:217], v170 offset:12432
	ds_read_b128 v[218:221], v170 offset:16528
	ds_read_b128 v[222:225], v170 offset:20624
	s_waitcnt lgkmcnt(6)
	v_pk_fma_f32 v[160:161], v[178:179], v[32:33], v[160:161]
	v_pk_fma_f32 v[160:161], v[180:181], v[34:35], v[160:161]
	v_pk_fma_f32 v[162:163], v[182:183], v[32:33], v[162:163]
	v_pk_fma_f32 v[162:163], v[184:185], v[34:35], v[162:163]
	v_pk_fma_f32 v[164:165], v[186:187], v[32:33], v[164:165]
	v_pk_fma_f32 v[164:165], v[188:189], v[34:35], v[164:165]
	v_pk_fma_f32 v[172:173], v[190:191], v[32:33], v[172:173]
	v_pk_fma_f32 v[172:173], v[192:193], v[34:35], v[172:173]
	v_pk_fma_f32 v[174:175], v[194:195], v[32:33], v[174:175]
	v_pk_fma_f32 v[174:175], v[196:197], v[34:35], v[174:175]
	v_pk_fma_f32 v[176:177], v[198:199], v[32:33], v[176:177]
	v_pk_fma_f32 v[176:177], v[200:201], v[34:35], v[176:177]
	ds_read_b128 v[178:181], v170 offset:24720
	ds_read_b128 v[182:185], v170 offset:28816
	ds_read_b128 v[186:189], v170 offset:32912
	ds_read_b128 v[190:193], v170 offset:37008
	ds_read_b128 v[194:197], v170 offset:41104
	ds_read_b128 v[198:201], v170 offset:45200
	s_waitcnt lgkmcnt(6)
	s_waitcnt vmcnt(63)
	v_pk_fma_f32 v[136:137], v[202:203], v[36:37], v[136:137]
	v_pk_fma_f32 v[136:137], v[204:205], v[38:39], v[136:137]
	v_pk_fma_f32 v[138:139], v[206:207], v[36:37], v[138:139]
	v_pk_fma_f32 v[138:139], v[208:209], v[38:39], v[138:139]
	v_pk_fma_f32 v[140:141], v[210:211], v[36:37], v[140:141]
	v_pk_fma_f32 v[140:141], v[212:213], v[38:39], v[140:141]
	v_pk_fma_f32 v[142:143], v[214:215], v[36:37], v[142:143]
	v_pk_fma_f32 v[142:143], v[216:217], v[38:39], v[142:143]
	v_pk_fma_f32 v[144:145], v[218:219], v[36:37], v[144:145]
	v_pk_fma_f32 v[144:145], v[220:221], v[38:39], v[144:145]
	v_pk_fma_f32 v[146:147], v[222:223], v[36:37], v[146:147]
	v_pk_fma_f32 v[146:147], v[224:225], v[38:39], v[146:147]
	ds_read_b128 v[202:205], v170 offset:49296
	ds_read_b128 v[206:209], v170 offset:53392
	ds_read_b128 v[210:213], v170 offset:57488
	ds_read_b128 v[214:217], v170 offset:61584
	ds_read_b128 v[218:221], v171 offset:144
	ds_read_b128 v[222:225], v171 offset:4240
	s_waitcnt lgkmcnt(6)
	v_pk_fma_f32 v[148:149], v[178:179], v[36:37], v[148:149]
	v_pk_fma_f32 v[148:149], v[180:181], v[38:39], v[148:149]
	v_pk_fma_f32 v[150:151], v[182:183], v[36:37], v[150:151]
	v_pk_fma_f32 v[150:151], v[184:185], v[38:39], v[150:151]
	v_pk_fma_f32 v[152:153], v[186:187], v[36:37], v[152:153]
	v_pk_fma_f32 v[152:153], v[188:189], v[38:39], v[152:153]
	v_pk_fma_f32 v[154:155], v[190:191], v[36:37], v[154:155]
	v_pk_fma_f32 v[154:155], v[192:193], v[38:39], v[154:155]
	v_pk_fma_f32 v[156:157], v[194:195], v[36:37], v[156:157]
	v_pk_fma_f32 v[156:157], v[196:197], v[38:39], v[156:157]
	v_pk_fma_f32 v[158:159], v[198:199], v[36:37], v[158:159]
	v_pk_fma_f32 v[158:159], v[200:201], v[38:39], v[158:159]
	ds_read_b128 v[178:181], v170 offset:160
	ds_read_b128 v[182:185], v170 offset:4256
	ds_read_b128 v[186:189], v170 offset:8352
	ds_read_b128 v[190:193], v170 offset:12448
	ds_read_b128 v[194:197], v170 offset:16544
	ds_read_b128 v[198:201], v170 offset:20640
	s_waitcnt lgkmcnt(6)
	v_pk_fma_f32 v[160:161], v[202:203], v[36:37], v[160:161]
	v_pk_fma_f32 v[160:161], v[204:205], v[38:39], v[160:161]
	v_pk_fma_f32 v[162:163], v[206:207], v[36:37], v[162:163]
	v_pk_fma_f32 v[162:163], v[208:209], v[38:39], v[162:163]
	v_pk_fma_f32 v[164:165], v[210:211], v[36:37], v[164:165]
	v_pk_fma_f32 v[164:165], v[212:213], v[38:39], v[164:165]
	v_pk_fma_f32 v[172:173], v[214:215], v[36:37], v[172:173]
	v_pk_fma_f32 v[172:173], v[216:217], v[38:39], v[172:173]
	v_pk_fma_f32 v[174:175], v[218:219], v[36:37], v[174:175]
	v_pk_fma_f32 v[174:175], v[220:221], v[38:39], v[174:175]
	v_pk_fma_f32 v[176:177], v[222:223], v[36:37], v[176:177]
	v_pk_fma_f32 v[176:177], v[224:225], v[38:39], v[176:177]
	ds_read_b128 v[202:205], v170 offset:24736
	ds_read_b128 v[206:209], v170 offset:28832
	ds_read_b128 v[210:213], v170 offset:32928
	ds_read_b128 v[214:217], v170 offset:37024
	ds_read_b128 v[218:221], v170 offset:41120
	ds_read_b128 v[222:225], v170 offset:45216
	s_waitcnt lgkmcnt(6)
	s_waitcnt vmcnt(63)
	v_pk_fma_f32 v[136:137], v[178:179], v[40:41], v[136:137]
	v_pk_fma_f32 v[136:137], v[180:181], v[42:43], v[136:137]
	v_pk_fma_f32 v[138:139], v[182:183], v[40:41], v[138:139]
	v_pk_fma_f32 v[138:139], v[184:185], v[42:43], v[138:139]
	v_pk_fma_f32 v[140:141], v[186:187], v[40:41], v[140:141]
	v_pk_fma_f32 v[140:141], v[188:189], v[42:43], v[140:141]
	v_pk_fma_f32 v[142:143], v[190:191], v[40:41], v[142:143]
	v_pk_fma_f32 v[142:143], v[192:193], v[42:43], v[142:143]
	v_pk_fma_f32 v[144:145], v[194:195], v[40:41], v[144:145]
	v_pk_fma_f32 v[144:145], v[196:197], v[42:43], v[144:145]
	v_pk_fma_f32 v[146:147], v[198:199], v[40:41], v[146:147]
	v_pk_fma_f32 v[146:147], v[200:201], v[42:43], v[146:147]
	ds_read_b128 v[178:181], v170 offset:49312
	ds_read_b128 v[182:185], v170 offset:53408
	ds_read_b128 v[186:189], v170 offset:57504
	ds_read_b128 v[190:193], v170 offset:61600
	ds_read_b128 v[194:197], v171 offset:160
	ds_read_b128 v[198:201], v171 offset:4256
	s_waitcnt lgkmcnt(6)
; #define LAS __attribute__((address_space(3)))
; DI void p0_mod_unit(const Params& p, int u, LAS unsigned char* ldsb) {
;     ...
;     for (int k = 0; k < 128; k += 4) {
;         const float w0 = wp[(size_t)(k + 0) * 3072], w1 = wp[(size_t)(k + 1) * 3072], w2 = wp[(size_t)(k + 2) * 3072], w3 = wp[(size_t)(k + 3) * 3072];
; #pragma unroll
;         for (int i = 0; i < 18; ++i) { const f32x4 s = *(const LAS f32x4*)(lds + i * 1024 + wid * 128 + k); acc[i] += s.x * w0 + s.y * w1 + s.z * w2 + s.w * w3; }
	v_pk_fma_f32 v[148:149], v[202:203], v[40:41], v[148:149]
	v_pk_fma_f32 v[148:149], v[204:205], v[42:43], v[148:149]
	v_pk_fma_f32 v[150:151], v[206:207], v[40:41], v[150:151]
	v_pk_fma_f32 v[150:151], v[208:209], v[42:43], v[150:151]
	v_pk_fma_f32 v[152:153], v[210:211], v[40:41], v[152:153]
	v_pk_fma_f32 v[152:153], v[212:213], v[42:43], v[152:153]
	v_pk_fma_f32 v[154:155], v[214:215], v[40:41], v[154:155]
	v_pk_fma_f32 v[154:155], v[216:217], v[42:43], v[154:155]
	v_pk_fma_f32 v[156:157], v[218:219], v[40:41], v[156:157]
	v_pk_fma_f32 v[156:157], v[220:221], v[42:43], v[156:157]
	v_pk_fma_f32 v[158:159], v[222:223], v[40:41], v[158:159]
	v_pk_fma_f32 v[158:159], v[224:225], v[42:43], v[158:159]
	ds_read_b128 v[202:205], v170 offset:176
	ds_read_b128 v[206:209], v170 offset:4272
	ds_read_b128 v[210:213], v170 offset:8368
	ds_read_b128 v[214:217], v170 offset:12464
	ds_read_b128 v[218:221], v170 offset:16560
	ds_read_b128 v[222:225], v170 offset:20656
	s_waitcnt lgkmcnt(6)
	v_pk_fma_f32 v[160:161], v[178:179], v[40:41], v[160:161]
	v_pk_fma_f32 v[160:161], v[180:181], v[42:43], v[160:161]
	v_pk_fma_f32 v[162:163], v[182:183], v[40:41], v[162:163]
	v_pk_fma_f32 v[162:163], v[184:185], v[42:43], v[162:163]
	v_pk_fma_f32 v[164:165], v[186:187], v[40:41], v[164:165]
	v_pk_fma_f32 v[164:165], v[188:189], v[42:43], v[164:165]
	v_pk_fma_f32 v[172:173], v[190:191], v[40:41], v[172:173]
	v_pk_fma_f32 v[172:173], v[192:193], v[42:43], v[172:173]
	v_pk_fma_f32 v[174:175], v[194:195], v[40:41], v[174:175]
	v_pk_fma_f32 v[174:175], v[196:197], v[42:43], v[174:175]
	v_pk_fma_f32 v[176:177], v[198:199], v[40:41], v[176:177]
	v_pk_fma_f32 v[176:177], v[200:201], v[42:43], v[176:177]
	ds_read_b128 v[178:181], v170 offset:24752
	ds_read_b128 v[182:185], v170 offset:28848
	ds_read_b128 v[186:189], v170 offset:32944
	ds_read_b128 v[190:193], v170 offset:37040
	ds_read_b128 v[194:197], v170 offset:41136
	ds_read_b128 v[198:201], v170 offset:45232
	s_waitcnt lgkmcnt(6)
	s_waitcnt vmcnt(63)
	v_pk_fma_f32 v[136:137], v[202:203], v[44:45], v[136:137]
	v_pk_fma_f32 v[136:137], v[204:205], v[46:47], v[136:137]
	v_pk_fma_f32 v[138:139], v[206:207], v[44:45], v[138:139]
	v_pk_fma_f32 v[138:139], v[208:209], v[46:47], v[138:139]
	v_pk_fma_f32 v[140:141], v[210:211], v[44:45], v[140:141]
	v_pk_fma_f32 v[140:141], v[212:213], v[46:47], v[140:141]
	v_pk_fma_f32 v[142:143], v[214:215], v[44:45], v[142:143]
	v_pk_fma_f32 v[142:143], v[216:217], v[46:47], v[142:143]
	v_pk_fma_f32 v[144:145], v[218:219], v[44:45], v[144:145]
	v_pk_fma_f32 v[144:145], v[220:221], v[46:47], v[144:145]
	v_pk_fma_f32 v[146:147], v[222:223], v[44:45], v[146:147]
	v_pk_fma_f32 v[146:147], v[224:225], v[46:47], v[146:147]
	ds_read_b128 v[202:205], v170 offset:49328
	ds_read_b128 v[206:209], v170 offset:53424
	ds_read_b128 v[210:213], v170 offset:57520
	ds_read_b128 v[214:217], v170 offset:61616
	ds_read_b128 v[218:221], v171 offset:176
	ds_read_b128 v[222:225], v171 offset:4272
	s_waitcnt lgkmcnt(6)
	v_pk_fma_f32 v[148:149], v[178:179], v[44:45], v[148:149]
	v_pk_fma_f32 v[148:149], v[180:181], v[46:47], v[148:149]
	v_pk_fma_f32 v[150:151], v[182:183], v[44:45], v[150:151]
	v_pk_fma_f32 v[150:151], v[184:185], v[46:47], v[150:151]
	v_pk_fma_f32 v[152:153], v[186:187], v[44:45], v[152:153]
	v_pk_fma_f32 v[152:153], v[188:189], v[46:47], v[152:153]
	v_pk_fma_f32 v[154:155], v[190:191], v[44:45], v[154:155]
	v_pk_fma_f32 v[154:155], v[192:193], v[46:47], v[154:155]
	v_pk_fma_f32 v[156:157], v[194:195], v[44:45], v[156:157]
	v_pk_fma_f32 v[156:157], v[196:197], v[46:47], v[156:157]
	v_pk_fma_f32 v[158:159], v[198:199], v[44:45], v[158:159]
	v_pk_fma_f32 v[158:159], v[200:201], v[46:47], v[158:159]
	ds_read_b128 v[178:181], v170 offset:192
	ds_read_b128 v[182:185], v170 offset:4288
	ds_read_b128 v[186:189], v170 offset:8384
	ds_read_b128 v[190:193], v170 offset:12480
	ds_read_b128 v[194:197], v170 offset:16576
	ds_read_b128 v[198:201], v170 offset:20672
	s_waitcnt lgkmcnt(6)
	v_pk_fma_f32 v[160:161], v[202:203], v[44:45], v[160:161]
	v_pk_fma_f32 v[160:161], v[204:205], v[46:47], v[160:161]
	v_pk_fma_f32 v[162:163], v[206:207], v[44:45], v[162:163]
	v_pk_fma_f32 v[162:163], v[208:209], v[46:47], v[162:163]
	v_pk_fma_f32 v[164:165], v[210:211], v[44:45], v[164:165]
	v_pk_fma_f32 v[164:165], v[212:213], v[46:47], v[164:165]
	v_pk_fma_f32 v[172:173], v[214:215], v[44:45], v[172:173]
	v_pk_fma_f32 v[172:173], v[216:217], v[46:47], v[172:173]
	v_pk_fma_f32 v[174:175], v[218:219], v[44:45], v[174:175]
	v_pk_fma_f32 v[174:175], v[220:221], v[46:47], v[174:175]
	v_pk_fma_f32 v[176:177], v[222:223], v[44:45], v[176:177]
	v_pk_fma_f32 v[176:177], v[224:225], v[46:47], v[176:177]
	ds_read_b128 v[202:205], v170 offset:24768
	ds_read_b128 v[206:209], v170 offset:28864
	ds_read_b128 v[210:213], v170 offset:32960
	ds_read_b128 v[214:217], v170 offset:37056
	ds_read_b128 v[218:221], v170 offset:41152
	ds_read_b128 v[222:225], v170 offset:45248
	s_waitcnt lgkmcnt(6)
	s_waitcnt vmcnt(63)
	v_pk_fma_f32 v[136:137], v[178:179], v[48:49], v[136:137]
	v_pk_fma_f32 v[136:137], v[180:181], v[50:51], v[136:137]
	v_pk_fma_f32 v[138:139], v[182:183], v[48:49], v[138:139]
	v_pk_fma_f32 v[138:139], v[184:185], v[50:51], v[138:139]
	v_pk_fma_f32 v[140:141], v[186:187], v[48:49], v[140:141]
	v_pk_fma_f32 v[140:141], v[188:189], v[50:51], v[140:141]
	v_pk_fma_f32 v[142:143], v[190:191], v[48:49], v[142:143]
	v_pk_fma_f32 v[142:143], v[192:193], v[50:51], v[142:143]
	v_pk_fma_f32 v[144:145], v[194:195], v[48:49], v[144:145]
	v_pk_fma_f32 v[144:145], v[196:197], v[50:51], v[144:145]
	v_pk_fma_f32 v[146:147], v[198:199], v[48:49], v[146:147]
	v_pk_fma_f32 v[146:147], v[200:201], v[50:51], v[146:147]
	ds_read_b128 v[178:181], v170 offset:49344
	ds_read_b128 v[182:185], v170 offset:53440
	ds_read_b128 v[186:189], v170 offset:57536
	ds_read_b128 v[190:193], v170 offset:61632
	ds_read_b128 v[194:197], v171 offset:192
	ds_read_b128 v[198:201], v171 offset:4288
	s_waitcnt lgkmcnt(6)
; #define LAS __attribute__((address_space(3)))
; DI void p0_mod_unit(const Params& p, int u, LAS unsigned char* ldsb) {
;     ...
;     for (int k = 0; k < 128; k += 4) {
;         const float w0 = wp[(size_t)(k + 0) * 3072], w1 = wp[(size_t)(k + 1) * 3072], w2 = wp[(size_t)(k + 2) * 3072], w3 = wp[(size_t)(k + 3) * 3072];
; #pragma unroll
;         for (int i = 0; i < 18; ++i) { const f32x4 s = *(const LAS f32x4*)(lds + i * 1024 + wid * 128 + k); acc[i] += s.x * w0 + s.y * w1 + s.z * w2 + s.w * w3; }
	v_pk_fma_f32 v[148:149], v[202:203], v[48:49], v[148:149]
	v_pk_fma_f32 v[148:149], v[204:205], v[50:51], v[148:149]
	v_pk_fma_f32 v[150:151], v[206:207], v[48:49], v[150:151]
	v_pk_fma_f32 v[150:151], v[208:209], v[50:51], v[150:151]
	v_pk_fma_f32 v[152:153], v[210:211], v[48:49], v[152:153]
	v_pk_fma_f32 v[152:153], v[212:213], v[50:51], v[152:153]
	v_pk_fma_f32 v[154:155], v[214:215], v[48:49], v[154:155]
	v_pk_fma_f32 v[154:155], v[216:217], v[50:51], v[154:155]
	v_pk_fma_f32 v[156:157], v[218:219], v[48:49], v[156:157]
	v_pk_fma_f32 v[156:157], v[220:221], v[50:51], v[156:157]
	v_pk_fma_f32 v[158:159], v[222:223], v[48:49], v[158:159]
	v_pk_fma_f32 v[158:159], v[224:225], v[50:51], v[158:159]
	ds_read_b128 v[202:205], v170 offset:208
	ds_read_b128 v[206:209], v170 offset:4304
	ds_read_b128 v[210:213], v170 offset:8400
	ds_read_b128 v[214:217], v170 offset:12496
	ds_read_b128 v[218:221], v170 offset:16592
	ds_read_b128 v[222:225], v170 offset:20688
	s_waitcnt lgkmcnt(6)
	v_pk_fma_f32 v[160:161], v[178:179], v[48:49], v[160:161]
	v_pk_fma_f32 v[160:161], v[180:181], v[50:51], v[160:161]
	v_pk_fma_f32 v[162:163], v[182:183], v[48:49], v[162:163]
	v_pk_fma_f32 v[162:163], v[184:185], v[50:51], v[162:163]
	v_pk_fma_f32 v[164:165], v[186:187], v[48:49], v[164:165]
	v_pk_fma_f32 v[164:165], v[188:189], v[50:51], v[164:165]
	v_pk_fma_f32 v[172:173], v[190:191], v[48:49], v[172:173]
	v_pk_fma_f32 v[172:173], v[192:193], v[50:51], v[172:173]
	v_pk_fma_f32 v[174:175], v[194:195], v[48:49], v[174:175]
	v_pk_fma_f32 v[174:175], v[196:197], v[50:51], v[174:175]
	v_pk_fma_f32 v[176:177], v[198:199], v[48:49], v[176:177]
	v_pk_fma_f32 v[176:177], v[200:201], v[50:51], v[176:177]
	ds_read_b128 v[178:181], v170 offset:24784
	ds_read_b128 v[182:185], v170 offset:28880
	ds_read_b128 v[186:189], v170 offset:32976
	ds_read_b128 v[190:193], v170 offset:37072
	ds_read_b128 v[194:197], v170 offset:41168
	ds_read_b128 v[198:201], v170 offset:45264
	s_waitcnt lgkmcnt(6)
	s_waitcnt vmcnt(63)
	v_pk_fma_f32 v[136:137], v[202:203], v[52:53], v[136:137]
	v_pk_fma_f32 v[136:137], v[204:205], v[54:55], v[136:137]
	v_pk_fma_f32 v[138:139], v[206:207], v[52:53], v[138:139]
	v_pk_fma_f32 v[138:139], v[208:209], v[54:55], v[138:139]
	v_pk_fma_f32 v[140:141], v[210:211], v[52:53], v[140:141]
	v_pk_fma_f32 v[140:141], v[212:213], v[54:55], v[140:141]
	v_pk_fma_f32 v[142:143], v[214:215], v[52:53], v[142:143]
	v_pk_fma_f32 v[142:143], v[216:217], v[54:55], v[142:143]
	v_pk_fma_f32 v[144:145], v[218:219], v[52:53], v[144:145]
	v_pk_fma_f32 v[144:145], v[220:221], v[54:55], v[144:145]
	v_pk_fma_f32 v[146:147], v[222:223], v[52:53], v[146:147]
	v_pk_fma_f32 v[146:147], v[224:225], v[54:55], v[146:147]
	ds_read_b128 v[202:205], v170 offset:49360
	ds_read_b128 v[206:209], v170 offset:53456
	ds_read_b128 v[210:213], v170 offset:57552
	ds_read_b128 v[214:217], v170 offset:61648
	ds_read_b128 v[218:221], v171 offset:208
	ds_read_b128 v[222:225], v171 offset:4304
	s_waitcnt lgkmcnt(6)
	v_pk_fma_f32 v[148:149], v[178:179], v[52:53], v[148:149]
	v_pk_fma_f32 v[148:149], v[180:181], v[54:55], v[148:149]
	v_pk_fma_f32 v[150:151], v[182:183], v[52:53], v[150:151]
	v_pk_fma_f32 v[150:151], v[184:185], v[54:55], v[150:151]
	v_pk_fma_f32 v[152:153], v[186:187], v[52:53], v[152:153]
	v_pk_fma_f32 v[152:153], v[188:189], v[54:55], v[152:153]
	v_pk_fma_f32 v[154:155], v[190:191], v[52:53], v[154:155]
	v_pk_fma_f32 v[154:155], v[192:193], v[54:55], v[154:155]
	v_pk_fma_f32 v[156:157], v[194:195], v[52:53], v[156:157]
	v_pk_fma_f32 v[156:157], v[196:197], v[54:55], v[156:157]
	v_pk_fma_f32 v[158:159], v[198:199], v[52:53], v[158:159]
	v_pk_fma_f32 v[158:159], v[200:201], v[54:55], v[158:159]
	ds_read_b128 v[178:181], v170 offset:224
	ds_read_b128 v[182:185], v170 offset:4320
	ds_read_b128 v[186:189], v170 offset:8416
	ds_read_b128 v[190:193], v170 offset:12512
	ds_read_b128 v[194:197], v170 offset:16608
	ds_read_b128 v[198:201], v170 offset:20704
	s_waitcnt lgkmcnt(6)
	v_pk_fma_f32 v[160:161], v[202:203], v[52:53], v[160:161]
	v_pk_fma_f32 v[160:161], v[204:205], v[54:55], v[160:161]
	v_pk_fma_f32 v[162:163], v[206:207], v[52:53], v[162:163]
	v_pk_fma_f32 v[162:163], v[208:209], v[54:55], v[162:163]
	v_pk_fma_f32 v[164:165], v[210:211], v[52:53], v[164:165]
	v_pk_fma_f32 v[164:165], v[212:213], v[54:55], v[164:165]
	v_pk_fma_f32 v[172:173], v[214:215], v[52:53], v[172:173]
	v_pk_fma_f32 v[172:173], v[216:217], v[54:55], v[172:173]
	v_pk_fma_f32 v[174:175], v[218:219], v[52:53], v[174:175]
	v_pk_fma_f32 v[174:175], v[220:221], v[54:55], v[174:175]
	v_pk_fma_f32 v[176:177], v[222:223], v[52:53], v[176:177]
	v_pk_fma_f32 v[176:177], v[224:225], v[54:55], v[176:177]
	ds_read_b128 v[202:205], v170 offset:24800
	ds_read_b128 v[206:209], v170 offset:28896
	ds_read_b128 v[210:213], v170 offset:32992
	ds_read_b128 v[214:217], v170 offset:37088
	ds_read_b128 v[218:221], v170 offset:41184
	ds_read_b128 v[222:225], v170 offset:45280
	s_waitcnt lgkmcnt(6)
	s_waitcnt vmcnt(63)
	v_pk_fma_f32 v[136:137], v[178:179], v[56:57], v[136:137]
	v_pk_fma_f32 v[136:137], v[180:181], v[58:59], v[136:137]
	v_pk_fma_f32 v[138:139], v[182:183], v[56:57], v[138:139]
	v_pk_fma_f32 v[138:139], v[184:185], v[58:59], v[138:139]
	v_pk_fma_f32 v[140:141], v[186:187], v[56:57], v[140:141]
	v_pk_fma_f32 v[140:141], v[188:189], v[58:59], v[140:141]
	v_pk_fma_f32 v[142:143], v[190:191], v[56:57], v[142:143]
	v_pk_fma_f32 v[142:143], v[192:193], v[58:59], v[142:143]
	v_pk_fma_f32 v[144:145], v[194:195], v[56:57], v[144:145]
	v_pk_fma_f32 v[144:145], v[196:197], v[58:59], v[144:145]
	v_pk_fma_f32 v[146:147], v[198:199], v[56:57], v[146:147]
	v_pk_fma_f32 v[146:147], v[200:201], v[58:59], v[146:147]
	ds_read_b128 v[178:181], v170 offset:49376
	ds_read_b128 v[182:185], v170 offset:53472
	ds_read_b128 v[186:189], v170 offset:57568
	ds_read_b128 v[190:193], v170 offset:61664
	ds_read_b128 v[194:197], v171 offset:224
	ds_read_b128 v[198:201], v171 offset:4320
	s_waitcnt lgkmcnt(6)
; #define LAS __attribute__((address_space(3)))
; DI void p0_mod_unit(const Params& p, int u, LAS unsigned char* ldsb) {
;     ...
;     for (int k = 0; k < 128; k += 4) {
;         const float w0 = wp[(size_t)(k + 0) * 3072], w1 = wp[(size_t)(k + 1) * 3072], w2 = wp[(size_t)(k + 2) * 3072], w3 = wp[(size_t)(k + 3) * 3072];
; #pragma unroll
;         for (int i = 0; i < 18; ++i) { const f32x4 s = *(const LAS f32x4*)(lds + i * 1024 + wid * 128 + k); acc[i] += s.x * w0 + s.y * w1 + s.z * w2 + s.w * w3; }
	v_pk_fma_f32 v[148:149], v[202:203], v[56:57], v[148:149]
	v_pk_fma_f32 v[148:149], v[204:205], v[58:59], v[148:149]
	v_pk_fma_f32 v[150:151], v[206:207], v[56:57], v[150:151]
	v_pk_fma_f32 v[150:151], v[208:209], v[58:59], v[150:151]
	v_pk_fma_f32 v[152:153], v[210:211], v[56:57], v[152:153]
	v_pk_fma_f32 v[152:153], v[212:213], v[58:59], v[152:153]
	v_pk_fma_f32 v[154:155], v[214:215], v[56:57], v[154:155]
	v_pk_fma_f32 v[154:155], v[216:217], v[58:59], v[154:155]
	v_pk_fma_f32 v[156:157], v[218:219], v[56:57], v[156:157]
	v_pk_fma_f32 v[156:157], v[220:221], v[58:59], v[156:157]
	v_pk_fma_f32 v[158:159], v[222:223], v[56:57], v[158:159]
	v_pk_fma_f32 v[158:159], v[224:225], v[58:59], v[158:159]
	ds_read_b128 v[202:205], v170 offset:240
	ds_read_b128 v[206:209], v170 offset:4336
	ds_read_b128 v[210:213], v170 offset:8432
	ds_read_b128 v[214:217], v170 offset:12528
	ds_read_b128 v[218:221], v170 offset:16624
	ds_read_b128 v[222:225], v170 offset:20720
	s_waitcnt lgkmcnt(6)
	v_pk_fma_f32 v[160:161], v[178:179], v[56:57], v[160:161]
	v_pk_fma_f32 v[160:161], v[180:181], v[58:59], v[160:161]
	v_pk_fma_f32 v[162:163], v[182:183], v[56:57], v[162:163]
	v_pk_fma_f32 v[162:163], v[184:185], v[58:59], v[162:163]
	v_pk_fma_f32 v[164:165], v[186:187], v[56:57], v[164:165]
	v_pk_fma_f32 v[164:165], v[188:189], v[58:59], v[164:165]
	v_pk_fma_f32 v[172:173], v[190:191], v[56:57], v[172:173]
	v_pk_fma_f32 v[172:173], v[192:193], v[58:59], v[172:173]
	v_pk_fma_f32 v[174:175], v[194:195], v[56:57], v[174:175]
	v_pk_fma_f32 v[174:175], v[196:197], v[58:59], v[174:175]
	v_pk_fma_f32 v[176:177], v[198:199], v[56:57], v[176:177]
	v_pk_fma_f32 v[176:177], v[200:201], v[58:59], v[176:177]
	ds_read_b128 v[178:181], v170 offset:24816
	ds_read_b128 v[182:185], v170 offset:28912
	ds_read_b128 v[186:189], v170 offset:33008
	ds_read_b128 v[190:193], v170 offset:37104
	ds_read_b128 v[194:197], v170 offset:41200
	ds_read_b128 v[198:201], v170 offset:45296
	s_waitcnt lgkmcnt(6)
	s_waitcnt vmcnt(63)
	v_pk_fma_f32 v[136:137], v[202:203], v[60:61], v[136:137]
	v_pk_fma_f32 v[136:137], v[204:205], v[62:63], v[136:137]
	v_pk_fma_f32 v[138:139], v[206:207], v[60:61], v[138:139]
	v_pk_fma_f32 v[138:139], v[208:209], v[62:63], v[138:139]
	v_pk_fma_f32 v[140:141], v[210:211], v[60:61], v[140:141]
	v_pk_fma_f32 v[140:141], v[212:213], v[62:63], v[140:141]
	v_pk_fma_f32 v[142:143], v[214:215], v[60:61], v[142:143]
	v_pk_fma_f32 v[142:143], v[216:217], v[62:63], v[142:143]
	v_pk_fma_f32 v[144:145], v[218:219], v[60:61], v[144:145]
	v_pk_fma_f32 v[144:145], v[220:221], v[62:63], v[144:145]
	v_pk_fma_f32 v[146:147], v[222:223], v[60:61], v[146:147]
	v_pk_fma_f32 v[146:147], v[224:225], v[62:63], v[146:147]
	ds_read_b128 v[202:205], v170 offset:49392
	ds_read_b128 v[206:209], v170 offset:53488
	ds_read_b128 v[210:213], v170 offset:57584
	ds_read_b128 v[214:217], v170 offset:61680
	ds_read_b128 v[218:221], v171 offset:240
	ds_read_b128 v[222:225], v171 offset:4336
	s_waitcnt lgkmcnt(6)
	v_pk_fma_f32 v[148:149], v[178:179], v[60:61], v[148:149]
	v_pk_fma_f32 v[148:149], v[180:181], v[62:63], v[148:149]
	v_pk_fma_f32 v[150:151], v[182:183], v[60:61], v[150:151]
	v_pk_fma_f32 v[150:151], v[184:185], v[62:63], v[150:151]
	v_pk_fma_f32 v[152:153], v[186:187], v[60:61], v[152:153]
	v_pk_fma_f32 v[152:153], v[188:189], v[62:63], v[152:153]
	v_pk_fma_f32 v[154:155], v[190:191], v[60:61], v[154:155]
	v_pk_fma_f32 v[154:155], v[192:193], v[62:63], v[154:155]
	v_pk_fma_f32 v[156:157], v[194:195], v[60:61], v[156:157]
	v_pk_fma_f32 v[156:157], v[196:197], v[62:63], v[156:157]
	v_pk_fma_f32 v[158:159], v[198:199], v[60:61], v[158:159]
	v_pk_fma_f32 v[158:159], v[200:201], v[62:63], v[158:159]
	ds_read_b128 v[178:181], v170 offset:256
	ds_read_b128 v[182:185], v170 offset:4352
	ds_read_b128 v[186:189], v170 offset:8448
	ds_read_b128 v[190:193], v170 offset:12544
	ds_read_b128 v[194:197], v170 offset:16640
	ds_read_b128 v[198:201], v170 offset:20736
	s_waitcnt lgkmcnt(6)
	v_pk_fma_f32 v[160:161], v[202:203], v[60:61], v[160:161]
	v_pk_fma_f32 v[160:161], v[204:205], v[62:63], v[160:161]
	v_pk_fma_f32 v[162:163], v[206:207], v[60:61], v[162:163]
	v_pk_fma_f32 v[162:163], v[208:209], v[62:63], v[162:163]
	v_pk_fma_f32 v[164:165], v[210:211], v[60:61], v[164:165]
	v_pk_fma_f32 v[164:165], v[212:213], v[62:63], v[164:165]
	v_pk_fma_f32 v[172:173], v[214:215], v[60:61], v[172:173]
	v_pk_fma_f32 v[172:173], v[216:217], v[62:63], v[172:173]
	v_pk_fma_f32 v[174:175], v[218:219], v[60:61], v[174:175]
	v_pk_fma_f32 v[174:175], v[220:221], v[62:63], v[174:175]
	v_pk_fma_f32 v[176:177], v[222:223], v[60:61], v[176:177]
	v_pk_fma_f32 v[176:177], v[224:225], v[62:63], v[176:177]
	ds_read_b128 v[202:205], v170 offset:24832
	ds_read_b128 v[206:209], v170 offset:28928
	ds_read_b128 v[210:213], v170 offset:33024
	ds_read_b128 v[214:217], v170 offset:37120
	ds_read_b128 v[218:221], v170 offset:41216
	ds_read_b128 v[222:225], v170 offset:45312
	s_waitcnt lgkmcnt(6)
	s_waitcnt vmcnt(60)
	v_pk_fma_f32 v[136:137], v[178:179], v[64:65], v[136:137]
	v_pk_fma_f32 v[136:137], v[180:181], v[66:67], v[136:137]
	v_pk_fma_f32 v[138:139], v[182:183], v[64:65], v[138:139]
	v_pk_fma_f32 v[138:139], v[184:185], v[66:67], v[138:139]
	v_pk_fma_f32 v[140:141], v[186:187], v[64:65], v[140:141]
	v_pk_fma_f32 v[140:141], v[188:189], v[66:67], v[140:141]
	v_pk_fma_f32 v[142:143], v[190:191], v[64:65], v[142:143]
	v_pk_fma_f32 v[142:143], v[192:193], v[66:67], v[142:143]
	v_pk_fma_f32 v[144:145], v[194:195], v[64:65], v[144:145]
	v_pk_fma_f32 v[144:145], v[196:197], v[66:67], v[144:145]
	v_pk_fma_f32 v[146:147], v[198:199], v[64:65], v[146:147]
	v_pk_fma_f32 v[146:147], v[200:201], v[66:67], v[146:147]
	ds_read_b128 v[178:181], v170 offset:49408
	ds_read_b128 v[182:185], v170 offset:53504
	ds_read_b128 v[186:189], v170 offset:57600
	ds_read_b128 v[190:193], v170 offset:61696
	ds_read_b128 v[194:197], v171 offset:256
	ds_read_b128 v[198:201], v171 offset:4352
	s_waitcnt lgkmcnt(6)
; #define LAS __attribute__((address_space(3)))
; DI void p0_mod_unit(const Params& p, int u, LAS unsigned char* ldsb) {
;     ...
;     for (int k = 0; k < 128; k += 4) {
;         const float w0 = wp[(size_t)(k + 0) * 3072], w1 = wp[(size_t)(k + 1) * 3072], w2 = wp[(size_t)(k + 2) * 3072], w3 = wp[(size_t)(k + 3) * 3072];
; #pragma unroll
;         for (int i = 0; i < 18; ++i) { const f32x4 s = *(const LAS f32x4*)(lds + i * 1024 + wid * 128 + k); acc[i] += s.x * w0 + s.y * w1 + s.z * w2 + s.w * w3; }
	v_pk_fma_f32 v[148:149], v[202:203], v[64:65], v[148:149]
	v_pk_fma_f32 v[148:149], v[204:205], v[66:67], v[148:149]
	v_pk_fma_f32 v[150:151], v[206:207], v[64:65], v[150:151]
	v_pk_fma_f32 v[150:151], v[208:209], v[66:67], v[150:151]
	v_pk_fma_f32 v[152:153], v[210:211], v[64:65], v[152:153]
	v_pk_fma_f32 v[152:153], v[212:213], v[66:67], v[152:153]
	v_pk_fma_f32 v[154:155], v[214:215], v[64:65], v[154:155]
	v_pk_fma_f32 v[154:155], v[216:217], v[66:67], v[154:155]
	v_pk_fma_f32 v[156:157], v[218:219], v[64:65], v[156:157]
	v_pk_fma_f32 v[156:157], v[220:221], v[66:67], v[156:157]
	v_pk_fma_f32 v[158:159], v[222:223], v[64:65], v[158:159]
	v_pk_fma_f32 v[158:159], v[224:225], v[66:67], v[158:159]
	ds_read_b128 v[202:205], v170 offset:272
	ds_read_b128 v[206:209], v170 offset:4368
	ds_read_b128 v[210:213], v170 offset:8464
	ds_read_b128 v[214:217], v170 offset:12560
	ds_read_b128 v[218:221], v170 offset:16656
	ds_read_b128 v[222:225], v170 offset:20752
	s_waitcnt lgkmcnt(6)
	v_pk_fma_f32 v[160:161], v[178:179], v[64:65], v[160:161]
	v_pk_fma_f32 v[160:161], v[180:181], v[66:67], v[160:161]
	v_pk_fma_f32 v[162:163], v[182:183], v[64:65], v[162:163]
	v_pk_fma_f32 v[162:163], v[184:185], v[66:67], v[162:163]
	v_pk_fma_f32 v[164:165], v[186:187], v[64:65], v[164:165]
	v_pk_fma_f32 v[164:165], v[188:189], v[66:67], v[164:165]
	v_pk_fma_f32 v[172:173], v[190:191], v[64:65], v[172:173]
	v_pk_fma_f32 v[172:173], v[192:193], v[66:67], v[172:173]
	v_pk_fma_f32 v[174:175], v[194:195], v[64:65], v[174:175]
	v_pk_fma_f32 v[174:175], v[196:197], v[66:67], v[174:175]
	v_pk_fma_f32 v[176:177], v[198:199], v[64:65], v[176:177]
	v_pk_fma_f32 v[176:177], v[200:201], v[66:67], v[176:177]
	ds_read_b128 v[178:181], v170 offset:24848
	ds_read_b128 v[182:185], v170 offset:28944
	ds_read_b128 v[186:189], v170 offset:33040
	ds_read_b128 v[190:193], v170 offset:37136
	ds_read_b128 v[194:197], v170 offset:41232
	ds_read_b128 v[198:201], v170 offset:45328
	s_waitcnt lgkmcnt(6)
	s_waitcnt vmcnt(56)
	v_pk_fma_f32 v[136:137], v[202:203], v[68:69], v[136:137]
	v_pk_fma_f32 v[136:137], v[204:205], v[70:71], v[136:137]
	v_pk_fma_f32 v[138:139], v[206:207], v[68:69], v[138:139]
	v_pk_fma_f32 v[138:139], v[208:209], v[70:71], v[138:139]
	v_pk_fma_f32 v[140:141], v[210:211], v[68:69], v[140:141]
	v_pk_fma_f32 v[140:141], v[212:213], v[70:71], v[140:141]
	v_pk_fma_f32 v[142:143], v[214:215], v[68:69], v[142:143]
	v_pk_fma_f32 v[142:143], v[216:217], v[70:71], v[142:143]
	v_pk_fma_f32 v[144:145], v[218:219], v[68:69], v[144:145]
	v_pk_fma_f32 v[144:145], v[220:221], v[70:71], v[144:145]
	v_pk_fma_f32 v[146:147], v[222:223], v[68:69], v[146:147]
	v_pk_fma_f32 v[146:147], v[224:225], v[70:71], v[146:147]
	ds_read_b128 v[202:205], v170 offset:49424
	ds_read_b128 v[206:209], v170 offset:53520
	ds_read_b128 v[210:213], v170 offset:57616
	ds_read_b128 v[214:217], v170 offset:61712
	ds_read_b128 v[218:221], v171 offset:272
	ds_read_b128 v[222:225], v171 offset:4368
	s_waitcnt lgkmcnt(6)
	v_pk_fma_f32 v[148:149], v[178:179], v[68:69], v[148:149]
	v_pk_fma_f32 v[148:149], v[180:181], v[70:71], v[148:149]
	v_pk_fma_f32 v[150:151], v[182:183], v[68:69], v[150:151]
	v_pk_fma_f32 v[150:151], v[184:185], v[70:71], v[150:151]
	v_pk_fma_f32 v[152:153], v[186:187], v[68:69], v[152:153]
	v_pk_fma_f32 v[152:153], v[188:189], v[70:71], v[152:153]
	v_pk_fma_f32 v[154:155], v[190:191], v[68:69], v[154:155]
	v_pk_fma_f32 v[154:155], v[192:193], v[70:71], v[154:155]
	v_pk_fma_f32 v[156:157], v[194:195], v[68:69], v[156:157]
	v_pk_fma_f32 v[156:157], v[196:197], v[70:71], v[156:157]
	v_pk_fma_f32 v[158:159], v[198:199], v[68:69], v[158:159]
	v_pk_fma_f32 v[158:159], v[200:201], v[70:71], v[158:159]
	ds_read_b128 v[178:181], v170 offset:288
	ds_read_b128 v[182:185], v170 offset:4384
	ds_read_b128 v[186:189], v170 offset:8480
	ds_read_b128 v[190:193], v170 offset:12576
	ds_read_b128 v[194:197], v170 offset:16672
	ds_read_b128 v[198:201], v170 offset:20768
	s_waitcnt lgkmcnt(6)
	v_pk_fma_f32 v[160:161], v[202:203], v[68:69], v[160:161]
	v_pk_fma_f32 v[160:161], v[204:205], v[70:71], v[160:161]
	v_pk_fma_f32 v[162:163], v[206:207], v[68:69], v[162:163]
	v_pk_fma_f32 v[162:163], v[208:209], v[70:71], v[162:163]
	v_pk_fma_f32 v[164:165], v[210:211], v[68:69], v[164:165]
	v_pk_fma_f32 v[164:165], v[212:213], v[70:71], v[164:165]
	v_pk_fma_f32 v[172:173], v[214:215], v[68:69], v[172:173]
	v_pk_fma_f32 v[172:173], v[216:217], v[70:71], v[172:173]
	v_pk_fma_f32 v[174:175], v[218:219], v[68:69], v[174:175]
	v_pk_fma_f32 v[174:175], v[220:221], v[70:71], v[174:175]
	v_pk_fma_f32 v[176:177], v[222:223], v[68:69], v[176:177]
	v_pk_fma_f32 v[176:177], v[224:225], v[70:71], v[176:177]
	ds_read_b128 v[202:205], v170 offset:24864
	ds_read_b128 v[206:209], v170 offset:28960
	ds_read_b128 v[210:213], v170 offset:33056
	ds_read_b128 v[214:217], v170 offset:37152
	ds_read_b128 v[218:221], v170 offset:41248
	ds_read_b128 v[222:225], v170 offset:45344
	s_waitcnt lgkmcnt(6)
	s_waitcnt vmcnt(52)
	v_pk_fma_f32 v[136:137], v[178:179], v[72:73], v[136:137]
	v_pk_fma_f32 v[136:137], v[180:181], v[74:75], v[136:137]
	v_pk_fma_f32 v[138:139], v[182:183], v[72:73], v[138:139]
	v_pk_fma_f32 v[138:139], v[184:185], v[74:75], v[138:139]
	v_pk_fma_f32 v[140:141], v[186:187], v[72:73], v[140:141]
	v_pk_fma_f32 v[140:141], v[188:189], v[74:75], v[140:141]
	v_pk_fma_f32 v[142:143], v[190:191], v[72:73], v[142:143]
	v_pk_fma_f32 v[142:143], v[192:193], v[74:75], v[142:143]
	v_pk_fma_f32 v[144:145], v[194:195], v[72:73], v[144:145]
	v_pk_fma_f32 v[144:145], v[196:197], v[74:75], v[144:145]
	v_pk_fma_f32 v[146:147], v[198:199], v[72:73], v[146:147]
	v_pk_fma_f32 v[146:147], v[200:201], v[74:75], v[146:147]
	ds_read_b128 v[178:181], v170 offset:49440
	ds_read_b128 v[182:185], v170 offset:53536
	ds_read_b128 v[186:189], v170 offset:57632
	ds_read_b128 v[190:193], v170 offset:61728
	ds_read_b128 v[194:197], v171 offset:288
	ds_read_b128 v[198:201], v171 offset:4384
	s_waitcnt lgkmcnt(6)
; #define LAS __attribute__((address_space(3)))
; DI void p0_mod_unit(const Params& p, int u, LAS unsigned char* ldsb) {
;     ...
;     for (int k = 0; k < 128; k += 4) {
;         const float w0 = wp[(size_t)(k + 0) * 3072], w1 = wp[(size_t)(k + 1) * 3072], w2 = wp[(size_t)(k + 2) * 3072], w3 = wp[(size_t)(k + 3) * 3072];
; #pragma unroll
;         for (int i = 0; i < 18; ++i) { const f32x4 s = *(const LAS f32x4*)(lds + i * 1024 + wid * 128 + k); acc[i] += s.x * w0 + s.y * w1 + s.z * w2 + s.w * w3; }
	v_pk_fma_f32 v[148:149], v[202:203], v[72:73], v[148:149]
	v_pk_fma_f32 v[148:149], v[204:205], v[74:75], v[148:149]
	v_pk_fma_f32 v[150:151], v[206:207], v[72:73], v[150:151]
	v_pk_fma_f32 v[150:151], v[208:209], v[74:75], v[150:151]
	v_pk_fma_f32 v[152:153], v[210:211], v[72:73], v[152:153]
	v_pk_fma_f32 v[152:153], v[212:213], v[74:75], v[152:153]
	v_pk_fma_f32 v[154:155], v[214:215], v[72:73], v[154:155]
	v_pk_fma_f32 v[154:155], v[216:217], v[74:75], v[154:155]
	v_pk_fma_f32 v[156:157], v[218:219], v[72:73], v[156:157]
	v_pk_fma_f32 v[156:157], v[220:221], v[74:75], v[156:157]
	v_pk_fma_f32 v[158:159], v[222:223], v[72:73], v[158:159]
	v_pk_fma_f32 v[158:159], v[224:225], v[74:75], v[158:159]
	ds_read_b128 v[202:205], v170 offset:304
	ds_read_b128 v[206:209], v170 offset:4400
	ds_read_b128 v[210:213], v170 offset:8496
	ds_read_b128 v[214:217], v170 offset:12592
	ds_read_b128 v[218:221], v170 offset:16688
	ds_read_b128 v[222:225], v170 offset:20784
	s_waitcnt lgkmcnt(6)
	v_pk_fma_f32 v[160:161], v[178:179], v[72:73], v[160:161]
	v_pk_fma_f32 v[160:161], v[180:181], v[74:75], v[160:161]
	v_pk_fma_f32 v[162:163], v[182:183], v[72:73], v[162:163]
	v_pk_fma_f32 v[162:163], v[184:185], v[74:75], v[162:163]
	v_pk_fma_f32 v[164:165], v[186:187], v[72:73], v[164:165]
	v_pk_fma_f32 v[164:165], v[188:189], v[74:75], v[164:165]
	v_pk_fma_f32 v[172:173], v[190:191], v[72:73], v[172:173]
	v_pk_fma_f32 v[172:173], v[192:193], v[74:75], v[172:173]
	v_pk_fma_f32 v[174:175], v[194:195], v[72:73], v[174:175]
	v_pk_fma_f32 v[174:175], v[196:197], v[74:75], v[174:175]
	v_pk_fma_f32 v[176:177], v[198:199], v[72:73], v[176:177]
	v_pk_fma_f32 v[176:177], v[200:201], v[74:75], v[176:177]
	ds_read_b128 v[178:181], v170 offset:24880
	ds_read_b128 v[182:185], v170 offset:28976
	ds_read_b128 v[186:189], v170 offset:33072
	ds_read_b128 v[190:193], v170 offset:37168
	ds_read_b128 v[194:197], v170 offset:41264
	ds_read_b128 v[198:201], v170 offset:45360
	s_waitcnt lgkmcnt(6)
	s_waitcnt vmcnt(48)
	v_pk_fma_f32 v[136:137], v[202:203], v[76:77], v[136:137]
	v_pk_fma_f32 v[136:137], v[204:205], v[78:79], v[136:137]
	v_pk_fma_f32 v[138:139], v[206:207], v[76:77], v[138:139]
	v_pk_fma_f32 v[138:139], v[208:209], v[78:79], v[138:139]
	v_pk_fma_f32 v[140:141], v[210:211], v[76:77], v[140:141]
	v_pk_fma_f32 v[140:141], v[212:213], v[78:79], v[140:141]
	v_pk_fma_f32 v[142:143], v[214:215], v[76:77], v[142:143]
	v_pk_fma_f32 v[142:143], v[216:217], v[78:79], v[142:143]
	v_pk_fma_f32 v[144:145], v[218:219], v[76:77], v[144:145]
	v_pk_fma_f32 v[144:145], v[220:221], v[78:79], v[144:145]
	v_pk_fma_f32 v[146:147], v[222:223], v[76:77], v[146:147]
	v_pk_fma_f32 v[146:147], v[224:225], v[78:79], v[146:147]
	ds_read_b128 v[202:205], v170 offset:49456
	ds_read_b128 v[206:209], v170 offset:53552
	ds_read_b128 v[210:213], v170 offset:57648
	ds_read_b128 v[214:217], v170 offset:61744
	ds_read_b128 v[218:221], v171 offset:304
	ds_read_b128 v[222:225], v171 offset:4400
	s_waitcnt lgkmcnt(6)
	v_pk_fma_f32 v[148:149], v[178:179], v[76:77], v[148:149]
	v_pk_fma_f32 v[148:149], v[180:181], v[78:79], v[148:149]
	v_pk_fma_f32 v[150:151], v[182:183], v[76:77], v[150:151]
	v_pk_fma_f32 v[150:151], v[184:185], v[78:79], v[150:151]
	v_pk_fma_f32 v[152:153], v[186:187], v[76:77], v[152:153]
	v_pk_fma_f32 v[152:153], v[188:189], v[78:79], v[152:153]
	v_pk_fma_f32 v[154:155], v[190:191], v[76:77], v[154:155]
	v_pk_fma_f32 v[154:155], v[192:193], v[78:79], v[154:155]
	v_pk_fma_f32 v[156:157], v[194:195], v[76:77], v[156:157]
	v_pk_fma_f32 v[156:157], v[196:197], v[78:79], v[156:157]
	v_pk_fma_f32 v[158:159], v[198:199], v[76:77], v[158:159]
	v_pk_fma_f32 v[158:159], v[200:201], v[78:79], v[158:159]
	ds_read_b128 v[178:181], v170 offset:320
	ds_read_b128 v[182:185], v170 offset:4416
	ds_read_b128 v[186:189], v170 offset:8512
	ds_read_b128 v[190:193], v170 offset:12608
	ds_read_b128 v[194:197], v170 offset:16704
	ds_read_b128 v[198:201], v170 offset:20800
	s_waitcnt lgkmcnt(6)
	v_pk_fma_f32 v[160:161], v[202:203], v[76:77], v[160:161]
	v_pk_fma_f32 v[160:161], v[204:205], v[78:79], v[160:161]
	v_pk_fma_f32 v[162:163], v[206:207], v[76:77], v[162:163]
	v_pk_fma_f32 v[162:163], v[208:209], v[78:79], v[162:163]
	v_pk_fma_f32 v[164:165], v[210:211], v[76:77], v[164:165]
	v_pk_fma_f32 v[164:165], v[212:213], v[78:79], v[164:165]
	v_pk_fma_f32 v[172:173], v[214:215], v[76:77], v[172:173]
	v_pk_fma_f32 v[172:173], v[216:217], v[78:79], v[172:173]
	v_pk_fma_f32 v[174:175], v[218:219], v[76:77], v[174:175]
	v_pk_fma_f32 v[174:175], v[220:221], v[78:79], v[174:175]
	v_pk_fma_f32 v[176:177], v[222:223], v[76:77], v[176:177]
	v_pk_fma_f32 v[176:177], v[224:225], v[78:79], v[176:177]
	ds_read_b128 v[202:205], v170 offset:24896
	ds_read_b128 v[206:209], v170 offset:28992
	ds_read_b128 v[210:213], v170 offset:33088
	ds_read_b128 v[214:217], v170 offset:37184
	ds_read_b128 v[218:221], v170 offset:41280
	ds_read_b128 v[222:225], v170 offset:45376
	s_waitcnt lgkmcnt(6)
	s_waitcnt vmcnt(44)
	v_pk_fma_f32 v[136:137], v[178:179], v[80:81], v[136:137]
	v_pk_fma_f32 v[136:137], v[180:181], v[82:83], v[136:137]
	v_pk_fma_f32 v[138:139], v[182:183], v[80:81], v[138:139]
	v_pk_fma_f32 v[138:139], v[184:185], v[82:83], v[138:139]
	v_pk_fma_f32 v[140:141], v[186:187], v[80:81], v[140:141]
	v_pk_fma_f32 v[140:141], v[188:189], v[82:83], v[140:141]
	v_pk_fma_f32 v[142:143], v[190:191], v[80:81], v[142:143]
	v_pk_fma_f32 v[142:143], v[192:193], v[82:83], v[142:143]
	v_pk_fma_f32 v[144:145], v[194:195], v[80:81], v[144:145]
	v_pk_fma_f32 v[144:145], v[196:197], v[82:83], v[144:145]
	v_pk_fma_f32 v[146:147], v[198:199], v[80:81], v[146:147]
	v_pk_fma_f32 v[146:147], v[200:201], v[82:83], v[146:147]
	ds_read_b128 v[178:181], v170 offset:49472
	ds_read_b128 v[182:185], v170 offset:53568
	ds_read_b128 v[186:189], v170 offset:57664
	ds_read_b128 v[190:193], v170 offset:61760
	ds_read_b128 v[194:197], v171 offset:320
	ds_read_b128 v[198:201], v171 offset:4416
	s_waitcnt lgkmcnt(6)
; #define LAS __attribute__((address_space(3)))
; DI void p0_mod_unit(const Params& p, int u, LAS unsigned char* ldsb) {
;     ...
;     for (int k = 0; k < 128; k += 4) {
;         const float w0 = wp[(size_t)(k + 0) * 3072], w1 = wp[(size_t)(k + 1) * 3072], w2 = wp[(size_t)(k + 2) * 3072], w3 = wp[(size_t)(k + 3) * 3072];
; #pragma unroll
;         for (int i = 0; i < 18; ++i) { const f32x4 s = *(const LAS f32x4*)(lds + i * 1024 + wid * 128 + k); acc[i] += s.x * w0 + s.y * w1 + s.z * w2 + s.w * w3; }
	v_pk_fma_f32 v[148:149], v[202:203], v[80:81], v[148:149]
	v_pk_fma_f32 v[148:149], v[204:205], v[82:83], v[148:149]
	v_pk_fma_f32 v[150:151], v[206:207], v[80:81], v[150:151]
	v_pk_fma_f32 v[150:151], v[208:209], v[82:83], v[150:151]
	v_pk_fma_f32 v[152:153], v[210:211], v[80:81], v[152:153]
	v_pk_fma_f32 v[152:153], v[212:213], v[82:83], v[152:153]
	v_pk_fma_f32 v[154:155], v[214:215], v[80:81], v[154:155]
	v_pk_fma_f32 v[154:155], v[216:217], v[82:83], v[154:155]
	v_pk_fma_f32 v[156:157], v[218:219], v[80:81], v[156:157]
	v_pk_fma_f32 v[156:157], v[220:221], v[82:83], v[156:157]
	v_pk_fma_f32 v[158:159], v[222:223], v[80:81], v[158:159]
	v_pk_fma_f32 v[158:159], v[224:225], v[82:83], v[158:159]
	ds_read_b128 v[202:205], v170 offset:336
	ds_read_b128 v[206:209], v170 offset:4432
	ds_read_b128 v[210:213], v170 offset:8528
	ds_read_b128 v[214:217], v170 offset:12624
	ds_read_b128 v[218:221], v170 offset:16720
	ds_read_b128 v[222:225], v170 offset:20816
	s_waitcnt lgkmcnt(6)
	v_pk_fma_f32 v[160:161], v[178:179], v[80:81], v[160:161]
	v_pk_fma_f32 v[160:161], v[180:181], v[82:83], v[160:161]
	v_pk_fma_f32 v[162:163], v[182:183], v[80:81], v[162:163]
	v_pk_fma_f32 v[162:163], v[184:185], v[82:83], v[162:163]
	v_pk_fma_f32 v[164:165], v[186:187], v[80:81], v[164:165]
	v_pk_fma_f32 v[164:165], v[188:189], v[82:83], v[164:165]
	v_pk_fma_f32 v[172:173], v[190:191], v[80:81], v[172:173]
	v_pk_fma_f32 v[172:173], v[192:193], v[82:83], v[172:173]
	v_pk_fma_f32 v[174:175], v[194:195], v[80:81], v[174:175]
	v_pk_fma_f32 v[174:175], v[196:197], v[82:83], v[174:175]
	v_pk_fma_f32 v[176:177], v[198:199], v[80:81], v[176:177]
	v_pk_fma_f32 v[176:177], v[200:201], v[82:83], v[176:177]
	ds_read_b128 v[178:181], v170 offset:24912
	ds_read_b128 v[182:185], v170 offset:29008
	ds_read_b128 v[186:189], v170 offset:33104
	ds_read_b128 v[190:193], v170 offset:37200
	ds_read_b128 v[194:197], v170 offset:41296
	ds_read_b128 v[198:201], v170 offset:45392
	s_waitcnt lgkmcnt(6)
	s_waitcnt vmcnt(40)
	v_pk_fma_f32 v[136:137], v[202:203], v[84:85], v[136:137]
	v_pk_fma_f32 v[136:137], v[204:205], v[86:87], v[136:137]
	v_pk_fma_f32 v[138:139], v[206:207], v[84:85], v[138:139]
	v_pk_fma_f32 v[138:139], v[208:209], v[86:87], v[138:139]
	v_pk_fma_f32 v[140:141], v[210:211], v[84:85], v[140:141]
	v_pk_fma_f32 v[140:141], v[212:213], v[86:87], v[140:141]
	v_pk_fma_f32 v[142:143], v[214:215], v[84:85], v[142:143]
	v_pk_fma_f32 v[142:143], v[216:217], v[86:87], v[142:143]
	v_pk_fma_f32 v[144:145], v[218:219], v[84:85], v[144:145]
	v_pk_fma_f32 v[144:145], v[220:221], v[86:87], v[144:145]
	v_pk_fma_f32 v[146:147], v[222:223], v[84:85], v[146:147]
	v_pk_fma_f32 v[146:147], v[224:225], v[86:87], v[146:147]
	ds_read_b128 v[202:205], v170 offset:49488
	ds_read_b128 v[206:209], v170 offset:53584
	ds_read_b128 v[210:213], v170 offset:57680
	ds_read_b128 v[214:217], v170 offset:61776
	ds_read_b128 v[218:221], v171 offset:336
	ds_read_b128 v[222:225], v171 offset:4432
	s_waitcnt lgkmcnt(6)
	v_pk_fma_f32 v[148:149], v[178:179], v[84:85], v[148:149]
	v_pk_fma_f32 v[148:149], v[180:181], v[86:87], v[148:149]
	v_pk_fma_f32 v[150:151], v[182:183], v[84:85], v[150:151]
	v_pk_fma_f32 v[150:151], v[184:185], v[86:87], v[150:151]
	v_pk_fma_f32 v[152:153], v[186:187], v[84:85], v[152:153]
	v_pk_fma_f32 v[152:153], v[188:189], v[86:87], v[152:153]
	v_pk_fma_f32 v[154:155], v[190:191], v[84:85], v[154:155]
	v_pk_fma_f32 v[154:155], v[192:193], v[86:87], v[154:155]
	v_pk_fma_f32 v[156:157], v[194:195], v[84:85], v[156:157]
	v_pk_fma_f32 v[156:157], v[196:197], v[86:87], v[156:157]
	v_pk_fma_f32 v[158:159], v[198:199], v[84:85], v[158:159]
	v_pk_fma_f32 v[158:159], v[200:201], v[86:87], v[158:159]
	ds_read_b128 v[178:181], v170 offset:352
	ds_read_b128 v[182:185], v170 offset:4448
	ds_read_b128 v[186:189], v170 offset:8544
	ds_read_b128 v[190:193], v170 offset:12640
	ds_read_b128 v[194:197], v170 offset:16736
	ds_read_b128 v[198:201], v170 offset:20832
	s_waitcnt lgkmcnt(6)
	v_pk_fma_f32 v[160:161], v[202:203], v[84:85], v[160:161]
	v_pk_fma_f32 v[160:161], v[204:205], v[86:87], v[160:161]
	v_pk_fma_f32 v[162:163], v[206:207], v[84:85], v[162:163]
	v_pk_fma_f32 v[162:163], v[208:209], v[86:87], v[162:163]
	v_pk_fma_f32 v[164:165], v[210:211], v[84:85], v[164:165]
	v_pk_fma_f32 v[164:165], v[212:213], v[86:87], v[164:165]
	v_pk_fma_f32 v[172:173], v[214:215], v[84:85], v[172:173]
	v_pk_fma_f32 v[172:173], v[216:217], v[86:87], v[172:173]
	v_pk_fma_f32 v[174:175], v[218:219], v[84:85], v[174:175]
	v_pk_fma_f32 v[174:175], v[220:221], v[86:87], v[174:175]
	v_pk_fma_f32 v[176:177], v[222:223], v[84:85], v[176:177]
	v_pk_fma_f32 v[176:177], v[224:225], v[86:87], v[176:177]
	ds_read_b128 v[202:205], v170 offset:24928
	ds_read_b128 v[206:209], v170 offset:29024
	ds_read_b128 v[210:213], v170 offset:33120
	ds_read_b128 v[214:217], v170 offset:37216
	ds_read_b128 v[218:221], v170 offset:41312
	ds_read_b128 v[222:225], v170 offset:45408
	s_waitcnt lgkmcnt(6)
	s_waitcnt vmcnt(36)
	v_pk_fma_f32 v[136:137], v[178:179], v[88:89], v[136:137]
	v_pk_fma_f32 v[136:137], v[180:181], v[90:91], v[136:137]
	v_pk_fma_f32 v[138:139], v[182:183], v[88:89], v[138:139]
	v_pk_fma_f32 v[138:139], v[184:185], v[90:91], v[138:139]
	v_pk_fma_f32 v[140:141], v[186:187], v[88:89], v[140:141]
	v_pk_fma_f32 v[140:141], v[188:189], v[90:91], v[140:141]
	v_pk_fma_f32 v[142:143], v[190:191], v[88:89], v[142:143]
	v_pk_fma_f32 v[142:143], v[192:193], v[90:91], v[142:143]
	v_pk_fma_f32 v[144:145], v[194:195], v[88:89], v[144:145]
	v_pk_fma_f32 v[144:145], v[196:197], v[90:91], v[144:145]
	v_pk_fma_f32 v[146:147], v[198:199], v[88:89], v[146:147]
	v_pk_fma_f32 v[146:147], v[200:201], v[90:91], v[146:147]
	ds_read_b128 v[178:181], v170 offset:49504
	ds_read_b128 v[182:185], v170 offset:53600
	ds_read_b128 v[186:189], v170 offset:57696
	ds_read_b128 v[190:193], v170 offset:61792
	ds_read_b128 v[194:197], v171 offset:352
	ds_read_b128 v[198:201], v171 offset:4448
	s_waitcnt lgkmcnt(6)
; #define LAS __attribute__((address_space(3)))
; DI void p0_mod_unit(const Params& p, int u, LAS unsigned char* ldsb) {
;     ...
;     for (int k = 0; k < 128; k += 4) {
;         const float w0 = wp[(size_t)(k + 0) * 3072], w1 = wp[(size_t)(k + 1) * 3072], w2 = wp[(size_t)(k + 2) * 3072], w3 = wp[(size_t)(k + 3) * 3072];
; #pragma unroll
;         for (int i = 0; i < 18; ++i) { const f32x4 s = *(const LAS f32x4*)(lds + i * 1024 + wid * 128 + k); acc[i] += s.x * w0 + s.y * w1 + s.z * w2 + s.w * w3; }
	v_pk_fma_f32 v[148:149], v[202:203], v[88:89], v[148:149]
	v_pk_fma_f32 v[148:149], v[204:205], v[90:91], v[148:149]
	v_pk_fma_f32 v[150:151], v[206:207], v[88:89], v[150:151]
	v_pk_fma_f32 v[150:151], v[208:209], v[90:91], v[150:151]
	v_pk_fma_f32 v[152:153], v[210:211], v[88:89], v[152:153]
	v_pk_fma_f32 v[152:153], v[212:213], v[90:91], v[152:153]
	v_pk_fma_f32 v[154:155], v[214:215], v[88:89], v[154:155]
	v_pk_fma_f32 v[154:155], v[216:217], v[90:91], v[154:155]
	v_pk_fma_f32 v[156:157], v[218:219], v[88:89], v[156:157]
	v_pk_fma_f32 v[156:157], v[220:221], v[90:91], v[156:157]
	v_pk_fma_f32 v[158:159], v[222:223], v[88:89], v[158:159]
	v_pk_fma_f32 v[158:159], v[224:225], v[90:91], v[158:159]
	ds_read_b128 v[202:205], v170 offset:368
	ds_read_b128 v[206:209], v170 offset:4464
	ds_read_b128 v[210:213], v170 offset:8560
	ds_read_b128 v[214:217], v170 offset:12656
	ds_read_b128 v[218:221], v170 offset:16752
	ds_read_b128 v[222:225], v170 offset:20848
	s_waitcnt lgkmcnt(6)
	v_pk_fma_f32 v[160:161], v[178:179], v[88:89], v[160:161]
	v_pk_fma_f32 v[160:161], v[180:181], v[90:91], v[160:161]
	v_pk_fma_f32 v[162:163], v[182:183], v[88:89], v[162:163]
	v_pk_fma_f32 v[162:163], v[184:185], v[90:91], v[162:163]
	v_pk_fma_f32 v[164:165], v[186:187], v[88:89], v[164:165]
	v_pk_fma_f32 v[164:165], v[188:189], v[90:91], v[164:165]
	v_pk_fma_f32 v[172:173], v[190:191], v[88:89], v[172:173]
	v_pk_fma_f32 v[172:173], v[192:193], v[90:91], v[172:173]
	v_pk_fma_f32 v[174:175], v[194:195], v[88:89], v[174:175]
	v_pk_fma_f32 v[174:175], v[196:197], v[90:91], v[174:175]
	v_pk_fma_f32 v[176:177], v[198:199], v[88:89], v[176:177]
	v_pk_fma_f32 v[176:177], v[200:201], v[90:91], v[176:177]
	ds_read_b128 v[178:181], v170 offset:24944
	ds_read_b128 v[182:185], v170 offset:29040
	ds_read_b128 v[186:189], v170 offset:33136
	ds_read_b128 v[190:193], v170 offset:37232
	ds_read_b128 v[194:197], v170 offset:41328
	ds_read_b128 v[198:201], v170 offset:45424
	s_waitcnt lgkmcnt(6)
	s_waitcnt vmcnt(32)
	v_pk_fma_f32 v[136:137], v[202:203], v[92:93], v[136:137]
	v_pk_fma_f32 v[136:137], v[204:205], v[94:95], v[136:137]
	v_pk_fma_f32 v[138:139], v[206:207], v[92:93], v[138:139]
	v_pk_fma_f32 v[138:139], v[208:209], v[94:95], v[138:139]
	v_pk_fma_f32 v[140:141], v[210:211], v[92:93], v[140:141]
	v_pk_fma_f32 v[140:141], v[212:213], v[94:95], v[140:141]
	v_pk_fma_f32 v[142:143], v[214:215], v[92:93], v[142:143]
	v_pk_fma_f32 v[142:143], v[216:217], v[94:95], v[142:143]
	v_pk_fma_f32 v[144:145], v[218:219], v[92:93], v[144:145]
	v_pk_fma_f32 v[144:145], v[220:221], v[94:95], v[144:145]
	v_pk_fma_f32 v[146:147], v[222:223], v[92:93], v[146:147]
	v_pk_fma_f32 v[146:147], v[224:225], v[94:95], v[146:147]
	ds_read_b128 v[202:205], v170 offset:49520
	ds_read_b128 v[206:209], v170 offset:53616
	ds_read_b128 v[210:213], v170 offset:57712
	ds_read_b128 v[214:217], v170 offset:61808
	ds_read_b128 v[218:221], v171 offset:368
	ds_read_b128 v[222:225], v171 offset:4464
	s_waitcnt lgkmcnt(6)
	v_pk_fma_f32 v[148:149], v[178:179], v[92:93], v[148:149]
	v_pk_fma_f32 v[148:149], v[180:181], v[94:95], v[148:149]
	v_pk_fma_f32 v[150:151], v[182:183], v[92:93], v[150:151]
	v_pk_fma_f32 v[150:151], v[184:185], v[94:95], v[150:151]
	v_pk_fma_f32 v[152:153], v[186:187], v[92:93], v[152:153]
	v_pk_fma_f32 v[152:153], v[188:189], v[94:95], v[152:153]
	v_pk_fma_f32 v[154:155], v[190:191], v[92:93], v[154:155]
	v_pk_fma_f32 v[154:155], v[192:193], v[94:95], v[154:155]
	v_pk_fma_f32 v[156:157], v[194:195], v[92:93], v[156:157]
	v_pk_fma_f32 v[156:157], v[196:197], v[94:95], v[156:157]
	v_pk_fma_f32 v[158:159], v[198:199], v[92:93], v[158:159]
	v_pk_fma_f32 v[158:159], v[200:201], v[94:95], v[158:159]
	ds_read_b128 v[178:181], v170 offset:384
	ds_read_b128 v[182:185], v170 offset:4480
	ds_read_b128 v[186:189], v170 offset:8576
	ds_read_b128 v[190:193], v170 offset:12672
	ds_read_b128 v[194:197], v170 offset:16768
	ds_read_b128 v[198:201], v170 offset:20864
	s_waitcnt lgkmcnt(6)
	v_pk_fma_f32 v[160:161], v[202:203], v[92:93], v[160:161]
	v_pk_fma_f32 v[160:161], v[204:205], v[94:95], v[160:161]
	v_pk_fma_f32 v[162:163], v[206:207], v[92:93], v[162:163]
	v_pk_fma_f32 v[162:163], v[208:209], v[94:95], v[162:163]
	v_pk_fma_f32 v[164:165], v[210:211], v[92:93], v[164:165]
	v_pk_fma_f32 v[164:165], v[212:213], v[94:95], v[164:165]
	v_pk_fma_f32 v[172:173], v[214:215], v[92:93], v[172:173]
	v_pk_fma_f32 v[172:173], v[216:217], v[94:95], v[172:173]
	v_pk_fma_f32 v[174:175], v[218:219], v[92:93], v[174:175]
	v_pk_fma_f32 v[174:175], v[220:221], v[94:95], v[174:175]
	v_pk_fma_f32 v[176:177], v[222:223], v[92:93], v[176:177]
	v_pk_fma_f32 v[176:177], v[224:225], v[94:95], v[176:177]
	ds_read_b128 v[202:205], v170 offset:24960
	ds_read_b128 v[206:209], v170 offset:29056
	ds_read_b128 v[210:213], v170 offset:33152
	ds_read_b128 v[214:217], v170 offset:37248
	ds_read_b128 v[218:221], v170 offset:41344
	ds_read_b128 v[222:225], v170 offset:45440
	s_waitcnt lgkmcnt(6)
	s_waitcnt vmcnt(28)
	v_pk_fma_f32 v[136:137], v[178:179], v[96:97], v[136:137]
	v_pk_fma_f32 v[136:137], v[180:181], v[98:99], v[136:137]
	v_pk_fma_f32 v[138:139], v[182:183], v[96:97], v[138:139]
	v_pk_fma_f32 v[138:139], v[184:185], v[98:99], v[138:139]
	v_pk_fma_f32 v[140:141], v[186:187], v[96:97], v[140:141]
	v_pk_fma_f32 v[140:141], v[188:189], v[98:99], v[140:141]
	v_pk_fma_f32 v[142:143], v[190:191], v[96:97], v[142:143]
	v_pk_fma_f32 v[142:143], v[192:193], v[98:99], v[142:143]
	v_pk_fma_f32 v[144:145], v[194:195], v[96:97], v[144:145]
	v_pk_fma_f32 v[144:145], v[196:197], v[98:99], v[144:145]
	v_pk_fma_f32 v[146:147], v[198:199], v[96:97], v[146:147]
	v_pk_fma_f32 v[146:147], v[200:201], v[98:99], v[146:147]
	ds_read_b128 v[178:181], v170 offset:49536
	ds_read_b128 v[182:185], v170 offset:53632
	ds_read_b128 v[186:189], v170 offset:57728
	ds_read_b128 v[190:193], v170 offset:61824
	ds_read_b128 v[194:197], v171 offset:384
	ds_read_b128 v[198:201], v171 offset:4480
	s_waitcnt lgkmcnt(6)
; #define LAS __attribute__((address_space(3)))
; DI void p0_mod_unit(const Params& p, int u, LAS unsigned char* ldsb) {
;     ...
;     for (int k = 0; k < 128; k += 4) {
;         const float w0 = wp[(size_t)(k + 0) * 3072], w1 = wp[(size_t)(k + 1) * 3072], w2 = wp[(size_t)(k + 2) * 3072], w3 = wp[(size_t)(k + 3) * 3072];
; #pragma unroll
;         for (int i = 0; i < 18; ++i) { const f32x4 s = *(const LAS f32x4*)(lds + i * 1024 + wid * 128 + k); acc[i] += s.x * w0 + s.y * w1 + s.z * w2 + s.w * w3; }
	v_pk_fma_f32 v[148:149], v[202:203], v[96:97], v[148:149]
	v_pk_fma_f32 v[148:149], v[204:205], v[98:99], v[148:149]
	v_pk_fma_f32 v[150:151], v[206:207], v[96:97], v[150:151]
	v_pk_fma_f32 v[150:151], v[208:209], v[98:99], v[150:151]
	v_pk_fma_f32 v[152:153], v[210:211], v[96:97], v[152:153]
	v_pk_fma_f32 v[152:153], v[212:213], v[98:99], v[152:153]
	v_pk_fma_f32 v[154:155], v[214:215], v[96:97], v[154:155]
	v_pk_fma_f32 v[154:155], v[216:217], v[98:99], v[154:155]
	v_pk_fma_f32 v[156:157], v[218:219], v[96:97], v[156:157]
	v_pk_fma_f32 v[156:157], v[220:221], v[98:99], v[156:157]
	v_pk_fma_f32 v[158:159], v[222:223], v[96:97], v[158:159]
	v_pk_fma_f32 v[158:159], v[224:225], v[98:99], v[158:159]
	ds_read_b128 v[202:205], v170 offset:400
	ds_read_b128 v[206:209], v170 offset:4496
	ds_read_b128 v[210:213], v170 offset:8592
	ds_read_b128 v[214:217], v170 offset:12688
	ds_read_b128 v[218:221], v170 offset:16784
	ds_read_b128 v[222:225], v170 offset:20880
	s_waitcnt lgkmcnt(6)
	v_pk_fma_f32 v[160:161], v[178:179], v[96:97], v[160:161]
	v_pk_fma_f32 v[160:161], v[180:181], v[98:99], v[160:161]
	v_pk_fma_f32 v[162:163], v[182:183], v[96:97], v[162:163]
	v_pk_fma_f32 v[162:163], v[184:185], v[98:99], v[162:163]
	v_pk_fma_f32 v[164:165], v[186:187], v[96:97], v[164:165]
	v_pk_fma_f32 v[164:165], v[188:189], v[98:99], v[164:165]
	v_pk_fma_f32 v[172:173], v[190:191], v[96:97], v[172:173]
	v_pk_fma_f32 v[172:173], v[192:193], v[98:99], v[172:173]
	v_pk_fma_f32 v[174:175], v[194:195], v[96:97], v[174:175]
	v_pk_fma_f32 v[174:175], v[196:197], v[98:99], v[174:175]
	v_pk_fma_f32 v[176:177], v[198:199], v[96:97], v[176:177]
	v_pk_fma_f32 v[176:177], v[200:201], v[98:99], v[176:177]
	ds_read_b128 v[178:181], v170 offset:24976
	ds_read_b128 v[182:185], v170 offset:29072
	ds_read_b128 v[186:189], v170 offset:33168
	ds_read_b128 v[190:193], v170 offset:37264
	ds_read_b128 v[194:197], v170 offset:41360
	ds_read_b128 v[198:201], v170 offset:45456
	s_waitcnt lgkmcnt(6)
	s_waitcnt vmcnt(24)
	v_pk_fma_f32 v[136:137], v[202:203], v[100:101], v[136:137]
	v_pk_fma_f32 v[136:137], v[204:205], v[102:103], v[136:137]
	v_pk_fma_f32 v[138:139], v[206:207], v[100:101], v[138:139]
	v_pk_fma_f32 v[138:139], v[208:209], v[102:103], v[138:139]
	v_pk_fma_f32 v[140:141], v[210:211], v[100:101], v[140:141]
	v_pk_fma_f32 v[140:141], v[212:213], v[102:103], v[140:141]
	v_pk_fma_f32 v[142:143], v[214:215], v[100:101], v[142:143]
	v_pk_fma_f32 v[142:143], v[216:217], v[102:103], v[142:143]
	v_pk_fma_f32 v[144:145], v[218:219], v[100:101], v[144:145]
	v_pk_fma_f32 v[144:145], v[220:221], v[102:103], v[144:145]
	v_pk_fma_f32 v[146:147], v[222:223], v[100:101], v[146:147]
	v_pk_fma_f32 v[146:147], v[224:225], v[102:103], v[146:147]
	ds_read_b128 v[202:205], v170 offset:49552
	ds_read_b128 v[206:209], v170 offset:53648
	ds_read_b128 v[210:213], v170 offset:57744
	ds_read_b128 v[214:217], v170 offset:61840
	ds_read_b128 v[218:221], v171 offset:400
	ds_read_b128 v[222:225], v171 offset:4496
	s_waitcnt lgkmcnt(6)
	v_pk_fma_f32 v[148:149], v[178:179], v[100:101], v[148:149]
	v_pk_fma_f32 v[148:149], v[180:181], v[102:103], v[148:149]
	v_pk_fma_f32 v[150:151], v[182:183], v[100:101], v[150:151]
	v_pk_fma_f32 v[150:151], v[184:185], v[102:103], v[150:151]
	v_pk_fma_f32 v[152:153], v[186:187], v[100:101], v[152:153]
	v_pk_fma_f32 v[152:153], v[188:189], v[102:103], v[152:153]
	v_pk_fma_f32 v[154:155], v[190:191], v[100:101], v[154:155]
	v_pk_fma_f32 v[154:155], v[192:193], v[102:103], v[154:155]
	v_pk_fma_f32 v[156:157], v[194:195], v[100:101], v[156:157]
	v_pk_fma_f32 v[156:157], v[196:197], v[102:103], v[156:157]
	v_pk_fma_f32 v[158:159], v[198:199], v[100:101], v[158:159]
	v_pk_fma_f32 v[158:159], v[200:201], v[102:103], v[158:159]
	ds_read_b128 v[178:181], v170 offset:416
	ds_read_b128 v[182:185], v170 offset:4512
	ds_read_b128 v[186:189], v170 offset:8608
	ds_read_b128 v[190:193], v170 offset:12704
	ds_read_b128 v[194:197], v170 offset:16800
	ds_read_b128 v[198:201], v170 offset:20896
	s_waitcnt lgkmcnt(6)
	v_pk_fma_f32 v[160:161], v[202:203], v[100:101], v[160:161]
	v_pk_fma_f32 v[160:161], v[204:205], v[102:103], v[160:161]
	v_pk_fma_f32 v[162:163], v[206:207], v[100:101], v[162:163]
	v_pk_fma_f32 v[162:163], v[208:209], v[102:103], v[162:163]
	v_pk_fma_f32 v[164:165], v[210:211], v[100:101], v[164:165]
	v_pk_fma_f32 v[164:165], v[212:213], v[102:103], v[164:165]
	v_pk_fma_f32 v[172:173], v[214:215], v[100:101], v[172:173]
	v_pk_fma_f32 v[172:173], v[216:217], v[102:103], v[172:173]
	v_pk_fma_f32 v[174:175], v[218:219], v[100:101], v[174:175]
	v_pk_fma_f32 v[174:175], v[220:221], v[102:103], v[174:175]
	v_pk_fma_f32 v[176:177], v[222:223], v[100:101], v[176:177]
	v_pk_fma_f32 v[176:177], v[224:225], v[102:103], v[176:177]
	ds_read_b128 v[202:205], v170 offset:24992
	ds_read_b128 v[206:209], v170 offset:29088
	ds_read_b128 v[210:213], v170 offset:33184
	ds_read_b128 v[214:217], v170 offset:37280
	ds_read_b128 v[218:221], v170 offset:41376
	ds_read_b128 v[222:225], v170 offset:45472
	s_waitcnt lgkmcnt(6)
	s_waitcnt vmcnt(20)
	v_pk_fma_f32 v[136:137], v[178:179], v[104:105], v[136:137]
	v_pk_fma_f32 v[136:137], v[180:181], v[106:107], v[136:137]
	v_pk_fma_f32 v[138:139], v[182:183], v[104:105], v[138:139]
	v_pk_fma_f32 v[138:139], v[184:185], v[106:107], v[138:139]
	v_pk_fma_f32 v[140:141], v[186:187], v[104:105], v[140:141]
	v_pk_fma_f32 v[140:141], v[188:189], v[106:107], v[140:141]
	v_pk_fma_f32 v[142:143], v[190:191], v[104:105], v[142:143]
	v_pk_fma_f32 v[142:143], v[192:193], v[106:107], v[142:143]
	v_pk_fma_f32 v[144:145], v[194:195], v[104:105], v[144:145]
	v_pk_fma_f32 v[144:145], v[196:197], v[106:107], v[144:145]
	v_pk_fma_f32 v[146:147], v[198:199], v[104:105], v[146:147]
	v_pk_fma_f32 v[146:147], v[200:201], v[106:107], v[146:147]
	ds_read_b128 v[178:181], v170 offset:49568
	ds_read_b128 v[182:185], v170 offset:53664
	ds_read_b128 v[186:189], v170 offset:57760
	ds_read_b128 v[190:193], v170 offset:61856
	ds_read_b128 v[194:197], v171 offset:416
	ds_read_b128 v[198:201], v171 offset:4512
	s_waitcnt lgkmcnt(6)
; #define LAS __attribute__((address_space(3)))
; DI void p0_mod_unit(const Params& p, int u, LAS unsigned char* ldsb) {
;     ...
;     for (int k = 0; k < 128; k += 4) {
;         const float w0 = wp[(size_t)(k + 0) * 3072], w1 = wp[(size_t)(k + 1) * 3072], w2 = wp[(size_t)(k + 2) * 3072], w3 = wp[(size_t)(k + 3) * 3072];
; #pragma unroll
;         for (int i = 0; i < 18; ++i) { const f32x4 s = *(const LAS f32x4*)(lds + i * 1024 + wid * 128 + k); acc[i] += s.x * w0 + s.y * w1 + s.z * w2 + s.w * w3; }
	v_pk_fma_f32 v[148:149], v[202:203], v[104:105], v[148:149]
	v_pk_fma_f32 v[148:149], v[204:205], v[106:107], v[148:149]
	v_pk_fma_f32 v[150:151], v[206:207], v[104:105], v[150:151]
	v_pk_fma_f32 v[150:151], v[208:209], v[106:107], v[150:151]
	v_pk_fma_f32 v[152:153], v[210:211], v[104:105], v[152:153]
	v_pk_fma_f32 v[152:153], v[212:213], v[106:107], v[152:153]
	v_pk_fma_f32 v[154:155], v[214:215], v[104:105], v[154:155]
	v_pk_fma_f32 v[154:155], v[216:217], v[106:107], v[154:155]
	v_pk_fma_f32 v[156:157], v[218:219], v[104:105], v[156:157]
	v_pk_fma_f32 v[156:157], v[220:221], v[106:107], v[156:157]
	v_pk_fma_f32 v[158:159], v[222:223], v[104:105], v[158:159]
	v_pk_fma_f32 v[158:159], v[224:225], v[106:107], v[158:159]
	ds_read_b128 v[202:205], v170 offset:432
	ds_read_b128 v[206:209], v170 offset:4528
	ds_read_b128 v[210:213], v170 offset:8624
	ds_read_b128 v[214:217], v170 offset:12720
	ds_read_b128 v[218:221], v170 offset:16816
	ds_read_b128 v[222:225], v170 offset:20912
	s_waitcnt lgkmcnt(6)
	v_pk_fma_f32 v[160:161], v[178:179], v[104:105], v[160:161]
	v_pk_fma_f32 v[160:161], v[180:181], v[106:107], v[160:161]
	v_pk_fma_f32 v[162:163], v[182:183], v[104:105], v[162:163]
	v_pk_fma_f32 v[162:163], v[184:185], v[106:107], v[162:163]
	v_pk_fma_f32 v[164:165], v[186:187], v[104:105], v[164:165]
	v_pk_fma_f32 v[164:165], v[188:189], v[106:107], v[164:165]
	v_pk_fma_f32 v[172:173], v[190:191], v[104:105], v[172:173]
	v_pk_fma_f32 v[172:173], v[192:193], v[106:107], v[172:173]
	v_pk_fma_f32 v[174:175], v[194:195], v[104:105], v[174:175]
	v_pk_fma_f32 v[174:175], v[196:197], v[106:107], v[174:175]
	v_pk_fma_f32 v[176:177], v[198:199], v[104:105], v[176:177]
	v_pk_fma_f32 v[176:177], v[200:201], v[106:107], v[176:177]
	ds_read_b128 v[178:181], v170 offset:25008
	ds_read_b128 v[182:185], v170 offset:29104
	ds_read_b128 v[186:189], v170 offset:33200
	ds_read_b128 v[190:193], v170 offset:37296
	ds_read_b128 v[194:197], v170 offset:41392
	ds_read_b128 v[198:201], v170 offset:45488
	s_waitcnt lgkmcnt(6)
	s_waitcnt vmcnt(16)
	v_pk_fma_f32 v[136:137], v[202:203], v[108:109], v[136:137]
	v_pk_fma_f32 v[136:137], v[204:205], v[110:111], v[136:137]
	v_pk_fma_f32 v[138:139], v[206:207], v[108:109], v[138:139]
	v_pk_fma_f32 v[138:139], v[208:209], v[110:111], v[138:139]
	v_pk_fma_f32 v[140:141], v[210:211], v[108:109], v[140:141]
	v_pk_fma_f32 v[140:141], v[212:213], v[110:111], v[140:141]
	v_pk_fma_f32 v[142:143], v[214:215], v[108:109], v[142:143]
	v_pk_fma_f32 v[142:143], v[216:217], v[110:111], v[142:143]
	v_pk_fma_f32 v[144:145], v[218:219], v[108:109], v[144:145]
	v_pk_fma_f32 v[144:145], v[220:221], v[110:111], v[144:145]
	v_pk_fma_f32 v[146:147], v[222:223], v[108:109], v[146:147]
	v_pk_fma_f32 v[146:147], v[224:225], v[110:111], v[146:147]
	ds_read_b128 v[202:205], v170 offset:49584
	ds_read_b128 v[206:209], v170 offset:53680
	ds_read_b128 v[210:213], v170 offset:57776
	ds_read_b128 v[214:217], v170 offset:61872
	ds_read_b128 v[218:221], v171 offset:432
	ds_read_b128 v[222:225], v171 offset:4528
	s_waitcnt lgkmcnt(6)
	v_pk_fma_f32 v[148:149], v[178:179], v[108:109], v[148:149]
	v_pk_fma_f32 v[148:149], v[180:181], v[110:111], v[148:149]
	v_pk_fma_f32 v[150:151], v[182:183], v[108:109], v[150:151]
	v_pk_fma_f32 v[150:151], v[184:185], v[110:111], v[150:151]
	v_pk_fma_f32 v[152:153], v[186:187], v[108:109], v[152:153]
	v_pk_fma_f32 v[152:153], v[188:189], v[110:111], v[152:153]
	v_pk_fma_f32 v[154:155], v[190:191], v[108:109], v[154:155]
	v_pk_fma_f32 v[154:155], v[192:193], v[110:111], v[154:155]
	v_pk_fma_f32 v[156:157], v[194:195], v[108:109], v[156:157]
	v_pk_fma_f32 v[156:157], v[196:197], v[110:111], v[156:157]
	v_pk_fma_f32 v[158:159], v[198:199], v[108:109], v[158:159]
	v_pk_fma_f32 v[158:159], v[200:201], v[110:111], v[158:159]
	ds_read_b128 v[178:181], v170 offset:448
	ds_read_b128 v[182:185], v170 offset:4544
	ds_read_b128 v[186:189], v170 offset:8640
	ds_read_b128 v[190:193], v170 offset:12736
	ds_read_b128 v[194:197], v170 offset:16832
	ds_read_b128 v[198:201], v170 offset:20928
	s_waitcnt lgkmcnt(6)
	v_pk_fma_f32 v[160:161], v[202:203], v[108:109], v[160:161]
	v_pk_fma_f32 v[160:161], v[204:205], v[110:111], v[160:161]
	v_pk_fma_f32 v[162:163], v[206:207], v[108:109], v[162:163]
	v_pk_fma_f32 v[162:163], v[208:209], v[110:111], v[162:163]
	v_pk_fma_f32 v[164:165], v[210:211], v[108:109], v[164:165]
	v_pk_fma_f32 v[164:165], v[212:213], v[110:111], v[164:165]
	v_pk_fma_f32 v[172:173], v[214:215], v[108:109], v[172:173]
	v_pk_fma_f32 v[172:173], v[216:217], v[110:111], v[172:173]
	v_pk_fma_f32 v[174:175], v[218:219], v[108:109], v[174:175]
	v_pk_fma_f32 v[174:175], v[220:221], v[110:111], v[174:175]
	v_pk_fma_f32 v[176:177], v[222:223], v[108:109], v[176:177]
	v_pk_fma_f32 v[176:177], v[224:225], v[110:111], v[176:177]
	ds_read_b128 v[202:205], v170 offset:25024
	ds_read_b128 v[206:209], v170 offset:29120
	ds_read_b128 v[210:213], v170 offset:33216
	ds_read_b128 v[214:217], v170 offset:37312
	ds_read_b128 v[218:221], v170 offset:41408
	ds_read_b128 v[222:225], v170 offset:45504
	s_waitcnt lgkmcnt(6)
	s_waitcnt vmcnt(12)
	v_pk_fma_f32 v[136:137], v[178:179], v[112:113], v[136:137]
	v_pk_fma_f32 v[136:137], v[180:181], v[114:115], v[136:137]
	v_pk_fma_f32 v[138:139], v[182:183], v[112:113], v[138:139]
	v_pk_fma_f32 v[138:139], v[184:185], v[114:115], v[138:139]
	v_pk_fma_f32 v[140:141], v[186:187], v[112:113], v[140:141]
	v_pk_fma_f32 v[140:141], v[188:189], v[114:115], v[140:141]
	v_pk_fma_f32 v[142:143], v[190:191], v[112:113], v[142:143]
	v_pk_fma_f32 v[142:143], v[192:193], v[114:115], v[142:143]
	v_pk_fma_f32 v[144:145], v[194:195], v[112:113], v[144:145]
	v_pk_fma_f32 v[144:145], v[196:197], v[114:115], v[144:145]
	v_pk_fma_f32 v[146:147], v[198:199], v[112:113], v[146:147]
	v_pk_fma_f32 v[146:147], v[200:201], v[114:115], v[146:147]
	ds_read_b128 v[178:181], v170 offset:49600
	ds_read_b128 v[182:185], v170 offset:53696
	ds_read_b128 v[186:189], v170 offset:57792
	ds_read_b128 v[190:193], v170 offset:61888
	ds_read_b128 v[194:197], v171 offset:448
	ds_read_b128 v[198:201], v171 offset:4544
	s_waitcnt lgkmcnt(6)
; #define LAS __attribute__((address_space(3)))
; DI void p0_mod_unit(const Params& p, int u, LAS unsigned char* ldsb) {
;     ...
;     for (int k = 0; k < 128; k += 4) {
;         const float w0 = wp[(size_t)(k + 0) * 3072], w1 = wp[(size_t)(k + 1) * 3072], w2 = wp[(size_t)(k + 2) * 3072], w3 = wp[(size_t)(k + 3) * 3072];
; #pragma unroll
;         for (int i = 0; i < 18; ++i) { const f32x4 s = *(const LAS f32x4*)(lds + i * 1024 + wid * 128 + k); acc[i] += s.x * w0 + s.y * w1 + s.z * w2 + s.w * w3; }
	v_pk_fma_f32 v[148:149], v[202:203], v[112:113], v[148:149]
	v_pk_fma_f32 v[148:149], v[204:205], v[114:115], v[148:149]
	v_pk_fma_f32 v[150:151], v[206:207], v[112:113], v[150:151]
	v_pk_fma_f32 v[150:151], v[208:209], v[114:115], v[150:151]
	v_pk_fma_f32 v[152:153], v[210:211], v[112:113], v[152:153]
	v_pk_fma_f32 v[152:153], v[212:213], v[114:115], v[152:153]
	v_pk_fma_f32 v[154:155], v[214:215], v[112:113], v[154:155]
	v_pk_fma_f32 v[154:155], v[216:217], v[114:115], v[154:155]
	v_pk_fma_f32 v[156:157], v[218:219], v[112:113], v[156:157]
	v_pk_fma_f32 v[156:157], v[220:221], v[114:115], v[156:157]
	v_pk_fma_f32 v[158:159], v[222:223], v[112:113], v[158:159]
	v_pk_fma_f32 v[158:159], v[224:225], v[114:115], v[158:159]
	ds_read_b128 v[202:205], v170 offset:464
	ds_read_b128 v[206:209], v170 offset:4560
	ds_read_b128 v[210:213], v170 offset:8656
	ds_read_b128 v[214:217], v170 offset:12752
	ds_read_b128 v[218:221], v170 offset:16848
	ds_read_b128 v[222:225], v170 offset:20944
	s_waitcnt lgkmcnt(6)
	v_pk_fma_f32 v[160:161], v[178:179], v[112:113], v[160:161]
	v_pk_fma_f32 v[160:161], v[180:181], v[114:115], v[160:161]
	v_pk_fma_f32 v[162:163], v[182:183], v[112:113], v[162:163]
	v_pk_fma_f32 v[162:163], v[184:185], v[114:115], v[162:163]
	v_pk_fma_f32 v[164:165], v[186:187], v[112:113], v[164:165]
	v_pk_fma_f32 v[164:165], v[188:189], v[114:115], v[164:165]
	v_pk_fma_f32 v[172:173], v[190:191], v[112:113], v[172:173]
	v_pk_fma_f32 v[172:173], v[192:193], v[114:115], v[172:173]
	v_pk_fma_f32 v[174:175], v[194:195], v[112:113], v[174:175]
	v_pk_fma_f32 v[174:175], v[196:197], v[114:115], v[174:175]
	v_pk_fma_f32 v[176:177], v[198:199], v[112:113], v[176:177]
	v_pk_fma_f32 v[176:177], v[200:201], v[114:115], v[176:177]
	ds_read_b128 v[178:181], v170 offset:25040
	ds_read_b128 v[182:185], v170 offset:29136
	ds_read_b128 v[186:189], v170 offset:33232
	ds_read_b128 v[190:193], v170 offset:37328
	ds_read_b128 v[194:197], v170 offset:41424
	ds_read_b128 v[198:201], v170 offset:45520
	s_waitcnt lgkmcnt(6)
	s_waitcnt vmcnt(8)
	v_pk_fma_f32 v[136:137], v[202:203], v[116:117], v[136:137]
	v_pk_fma_f32 v[136:137], v[204:205], v[118:119], v[136:137]
	v_pk_fma_f32 v[138:139], v[206:207], v[116:117], v[138:139]
	v_pk_fma_f32 v[138:139], v[208:209], v[118:119], v[138:139]
	v_pk_fma_f32 v[140:141], v[210:211], v[116:117], v[140:141]
	v_pk_fma_f32 v[140:141], v[212:213], v[118:119], v[140:141]
	v_pk_fma_f32 v[142:143], v[214:215], v[116:117], v[142:143]
	v_pk_fma_f32 v[142:143], v[216:217], v[118:119], v[142:143]
	v_pk_fma_f32 v[144:145], v[218:219], v[116:117], v[144:145]
	v_pk_fma_f32 v[144:145], v[220:221], v[118:119], v[144:145]
	v_pk_fma_f32 v[146:147], v[222:223], v[116:117], v[146:147]
	v_pk_fma_f32 v[146:147], v[224:225], v[118:119], v[146:147]
	ds_read_b128 v[202:205], v170 offset:49616
	ds_read_b128 v[206:209], v170 offset:53712
	ds_read_b128 v[210:213], v170 offset:57808
	ds_read_b128 v[214:217], v170 offset:61904
	ds_read_b128 v[218:221], v171 offset:464
	ds_read_b128 v[222:225], v171 offset:4560
	s_waitcnt lgkmcnt(6)
	v_pk_fma_f32 v[148:149], v[178:179], v[116:117], v[148:149]
	v_pk_fma_f32 v[148:149], v[180:181], v[118:119], v[148:149]
	v_pk_fma_f32 v[150:151], v[182:183], v[116:117], v[150:151]
	v_pk_fma_f32 v[150:151], v[184:185], v[118:119], v[150:151]
	v_pk_fma_f32 v[152:153], v[186:187], v[116:117], v[152:153]
	v_pk_fma_f32 v[152:153], v[188:189], v[118:119], v[152:153]
	v_pk_fma_f32 v[154:155], v[190:191], v[116:117], v[154:155]
	v_pk_fma_f32 v[154:155], v[192:193], v[118:119], v[154:155]
	v_pk_fma_f32 v[156:157], v[194:195], v[116:117], v[156:157]
	v_pk_fma_f32 v[156:157], v[196:197], v[118:119], v[156:157]
	v_pk_fma_f32 v[158:159], v[198:199], v[116:117], v[158:159]
	v_pk_fma_f32 v[158:159], v[200:201], v[118:119], v[158:159]
	ds_read_b128 v[178:181], v170 offset:480
	ds_read_b128 v[182:185], v170 offset:4576
	ds_read_b128 v[186:189], v170 offset:8672
	ds_read_b128 v[190:193], v170 offset:12768
	ds_read_b128 v[194:197], v170 offset:16864
	ds_read_b128 v[198:201], v170 offset:20960
	s_waitcnt lgkmcnt(6)
	v_pk_fma_f32 v[160:161], v[202:203], v[116:117], v[160:161]
	v_pk_fma_f32 v[160:161], v[204:205], v[118:119], v[160:161]
	v_pk_fma_f32 v[162:163], v[206:207], v[116:117], v[162:163]
	v_pk_fma_f32 v[162:163], v[208:209], v[118:119], v[162:163]
	v_pk_fma_f32 v[164:165], v[210:211], v[116:117], v[164:165]
	v_pk_fma_f32 v[164:165], v[212:213], v[118:119], v[164:165]
	v_pk_fma_f32 v[172:173], v[214:215], v[116:117], v[172:173]
	v_pk_fma_f32 v[172:173], v[216:217], v[118:119], v[172:173]
	v_pk_fma_f32 v[174:175], v[218:219], v[116:117], v[174:175]
	v_pk_fma_f32 v[174:175], v[220:221], v[118:119], v[174:175]
	v_pk_fma_f32 v[176:177], v[222:223], v[116:117], v[176:177]
	v_pk_fma_f32 v[176:177], v[224:225], v[118:119], v[176:177]
	ds_read_b128 v[202:205], v170 offset:25056
	ds_read_b128 v[206:209], v170 offset:29152
	ds_read_b128 v[210:213], v170 offset:33248
	ds_read_b128 v[214:217], v170 offset:37344
	ds_read_b128 v[218:221], v170 offset:41440
	ds_read_b128 v[222:225], v170 offset:45536
	s_waitcnt lgkmcnt(6)
	s_waitcnt vmcnt(4)
	v_pk_fma_f32 v[136:137], v[178:179], v[120:121], v[136:137]
	v_pk_fma_f32 v[136:137], v[180:181], v[122:123], v[136:137]
	v_pk_fma_f32 v[138:139], v[182:183], v[120:121], v[138:139]
	v_pk_fma_f32 v[138:139], v[184:185], v[122:123], v[138:139]
	v_pk_fma_f32 v[140:141], v[186:187], v[120:121], v[140:141]
	v_pk_fma_f32 v[140:141], v[188:189], v[122:123], v[140:141]
	v_pk_fma_f32 v[142:143], v[190:191], v[120:121], v[142:143]
	v_pk_fma_f32 v[142:143], v[192:193], v[122:123], v[142:143]
	v_pk_fma_f32 v[144:145], v[194:195], v[120:121], v[144:145]
	v_pk_fma_f32 v[144:145], v[196:197], v[122:123], v[144:145]
	v_pk_fma_f32 v[146:147], v[198:199], v[120:121], v[146:147]
	v_pk_fma_f32 v[146:147], v[200:201], v[122:123], v[146:147]
	ds_read_b128 v[178:181], v170 offset:49632
	ds_read_b128 v[182:185], v170 offset:53728
	ds_read_b128 v[186:189], v170 offset:57824
	ds_read_b128 v[190:193], v170 offset:61920
	ds_read_b128 v[194:197], v171 offset:480
	ds_read_b128 v[198:201], v171 offset:4576
	s_waitcnt lgkmcnt(6)
; #define LAS __attribute__((address_space(3)))
; DI void p0_mod_unit(const Params& p, int u, LAS unsigned char* ldsb) {
;     ...
;     for (int k = 0; k < 128; k += 4) {
;         const float w0 = wp[(size_t)(k + 0) * 3072], w1 = wp[(size_t)(k + 1) * 3072], w2 = wp[(size_t)(k + 2) * 3072], w3 = wp[(size_t)(k + 3) * 3072];
; #pragma unroll
;         for (int i = 0; i < 18; ++i) { const f32x4 s = *(const LAS f32x4*)(lds + i * 1024 + wid * 128 + k); acc[i] += s.x * w0 + s.y * w1 + s.z * w2 + s.w * w3; }
;     }
;     __syncthreads();
; #pragma unroll
;     for (int i = 0; i < 18; ++i) lds[(wid * 18 + i) * 64 + lane] = acc[i];
;     __syncthreads();
	v_pk_fma_f32 v[148:149], v[202:203], v[120:121], v[148:149]
	v_pk_fma_f32 v[148:149], v[204:205], v[122:123], v[148:149]
	v_pk_fma_f32 v[150:151], v[206:207], v[120:121], v[150:151]
	v_pk_fma_f32 v[150:151], v[208:209], v[122:123], v[150:151]
	v_pk_fma_f32 v[152:153], v[210:211], v[120:121], v[152:153]
	v_pk_fma_f32 v[152:153], v[212:213], v[122:123], v[152:153]
	v_pk_fma_f32 v[154:155], v[214:215], v[120:121], v[154:155]
	v_pk_fma_f32 v[154:155], v[216:217], v[122:123], v[154:155]
	v_pk_fma_f32 v[156:157], v[218:219], v[120:121], v[156:157]
	v_pk_fma_f32 v[156:157], v[220:221], v[122:123], v[156:157]
	v_pk_fma_f32 v[158:159], v[222:223], v[120:121], v[158:159]
	v_pk_fma_f32 v[158:159], v[224:225], v[122:123], v[158:159]
	ds_read_b128 v[202:205], v170 offset:496
	ds_read_b128 v[206:209], v170 offset:4592
	ds_read_b128 v[210:213], v170 offset:8688
	ds_read_b128 v[214:217], v170 offset:12784
	ds_read_b128 v[218:221], v170 offset:16880
	ds_read_b128 v[222:225], v170 offset:20976
	s_waitcnt lgkmcnt(6)
	v_pk_fma_f32 v[160:161], v[178:179], v[120:121], v[160:161]
	v_pk_fma_f32 v[160:161], v[180:181], v[122:123], v[160:161]
	v_pk_fma_f32 v[162:163], v[182:183], v[120:121], v[162:163]
	v_pk_fma_f32 v[162:163], v[184:185], v[122:123], v[162:163]
	v_pk_fma_f32 v[164:165], v[186:187], v[120:121], v[164:165]
	v_pk_fma_f32 v[164:165], v[188:189], v[122:123], v[164:165]
	v_pk_fma_f32 v[172:173], v[190:191], v[120:121], v[172:173]
	v_pk_fma_f32 v[172:173], v[192:193], v[122:123], v[172:173]
	v_pk_fma_f32 v[174:175], v[194:195], v[120:121], v[174:175]
	v_pk_fma_f32 v[174:175], v[196:197], v[122:123], v[174:175]
	v_pk_fma_f32 v[176:177], v[198:199], v[120:121], v[176:177]
	v_pk_fma_f32 v[176:177], v[200:201], v[122:123], v[176:177]
	ds_read_b128 v[178:181], v170 offset:25072
	ds_read_b128 v[182:185], v170 offset:29168
	ds_read_b128 v[186:189], v170 offset:33264
	ds_read_b128 v[190:193], v170 offset:37360
	ds_read_b128 v[194:197], v170 offset:41456
	ds_read_b128 v[198:201], v170 offset:45552
	s_waitcnt lgkmcnt(6)
	s_waitcnt vmcnt(0)
	v_pk_fma_f32 v[136:137], v[202:203], v[124:125], v[136:137]
	v_pk_fma_f32 v[136:137], v[204:205], v[126:127], v[136:137]
	v_pk_fma_f32 v[138:139], v[206:207], v[124:125], v[138:139]
	v_pk_fma_f32 v[138:139], v[208:209], v[126:127], v[138:139]
	v_pk_fma_f32 v[140:141], v[210:211], v[124:125], v[140:141]
	v_pk_fma_f32 v[140:141], v[212:213], v[126:127], v[140:141]
	v_pk_fma_f32 v[142:143], v[214:215], v[124:125], v[142:143]
	v_pk_fma_f32 v[142:143], v[216:217], v[126:127], v[142:143]
	v_pk_fma_f32 v[144:145], v[218:219], v[124:125], v[144:145]
	v_pk_fma_f32 v[144:145], v[220:221], v[126:127], v[144:145]
	v_pk_fma_f32 v[146:147], v[222:223], v[124:125], v[146:147]
	v_pk_fma_f32 v[146:147], v[224:225], v[126:127], v[146:147]
	ds_read_b128 v[202:205], v170 offset:49648
	ds_read_b128 v[206:209], v170 offset:53744
	ds_read_b128 v[210:213], v170 offset:57840
	ds_read_b128 v[214:217], v170 offset:61936
	ds_read_b128 v[218:221], v171 offset:496
	ds_read_b128 v[222:225], v171 offset:4592
	s_waitcnt lgkmcnt(6)
	v_pk_fma_f32 v[148:149], v[178:179], v[124:125], v[148:149]
	v_pk_fma_f32 v[148:149], v[180:181], v[126:127], v[148:149]
	v_pk_fma_f32 v[150:151], v[182:183], v[124:125], v[150:151]
	v_pk_fma_f32 v[150:151], v[184:185], v[126:127], v[150:151]
	v_pk_fma_f32 v[152:153], v[186:187], v[124:125], v[152:153]
	v_pk_fma_f32 v[152:153], v[188:189], v[126:127], v[152:153]
	v_pk_fma_f32 v[154:155], v[190:191], v[124:125], v[154:155]
	v_pk_fma_f32 v[154:155], v[192:193], v[126:127], v[154:155]
	v_pk_fma_f32 v[156:157], v[194:195], v[124:125], v[156:157]
	v_pk_fma_f32 v[156:157], v[196:197], v[126:127], v[156:157]
	v_pk_fma_f32 v[158:159], v[198:199], v[124:125], v[158:159]
	v_pk_fma_f32 v[158:159], v[200:201], v[126:127], v[158:159]
	s_waitcnt lgkmcnt(0)
	v_pk_fma_f32 v[160:161], v[202:203], v[124:125], v[160:161]
	v_pk_fma_f32 v[160:161], v[204:205], v[126:127], v[160:161]
	v_pk_fma_f32 v[162:163], v[206:207], v[124:125], v[162:163]
	v_pk_fma_f32 v[162:163], v[208:209], v[126:127], v[162:163]
	v_pk_fma_f32 v[164:165], v[210:211], v[124:125], v[164:165]
	v_pk_fma_f32 v[164:165], v[212:213], v[126:127], v[164:165]
	v_pk_fma_f32 v[172:173], v[214:215], v[124:125], v[172:173]
	v_pk_fma_f32 v[172:173], v[216:217], v[126:127], v[172:173]
	v_pk_fma_f32 v[174:175], v[218:219], v[124:125], v[174:175]
	v_pk_fma_f32 v[174:175], v[220:221], v[126:127], v[174:175]
	v_pk_fma_f32 v[176:177], v[222:223], v[124:125], v[176:177]
	v_pk_fma_f32 v[176:177], v[224:225], v[126:127], v[176:177]
	v_add_f32_e32 v136, v136, v137
	v_add_f32_e32 v137, v138, v139
	v_add_f32_e32 v138, v140, v141
	v_add_f32_e32 v139, v142, v143
	v_add_f32_e32 v140, v144, v145
	v_add_f32_e32 v141, v146, v147
	v_add_f32_e32 v142, v148, v149
	v_add_f32_e32 v143, v150, v151
	v_add_f32_e32 v144, v152, v153
	v_add_f32_e32 v145, v154, v155
	v_add_f32_e32 v146, v156, v157
	v_add_f32_e32 v147, v158, v159
	v_add_f32_e32 v148, v160, v161
	v_add_f32_e32 v149, v162, v163
	v_add_f32_e32 v150, v164, v165
	v_add_f32_e32 v151, v172, v173
	v_add_f32_e32 v132, v174, v175
	v_add_f32_e32 v133, v176, v177
	v_lshl_add_u32 v0, v169, 2, 0
	v_mad_u64_u32 v[2:3], s[8:9], v168, s35, v[0:1]
	v_cmp_gt_i32_e32 vcc, s84, v167
	s_barrier
	ds_write2st64_b32 v2, v136, v137 offset1:1
	ds_write2st64_b32 v2, v138, v139 offset0:2 offset1:3
	ds_write2st64_b32 v2, v140, v141 offset0:4 offset1:5
	ds_write2st64_b32 v2, v142, v143 offset0:6 offset1:7
	ds_write2st64_b32 v2, v144, v145 offset0:8 offset1:9
	ds_write2st64_b32 v2, v146, v147 offset0:10 offset1:11
	ds_write2st64_b32 v2, v148, v149 offset0:12 offset1:13
	ds_write2st64_b32 v2, v150, v151 offset0:14 offset1:15
	ds_write2st64_b32 v2, v132, v133 offset0:16 offset1:17
	s_waitcnt lgkmcnt(0)
	s_barrier
	s_and_saveexec_b64 s[8:9], vcc
	s_cbranch_execz .LBB0_19
	s_and_b64 s[6:7], s[6:7], exec
	s_cselect_b32 s7, s59, s41
	s_cselect_b32 s6, s58, s40
	s_mul_i32 s87, s87, 36
	s_add_i32 s88, s88, s87
	v_lshl_add_u64 v[2:3], s[6:7], 0, v[130:131]
	v_lshl_add_u64 v[4:5], s[26:27], 0, v[130:131]
	s_mov_b64 s[6:7], 0

; #define LAS __attribute__((address_space(3)))
; DI int ltid() { int t = threadIdx.x; asm volatile("" : "+v"(t)); return t; }
; DI void phase3(const Params& p, LAS unsigned char* lds) {
;     const int tid = ltid(), wid = tid >> 6, lane = tid & 63, G = gridDim.x;
;     const int gw = blockIdx.x * NWAVES + wid, NGW = G * NWAVES;
;     for (int it = blockIdx.x; it < 256; it += G) decode_pair(p, (LAS float*)lds, it, wid, lane);
;     LAS unsigned char* wl = lds + wid * 10240;
;     if (G == 256) {
;         const int x = blockIdx.x & 7, lw = (blockIdx.x >> 3) * NWAVES + wid;
;         (void)lw; const int lb = blockIdx.x >> 3;
;         for (int k2 = 0; k2 < 4; ++k2) attn_block(p, lds, x * 8 + 2 * k2 + (lb >> 4), lb & 15, wid, lane);
.LBB0_299:
	s_or_b64 exec, exec, s[0:1]
	s_lshr_b32 s0, s2, 3
	s_mul_i32 s1, s0, 0x3334
	s_lshr_b32 s1, s1, 16
	s_mul_i32 s1, s1, 5
	s_sub_i32 s0, s0, s1
	s_nop 0
	v_writelane_b32 v254, s0, 0
	v_writelane_b32 v254, 0, 1
	v_writelane_b32 v254, 0, 2
	v_writelane_b32 v254, s78, 3
	v_writelane_b32 v254, s79, 4
	v_writelane_b32 v254, s80, 5
	v_writelane_b32 v254, s81, 6
.Lp3_reentry:
	v_mov_b32_e32 v177, v226
	s_waitcnt lgkmcnt(0)
	s_barrier
	v_cndmask_b32_e64 v0, 0, 1, s[6:7]
	v_and_b32_e32 v129, 63, v177
	v_ashrrev_i32_e32 v227, 6, v177
	v_cmp_ne_u32_e64 s[4:5], 1, v0
	s_andn2_b64 vcc, exec, s[6:7]
	v_bfe_u32 v157, v177, 6, 2
	v_lshrrev_b32_e32 v159, 4, v129
	v_cmp_gt_u32_e64 s[6:7], 16, v129
	s_cbranch_vccnz .LBB0_328
	v_readlane_b32 s0, v254, 1
	v_readlane_b32 vcc_lo, v254, 0
	s_nop 3
	s_cmp_lg_u32 s0, 0
	s_cbranch_scc1 .Lp3_do_d
	s_cmp_lg_u32 vcc_lo, 0
	s_cbranch_scc1 .LBB0_328
	v_writelane_b32 v254, 1, 1

; #define LAS __attribute__((address_space(3)))
; DI void decode_pair(const Params& p, LAS float* L  , int pairidx, int wid, int lane) {
;     ...
;     for (int i = 0; i < 2; ++i) {
;         const int e = kq + 4 * (lane + 64 * i);
;         sc[i] = -INFINITY;
;         if (e < 387) {
;             const int pi = e / 129, j = e - pi * 129, d = 1 << (2 * pi), idx = 2048 - j * d;
;             const float* kr = (idx == 2048) ? knew : ck + ((size_t)(b * 2048 + idx) * 16 + h) * 64;
;             float dot = 0.f;
; #pragma unroll
;             for (int dd = 0; dd < 64; dd += 4) { const f32x4 kv = __builtin_nontemporal_load((const f32x4*)(kr + dd)); const f32x4 qv = *(const LAS f32x4*)(qs + dd); dot += kv.x * qv.x + kv.y * qv.y + kv.z * qv.z + kv.w * qv.w; }
;             sc[i] = dot - slope * (float)(j * d);
;         }
;         mx = fmaxf(mx, sc[i]);
;     }
;     mx = wave_max(mx);
;     float ls = 0.f;
; #pragma unroll
;     for (int i = 0; i < 2; ++i) { const float pe = __expf(sc[i] - mx); ls += pe; pb[lane + 64 * i] = pe; }
;     ls = wave_sum(ls);
.LBB0_304:
	s_or_b64 exec, exec, s[0:1]
	s_waitcnt vmcnt(12)
	v_mul_f32_e32 v57, v81, v125
	v_fmac_f32_e32 v57, v80, v124
	v_mul_f32_e32 v73, v73, v121
	v_fmac_f32_e32 v57, v82, v126
	v_fmac_f32_e32 v73, v72, v120
	v_mul_f32_e32 v53, v53, v117
	v_fmac_f32_e32 v57, v83, v127
	v_fmac_f32_e32 v73, v74, v122
	v_fmac_f32_e32 v53, v52, v116
	v_mul_f32_e32 v45, v45, v113
	v_add_f32_e32 v57, 0, v57
	v_fmac_f32_e32 v73, v75, v123
	v_fmac_f32_e32 v53, v54, v118
	v_fmac_f32_e32 v45, v44, v112
	v_add_f32_e32 v57, v57, v73
	v_fmac_f32_e32 v53, v55, v119
	v_fmac_f32_e32 v45, v46, v114
	v_add_f32_e32 v52, v57, v53
	v_fmac_f32_e32 v45, v47, v115
	v_add_f32_e32 v44, v52, v45
	s_waitcnt vmcnt(8)
	v_mul_f32_e32 v45, v49, v109
	v_fmac_f32_e32 v45, v48, v108
	v_mul_f32_e32 v41, v41, v105
	v_fmac_f32_e32 v45, v50, v110
	v_fmac_f32_e32 v41, v40, v104
	v_fmac_f32_e32 v45, v51, v111
	v_fmac_f32_e32 v41, v42, v106
	v_add_f32_e32 v44, v44, v45
	v_fmac_f32_e32 v41, v43, v107
	v_add_f32_e32 v42, v44, v41
	v_mov_b32_e32 v41, v27
	v_mov_b32_e32 v27, v24
	v_mov_b32_e32 v24, v17
	v_mov_b32_e32 v40, v19
	v_mov_b32_e32 v19, v26
	v_mov_b32_e32 v26, v16
	v_pk_mul_f32 v[16:17], v[24:25], v[100:101]
	s_nop 0
	v_pk_fma_f32 v[16:17], v[26:27], v[102:103], v[16:17]
	s_nop 0
	v_pk_fma_f32 v[16:17], v[18:19], v[98:99], v[16:17]
	s_waitcnt vmcnt(4)
	v_mov_b32_e32 v19, v36
	v_pk_fma_f32 v[16:17], v[40:41], v[142:143], v[16:17]
	v_mov_b32_e32 v36, v33
	v_add_f32_e32 v16, v42, v16
	v_mov_b32_e32 v18, v32
	v_pk_mul_f32 v[24:25], v[36:37], v[92:93]
	v_add_f32_e32 v26, v16, v17
	v_mov_b32_e32 v16, v35
	v_mov_b32_e32 v35, v38
	v_pk_fma_f32 v[18:19], v[18:19], v[94:95], v[24:25]
	v_mov_b32_e32 v17, v39
	v_pk_fma_f32 v[18:19], v[34:35], v[90:91], v[18:19]
	s_nop 0
	v_pk_fma_f32 v[16:17], v[16:17], v[96:97], v[18:19]
	s_nop 0
	v_add_f32_e32 v16, v26, v16
	v_add_f32_e32 v18, v16, v17
	v_mov_b32_e32 v17, v15
	v_mov_b32_e32 v15, v12
	v_mov_b32_e32 v12, v9
	v_mov_b32_e32 v16, v11
	v_mov_b32_e32 v11, v14
	v_mov_b32_e32 v14, v8
	v_pk_mul_f32 v[8:9], v[12:13], v[84:85]
	s_nop 0
	v_pk_fma_f32 v[8:9], v[14:15], v[86:87], v[8:9]
	s_nop 0
	v_pk_fma_f32 v[8:9], v[10:11], v[78:79], v[8:9]
	s_waitcnt vmcnt(0)
	v_mov_b32_e32 v11, v28
	v_pk_fma_f32 v[8:9], v[16:17], v[88:89], v[8:9]
	v_mov_b32_e32 v28, v21
	v_add_f32_e32 v8, v18, v8
	v_mov_b32_e32 v10, v20
	v_pk_mul_f32 v[12:13], v[28:29], v[68:69]
	v_add_f32_e32 v14, v8, v9
	v_mov_b32_e32 v8, v23
	v_mov_b32_e32 v23, v30
	v_pk_fma_f32 v[10:11], v[10:11], v[70:71], v[12:13]
	v_mov_b32_e32 v9, v31
	v_pk_fma_f32 v[10:11], v[22:23], v[62:63], v[10:11]
	v_mov_b32_e32 v13, v155
	v_pk_fma_f32 v[8:9], v[8:9], v[76:77], v[10:11]
	s_nop 0
	v_add_f32_e32 v8, v14, v8
	v_add_f32_e32 v10, v8, v9
	v_mov_b32_e32 v9, v7
	v_mov_b32_e32 v7, v4
	v_mov_b32_e32 v4, v1
	v_mov_b32_e32 v8, v3
	v_mov_b32_e32 v3, v6
	v_mov_b32_e32 v6, v0
	v_pk_mul_f32 v[0:1], v[4:5], v[64:65]
	s_nop 0
	v_pk_fma_f32 v[0:1], v[6:7], v[66:67], v[0:1]
	s_nop 0
	v_pk_fma_f32 v[0:1], v[2:3], v[58:59], v[0:1]
	v_xor_b32_e32 v3, 1, v168
	v_pk_fma_f32 v[0:1], v[8:9], v[60:61], v[0:1]
	s_nop 0
	v_add_f32_e32 v0, v10, v0
	v_add_f32_e32 v0, v0, v1
	v_and_b32_e32 v1, 64, v168
	v_add_u32_e32 v1, 64, v1
	v_cmp_lt_i32_e32 vcc, v3, v1
	v_fma_f32 v2, -v137, v150, v0
	v_max3_f32 v0, v2, s54, v56
	v_cndmask_b32_e32 v3, v168, v3, vcc
	v_lshlrev_b32_e32 v3, 2, v3
	ds_bpermute_b32 v4, v3, v0
	s_waitcnt lgkmcnt(0)
	v_max_f32_e32 v4, v4, v4
	v_max_f32_e32 v0, v0, v4
	v_xor_b32_e32 v4, 2, v168
	v_cmp_lt_i32_e32 vcc, v4, v1
	s_nop 1
	v_cndmask_b32_e32 v4, v168, v4, vcc
	v_lshlrev_b32_e32 v4, 2, v4
	ds_bpermute_b32 v5, v4, v0
	s_waitcnt lgkmcnt(0)
	v_max_f32_e32 v5, v5, v5
	v_max_f32_e32 v0, v0, v5
	v_xor_b32_e32 v5, 4, v168
	v_cmp_lt_i32_e32 vcc, v5, v1
	s_nop 1
	v_cndmask_b32_e32 v5, v168, v5, vcc
	v_lshlrev_b32_e32 v5, 2, v5
	ds_bpermute_b32 v6, v5, v0
	s_waitcnt lgkmcnt(0)
	v_max_f32_e32 v6, v6, v6
	v_max_f32_e32 v0, v0, v6
	v_xor_b32_e32 v6, 8, v168
	v_cmp_lt_i32_e32 vcc, v6, v1
	s_nop 1
	v_cndmask_b32_e32 v6, v168, v6, vcc
	v_lshlrev_b32_e32 v6, 2, v6
	ds_bpermute_b32 v7, v6, v0
	s_waitcnt lgkmcnt(0)
	v_max_f32_e32 v7, v7, v7
	v_max_f32_e32 v0, v0, v7
	v_xor_b32_e32 v7, 16, v168
	v_cmp_lt_i32_e32 vcc, v7, v1
	s_nop 1
	v_cndmask_b32_e32 v7, v168, v7, vcc
	v_lshlrev_b32_e32 v12, 2, v7
	ds_bpermute_b32 v7, v12, v0
	s_waitcnt lgkmcnt(0)
	v_max_f32_e32 v7, v7, v7
	v_max_f32_e32 v0, v0, v7
	v_xor_b32_e32 v7, 32, v168
	v_cmp_lt_i32_e32 vcc, v7, v1
	s_nop 1
	v_cndmask_b32_e32 v1, v168, v7, vcc
	v_lshlrev_b32_e32 v1, 2, v1
	ds_bpermute_b32 v7, v1, v0
	s_waitcnt lgkmcnt(0)
	v_max_f32_e32 v7, v7, v7
	v_max_f32_e32 v0, v0, v7
	v_sub_f32_e32 v2, v2, v0
	v_mul_f32_e32 v2, 0x3fb8aa3b, v2
	v_sub_f32_e32 v7, v56, v0
	v_exp_f32_e32 v2, v2
	v_mul_f32_e32 v7, 0x3fb8aa3b, v7
	v_exp_f32_e32 v7, v7
	v_add_f32_e32 v8, 0, v2
	v_add_f32_e32 v8, v7, v8
	ds_bpermute_b32 v3, v3, v8
	ds_write2st64_b32 v148, v2, v7 offset0:1 offset1:2
	s_waitcnt lgkmcnt(0)
	v_mov_b32_e32 v2, v131
	s_waitcnt lgkmcnt(1)
	v_add_f32_e32 v3, v8, v3
	ds_bpermute_b32 v4, v4, v3
	v_mov_b32_e32 v8, v159
	s_waitcnt lgkmcnt(0)
	v_add_f32_e32 v3, v3, v4
	ds_bpermute_b32 v4, v5, v3
	v_mov_b32_e32 v5, v131
	s_waitcnt lgkmcnt(0)
	v_add_f32_e32 v3, v3, v4
	ds_bpermute_b32 v4, v6, v3
	v_lshl_add_u64 v[6:7], v[140:141], 2, s[42:43]
	s_waitcnt lgkmcnt(0)
	v_add_f32_e32 v3, v3, v4
	ds_bpermute_b32 v4, v12, v3
	s_waitcnt lgkmcnt(0)
; DI void decode_pair(const Params& p, LAS float* L  , int pairidx, int wid, int lane) {
;     ...
;     ls = wave_sum(ls);
;     asm volatile("s_waitcnt lgkmcnt(0)" ::: "memory");
;     const int g = lane >> 4, dq = (lane & 15) * 4;
;     f32x4 acc = (f32x4){0.f, 0.f, 0.f, 0.f};
; #pragma unroll 5
;     for (int n = g; n < 97; n += 4) {
;         const int e = kq + 4 * n;
;         if (e < 387) {
;             const int pi = e / 129, j = e - pi * 129, d = 1 << (2 * pi), idx = 2048 - j * d;
;             const float* vr = (idx == 2048) ? vnew : cv + ((size_t)(b * 2048 + idx) * 16 + h) * 64;
;             acc += __builtin_nontemporal_load((const f32x4*)(vr + dq)) * pb[n];
	v_add_f32_e32 v10, v3, v4
	ds_bpermute_b32 v11, v1, v10
	v_mov_b32_e32 v4, v131
	v_mov_b32_e32 v3, v131
	v_ashrrev_i32_e32 v137, 31, v136
	v_lshlrev_b32_e32 v14, 2, v128
	v_mov_b32_e32 v15, v131
	v_mov_b32_e32 v2, v131
	v_mov_b32_e32 v5, v131
	v_mov_b32_e32 v16, v158
	v_mul_u32_u24_e32 v17, 0x3f81, v16
	v_lshrrev_b32_e32 v17, 21, v17
	v_mul_i32_i24_e32 v18, 0xffffff7f, v17
	v_add_u32_e32 v18, v18, v16
	v_cmp_eq_u32_e32 vcc, 0, v18
	v_lshlrev_b32_e32 v17, 1, v17
	v_lshlrev_b32_e32 v17, v17, v18
	v_sub_u32_e32 v20, v169, v17
	v_ashrrev_i32_e32 v21, 31, v20
	v_lshlrev_b64 v[20:21], 12, v[20:21]
	v_lshl_add_u64 v[20:21], s[80:81], 0, v[20:21]
	v_cndmask_b32_e32 v21, v21, v7, vcc
	v_cndmask_b32_e32 v20, v20, v6, vcc
	v_lshl_add_u64 v[20:21], v[20:21], 0, v[130:131]
	v_lshl_add_u64 v[20:21], v[20:21], 0, v[14:15]
	global_load_dwordx4 v[24:27], v[20:21], off nt
	ds_read_b32 v170, v156 offset:0
	v_add_u32_e32 v16, 16, v158
	v_mul_u32_u24_e32 v17, 0x3f81, v16
	v_lshrrev_b32_e32 v17, 21, v17
	v_mul_i32_i24_e32 v18, 0xffffff7f, v17
	v_add_u32_e32 v18, v18, v16
	v_cmp_eq_u32_e32 vcc, 0, v18
	v_lshlrev_b32_e32 v17, 1, v17
	v_lshlrev_b32_e32 v17, v17, v18
	v_sub_u32_e32 v20, v169, v17
	v_ashrrev_i32_e32 v21, 31, v20
	v_lshlrev_b64 v[20:21], 12, v[20:21]
	v_lshl_add_u64 v[20:21], s[80:81], 0, v[20:21]
	v_cndmask_b32_e32 v21, v21, v7, vcc
	v_cndmask_b32_e32 v20, v20, v6, vcc
	v_lshl_add_u64 v[20:21], v[20:21], 0, v[130:131]
	v_lshl_add_u64 v[20:21], v[20:21], 0, v[14:15]
	global_load_dwordx4 v[28:31], v[20:21], off nt
	ds_read_b32 v172, v156 offset:16
	v_add_u32_e32 v16, 32, v158
	v_mul_u32_u24_e32 v17, 0x3f81, v16
	v_lshrrev_b32_e32 v17, 21, v17
	v_mul_i32_i24_e32 v18, 0xffffff7f, v17
	v_add_u32_e32 v18, v18, v16
	v_cmp_eq_u32_e32 vcc, 0, v18
	v_lshlrev_b32_e32 v17, 1, v17
	v_lshlrev_b32_e32 v17, v17, v18
	v_sub_u32_e32 v20, v169, v17
	v_ashrrev_i32_e32 v21, 31, v20
	v_lshlrev_b64 v[20:21], 12, v[20:21]
	v_lshl_add_u64 v[20:21], s[80:81], 0, v[20:21]
	v_cndmask_b32_e32 v21, v21, v7, vcc
	v_cndmask_b32_e32 v20, v20, v6, vcc
	v_lshl_add_u64 v[20:21], v[20:21], 0, v[130:131]
	v_lshl_add_u64 v[20:21], v[20:21], 0, v[14:15]
	global_load_dwordx4 v[32:35], v[20:21], off nt
	ds_read_b32 v174, v156 offset:32
	v_add_u32_e32 v16, 48, v158
	v_mul_u32_u24_e32 v17, 0x3f81, v16
	v_lshrrev_b32_e32 v17, 21, v17
	v_mul_i32_i24_e32 v18, 0xffffff7f, v17
	v_add_u32_e32 v18, v18, v16
	v_cmp_eq_u32_e32 vcc, 0, v18
	v_lshlrev_b32_e32 v17, 1, v17
	v_lshlrev_b32_e32 v17, v17, v18
	v_sub_u32_e32 v20, v169, v17
	v_ashrrev_i32_e32 v21, 31, v20
	v_lshlrev_b64 v[20:21], 12, v[20:21]
	v_lshl_add_u64 v[20:21], s[80:81], 0, v[20:21]
	v_cndmask_b32_e32 v21, v21, v7, vcc
	v_cndmask_b32_e32 v20, v20, v6, vcc
	v_lshl_add_u64 v[20:21], v[20:21], 0, v[130:131]
	v_lshl_add_u64 v[20:21], v[20:21], 0, v[14:15]
	global_load_dwordx4 v[36:39], v[20:21], off nt
	ds_read_b32 v176, v156 offset:48
	v_add_u32_e32 v16, 64, v158
	v_mul_u32_u24_e32 v17, 0x3f81, v16
	v_lshrrev_b32_e32 v17, 21, v17
	v_mul_i32_i24_e32 v18, 0xffffff7f, v17
	v_add_u32_e32 v18, v18, v16
	v_cmp_eq_u32_e32 vcc, 0, v18
	v_lshlrev_b32_e32 v17, 1, v17
	v_lshlrev_b32_e32 v17, v17, v18
	v_sub_u32_e32 v20, v169, v17
	v_ashrrev_i32_e32 v21, 31, v20
	v_lshlrev_b64 v[20:21], 12, v[20:21]
	v_lshl_add_u64 v[20:21], s[80:81], 0, v[20:21]
	v_cndmask_b32_e32 v21, v21, v7, vcc
	v_cndmask_b32_e32 v20, v20, v6, vcc
	v_lshl_add_u64 v[20:21], v[20:21], 0, v[130:131]
	v_lshl_add_u64 v[20:21], v[20:21], 0, v[14:15]
	global_load_dwordx4 v[40:43], v[20:21], off nt
	ds_read_b32 v178, v156 offset:64
	v_add_u32_e32 v16, 80, v158
	v_mul_u32_u24_e32 v17, 0x3f81, v16
	v_lshrrev_b32_e32 v17, 21, v17
	v_mul_i32_i24_e32 v18, 0xffffff7f, v17
	v_add_u32_e32 v18, v18, v16
	v_cmp_eq_u32_e32 vcc, 0, v18
	v_lshlrev_b32_e32 v17, 1, v17
	v_lshlrev_b32_e32 v17, v17, v18
	v_sub_u32_e32 v20, v169, v17
	v_ashrrev_i32_e32 v21, 31, v20
	v_lshlrev_b64 v[20:21], 12, v[20:21]
	v_lshl_add_u64 v[20:21], s[80:81], 0, v[20:21]
	v_cndmask_b32_e32 v21, v21, v7, vcc
	v_cndmask_b32_e32 v20, v20, v6, vcc
	v_lshl_add_u64 v[20:21], v[20:21], 0, v[130:131]
	v_lshl_add_u64 v[20:21], v[20:21], 0, v[14:15]
	global_load_dwordx4 v[44:47], v[20:21], off nt
	ds_read_b32 v180, v156 offset:80
	v_add_u32_e32 v16, 96, v158
	v_mul_u32_u24_e32 v17, 0x3f81, v16
	v_lshrrev_b32_e32 v17, 21, v17
	v_mul_i32_i24_e32 v18, 0xffffff7f, v17
	v_add_u32_e32 v18, v18, v16
	v_cmp_eq_u32_e32 vcc, 0, v18
	v_lshlrev_b32_e32 v17, 1, v17
	v_lshlrev_b32_e32 v17, v17, v18
	v_sub_u32_e32 v20, v169, v17
	v_ashrrev_i32_e32 v21, 31, v20
	v_lshlrev_b64 v[20:21], 12, v[20:21]
	v_lshl_add_u64 v[20:21], s[80:81], 0, v[20:21]
	v_cndmask_b32_e32 v21, v21, v7, vcc
	v_cndmask_b32_e32 v20, v20, v6, vcc
	v_lshl_add_u64 v[20:21], v[20:21], 0, v[130:131]
	v_lshl_add_u64 v[20:21], v[20:21], 0, v[14:15]
	global_load_dwordx4 v[48:51], v[20:21], off nt
	ds_read_b32 v182, v156 offset:96
	v_add_u32_e32 v16, 112, v158
	v_mul_u32_u24_e32 v17, 0x3f81, v16
	v_lshrrev_b32_e32 v17, 21, v17
	v_mul_i32_i24_e32 v18, 0xffffff7f, v17
	v_add_u32_e32 v18, v18, v16
	v_cmp_eq_u32_e32 vcc, 0, v18
	v_lshlrev_b32_e32 v17, 1, v17
	v_lshlrev_b32_e32 v17, v17, v18
	v_sub_u32_e32 v20, v169, v17
	v_ashrrev_i32_e32 v21, 31, v20
	v_lshlrev_b64 v[20:21], 12, v[20:21]
	v_lshl_add_u64 v[20:21], s[80:81], 0, v[20:21]
	v_cndmask_b32_e32 v21, v21, v7, vcc
	v_cndmask_b32_e32 v20, v20, v6, vcc
	v_lshl_add_u64 v[20:21], v[20:21], 0, v[130:131]
	v_lshl_add_u64 v[20:21], v[20:21], 0, v[14:15]
	global_load_dwordx4 v[52:55], v[20:21], off nt
	ds_read_b32 v184, v156 offset:112
	v_add_u32_e32 v16, 128, v158
	v_mul_u32_u24_e32 v17, 0x3f81, v16
	v_lshrrev_b32_e32 v17, 21, v17
; DI void decode_pair(const Params& p, LAS float* L  , int pairidx, int wid, int lane) {
;     ...
;     for (int n = g; n < 97; n += 4) {
;         const int e = kq + 4 * n;
;         if (e < 387) {
;             const int pi = e / 129, j = e - pi * 129, d = 1 << (2 * pi), idx = 2048 - j * d;
;             const float* vr = (idx == 2048) ? vnew : cv + ((size_t)(b * 2048 + idx) * 16 + h) * 64;
;             acc += __builtin_nontemporal_load((const f32x4*)(vr + dq)) * pb[n];
	v_mul_i32_i24_e32 v18, 0xffffff7f, v17
	v_add_u32_e32 v18, v18, v16
	v_cmp_eq_u32_e32 vcc, 0, v18
	v_lshlrev_b32_e32 v17, 1, v17
	v_lshlrev_b32_e32 v17, v17, v18
	v_sub_u32_e32 v20, v169, v17
	v_ashrrev_i32_e32 v21, 31, v20
	v_lshlrev_b64 v[20:21], 12, v[20:21]
	v_lshl_add_u64 v[20:21], s[80:81], 0, v[20:21]
	v_cndmask_b32_e32 v21, v21, v7, vcc
	v_cndmask_b32_e32 v20, v20, v6, vcc
	v_lshl_add_u64 v[20:21], v[20:21], 0, v[130:131]
	v_lshl_add_u64 v[20:21], v[20:21], 0, v[14:15]
	global_load_dwordx4 v[56:59], v[20:21], off nt
	ds_read_b32 v186, v156 offset:128
	v_add_u32_e32 v16, 144, v158
	v_mul_u32_u24_e32 v17, 0x3f81, v16
	v_lshrrev_b32_e32 v17, 21, v17
	v_mul_i32_i24_e32 v18, 0xffffff7f, v17
	v_add_u32_e32 v18, v18, v16
	v_cmp_eq_u32_e32 vcc, 0, v18
	v_lshlrev_b32_e32 v17, 1, v17
	v_lshlrev_b32_e32 v17, v17, v18
	v_sub_u32_e32 v20, v169, v17
	v_ashrrev_i32_e32 v21, 31, v20
	v_lshlrev_b64 v[20:21], 12, v[20:21]
	v_lshl_add_u64 v[20:21], s[80:81], 0, v[20:21]
	v_cndmask_b32_e32 v21, v21, v7, vcc
	v_cndmask_b32_e32 v20, v20, v6, vcc
	v_lshl_add_u64 v[20:21], v[20:21], 0, v[130:131]
	v_lshl_add_u64 v[20:21], v[20:21], 0, v[14:15]
	global_load_dwordx4 v[60:63], v[20:21], off nt
	ds_read_b32 v188, v156 offset:144
	v_add_u32_e32 v16, 160, v158
	v_mul_u32_u24_e32 v17, 0x3f81, v16
	v_lshrrev_b32_e32 v17, 21, v17
	v_mul_i32_i24_e32 v18, 0xffffff7f, v17
	v_add_u32_e32 v18, v18, v16
	v_cmp_eq_u32_e32 vcc, 0, v18
	v_lshlrev_b32_e32 v17, 1, v17
	v_lshlrev_b32_e32 v17, v17, v18
	v_sub_u32_e32 v20, v169, v17
	v_ashrrev_i32_e32 v21, 31, v20
	v_lshlrev_b64 v[20:21], 12, v[20:21]
	v_lshl_add_u64 v[20:21], s[80:81], 0, v[20:21]
	v_cndmask_b32_e32 v21, v21, v7, vcc
	v_cndmask_b32_e32 v20, v20, v6, vcc
	v_lshl_add_u64 v[20:21], v[20:21], 0, v[130:131]
	v_lshl_add_u64 v[20:21], v[20:21], 0, v[14:15]
	global_load_dwordx4 v[64:67], v[20:21], off nt
	ds_read_b32 v190, v156 offset:160
	v_add_u32_e32 v16, 176, v158
	v_mul_u32_u24_e32 v17, 0x3f81, v16
	v_lshrrev_b32_e32 v17, 21, v17
	v_mul_i32_i24_e32 v18, 0xffffff7f, v17
	v_add_u32_e32 v18, v18, v16
	v_cmp_eq_u32_e32 vcc, 0, v18
	v_lshlrev_b32_e32 v17, 1, v17
	v_lshlrev_b32_e32 v17, v17, v18
	v_sub_u32_e32 v20, v169, v17
	v_ashrrev_i32_e32 v21, 31, v20
	v_lshlrev_b64 v[20:21], 12, v[20:21]
	v_lshl_add_u64 v[20:21], s[80:81], 0, v[20:21]
	v_cndmask_b32_e32 v21, v21, v7, vcc
	v_cndmask_b32_e32 v20, v20, v6, vcc
	v_lshl_add_u64 v[20:21], v[20:21], 0, v[130:131]
	v_lshl_add_u64 v[20:21], v[20:21], 0, v[14:15]
	global_load_dwordx4 v[68:71], v[20:21], off nt
	ds_read_b32 v192, v156 offset:176
	v_add_u32_e32 v16, 192, v158
	v_mul_u32_u24_e32 v17, 0x3f81, v16
	v_lshrrev_b32_e32 v17, 21, v17
	v_mul_i32_i24_e32 v18, 0xffffff7f, v17
	v_add_u32_e32 v18, v18, v16
	v_cmp_eq_u32_e32 vcc, 0, v18
	v_lshlrev_b32_e32 v17, 1, v17
	v_lshlrev_b32_e32 v17, v17, v18
	v_sub_u32_e32 v20, v169, v17
	v_ashrrev_i32_e32 v21, 31, v20
	v_lshlrev_b64 v[20:21], 12, v[20:21]
	v_lshl_add_u64 v[20:21], s[80:81], 0, v[20:21]
	v_cndmask_b32_e32 v21, v21, v7, vcc
	v_cndmask_b32_e32 v20, v20, v6, vcc
	v_lshl_add_u64 v[20:21], v[20:21], 0, v[130:131]
	v_lshl_add_u64 v[20:21], v[20:21], 0, v[14:15]
	global_load_dwordx4 v[72:75], v[20:21], off nt
	ds_read_b32 v194, v156 offset:192
	v_add_u32_e32 v16, 208, v158
	v_mul_u32_u24_e32 v17, 0x3f81, v16
	v_lshrrev_b32_e32 v17, 21, v17
	v_mul_i32_i24_e32 v18, 0xffffff7f, v17
	v_add_u32_e32 v18, v18, v16
	v_cmp_eq_u32_e32 vcc, 0, v18
	v_lshlrev_b32_e32 v17, 1, v17
	v_lshlrev_b32_e32 v17, v17, v18
	v_sub_u32_e32 v20, v169, v17
	v_ashrrev_i32_e32 v21, 31, v20
	v_lshlrev_b64 v[20:21], 12, v[20:21]
	v_lshl_add_u64 v[20:21], s[80:81], 0, v[20:21]
	v_cndmask_b32_e32 v21, v21, v7, vcc
	v_cndmask_b32_e32 v20, v20, v6, vcc
	v_lshl_add_u64 v[20:21], v[20:21], 0, v[130:131]
	v_lshl_add_u64 v[20:21], v[20:21], 0, v[14:15]
	global_load_dwordx4 v[76:79], v[20:21], off nt
	ds_read_b32 v196, v156 offset:208
	v_add_u32_e32 v16, 224, v158
	v_mul_u32_u24_e32 v17, 0x3f81, v16
	v_lshrrev_b32_e32 v17, 21, v17
	v_mul_i32_i24_e32 v18, 0xffffff7f, v17
	v_add_u32_e32 v18, v18, v16
	v_cmp_eq_u32_e32 vcc, 0, v18
	v_lshlrev_b32_e32 v17, 1, v17
	v_lshlrev_b32_e32 v17, v17, v18
	v_sub_u32_e32 v20, v169, v17
	v_ashrrev_i32_e32 v21, 31, v20
	v_lshlrev_b64 v[20:21], 12, v[20:21]
	v_lshl_add_u64 v[20:21], s[80:81], 0, v[20:21]
	v_cndmask_b32_e32 v21, v21, v7, vcc
	v_cndmask_b32_e32 v20, v20, v6, vcc
	v_lshl_add_u64 v[20:21], v[20:21], 0, v[130:131]
	v_lshl_add_u64 v[20:21], v[20:21], 0, v[14:15]
	global_load_dwordx4 v[80:83], v[20:21], off nt
	ds_read_b32 v198, v156 offset:224
	v_add_u32_e32 v16, 240, v158
	v_mul_u32_u24_e32 v17, 0x3f81, v16
	v_lshrrev_b32_e32 v17, 21, v17
	v_mul_i32_i24_e32 v18, 0xffffff7f, v17
	v_add_u32_e32 v18, v18, v16
	v_cmp_eq_u32_e32 vcc, 0, v18
	v_lshlrev_b32_e32 v17, 1, v17
	v_lshlrev_b32_e32 v17, v17, v18
	v_sub_u32_e32 v20, v169, v17
	v_ashrrev_i32_e32 v21, 31, v20
	v_lshlrev_b64 v[20:21], 12, v[20:21]
	v_lshl_add_u64 v[20:21], s[80:81], 0, v[20:21]
	v_cndmask_b32_e32 v21, v21, v7, vcc
	v_cndmask_b32_e32 v20, v20, v6, vcc
	v_lshl_add_u64 v[20:21], v[20:21], 0, v[130:131]
	v_lshl_add_u64 v[20:21], v[20:21], 0, v[14:15]
	global_load_dwordx4 v[84:87], v[20:21], off nt
	ds_read_b32 v200, v156 offset:240
	v_add_u32_e32 v16, 256, v158
	v_mul_u32_u24_e32 v17, 0x3f81, v16
	v_lshrrev_b32_e32 v17, 21, v17
	v_mul_i32_i24_e32 v18, 0xffffff7f, v17
	v_add_u32_e32 v18, v18, v16
	v_cmp_eq_u32_e32 vcc, 0, v18
	v_lshlrev_b32_e32 v17, 1, v17
	v_lshlrev_b32_e32 v17, v17, v18
	v_sub_u32_e32 v20, v169, v17
	v_ashrrev_i32_e32 v21, 31, v20
	v_lshlrev_b64 v[20:21], 12, v[20:21]
	v_lshl_add_u64 v[20:21], s[80:81], 0, v[20:21]
; DI void decode_pair(const Params& p, LAS float* L  , int pairidx, int wid, int lane) {
;     ...
;     for (int n = g; n < 97; n += 4) {
;         const int e = kq + 4 * n;
;         if (e < 387) {
;             const int pi = e / 129, j = e - pi * 129, d = 1 << (2 * pi), idx = 2048 - j * d;
;             const float* vr = (idx == 2048) ? vnew : cv + ((size_t)(b * 2048 + idx) * 16 + h) * 64;
;             acc += __builtin_nontemporal_load((const f32x4*)(vr + dq)) * pb[n];
	v_cndmask_b32_e32 v21, v21, v7, vcc
	v_cndmask_b32_e32 v20, v20, v6, vcc
	v_lshl_add_u64 v[20:21], v[20:21], 0, v[130:131]
	v_lshl_add_u64 v[20:21], v[20:21], 0, v[14:15]
	global_load_dwordx4 v[88:91], v[20:21], off nt
	ds_read_b32 v202, v156 offset:256
	v_add_u32_e32 v16, 272, v158
	v_mul_u32_u24_e32 v17, 0x3f81, v16
	v_lshrrev_b32_e32 v17, 21, v17
	v_mul_i32_i24_e32 v18, 0xffffff7f, v17
	v_add_u32_e32 v18, v18, v16
	v_cmp_eq_u32_e32 vcc, 0, v18
	v_lshlrev_b32_e32 v17, 1, v17
	v_lshlrev_b32_e32 v17, v17, v18
	v_sub_u32_e32 v20, v169, v17
	v_ashrrev_i32_e32 v21, 31, v20
	v_lshlrev_b64 v[20:21], 12, v[20:21]
	v_lshl_add_u64 v[20:21], s[80:81], 0, v[20:21]
	v_cndmask_b32_e32 v21, v21, v7, vcc
	v_cndmask_b32_e32 v20, v20, v6, vcc
	v_lshl_add_u64 v[20:21], v[20:21], 0, v[130:131]
	v_lshl_add_u64 v[20:21], v[20:21], 0, v[14:15]
	global_load_dwordx4 v[92:95], v[20:21], off nt
	ds_read_b32 v204, v156 offset:272
	v_add_u32_e32 v16, 288, v158
	v_mul_u32_u24_e32 v17, 0x3f81, v16
	v_lshrrev_b32_e32 v17, 21, v17
	v_mul_i32_i24_e32 v18, 0xffffff7f, v17
	v_add_u32_e32 v18, v18, v16
	v_cmp_eq_u32_e32 vcc, 0, v18
	v_lshlrev_b32_e32 v17, 1, v17
	v_lshlrev_b32_e32 v17, v17, v18
	v_sub_u32_e32 v20, v169, v17
	v_ashrrev_i32_e32 v21, 31, v20
	v_lshlrev_b64 v[20:21], 12, v[20:21]
	v_lshl_add_u64 v[20:21], s[80:81], 0, v[20:21]
	v_cndmask_b32_e32 v21, v21, v7, vcc
	v_cndmask_b32_e32 v20, v20, v6, vcc
	v_lshl_add_u64 v[20:21], v[20:21], 0, v[130:131]
	v_lshl_add_u64 v[20:21], v[20:21], 0, v[14:15]
	global_load_dwordx4 v[96:99], v[20:21], off nt
	ds_read_b32 v206, v156 offset:288
	v_add_u32_e32 v16, 304, v158
	v_mul_u32_u24_e32 v17, 0x3f81, v16
	v_lshrrev_b32_e32 v17, 21, v17
	v_mul_i32_i24_e32 v18, 0xffffff7f, v17
	v_add_u32_e32 v18, v18, v16
	v_cmp_eq_u32_e32 vcc, 0, v18
	v_lshlrev_b32_e32 v17, 1, v17
	v_lshlrev_b32_e32 v17, v17, v18
	v_sub_u32_e32 v20, v169, v17
	v_ashrrev_i32_e32 v21, 31, v20
	v_lshlrev_b64 v[20:21], 12, v[20:21]
	v_lshl_add_u64 v[20:21], s[80:81], 0, v[20:21]
	v_cndmask_b32_e32 v21, v21, v7, vcc
	v_cndmask_b32_e32 v20, v20, v6, vcc
	v_lshl_add_u64 v[20:21], v[20:21], 0, v[130:131]
	v_lshl_add_u64 v[20:21], v[20:21], 0, v[14:15]
	global_load_dwordx4 v[100:103], v[20:21], off nt
	ds_read_b32 v208, v156 offset:304
	v_add_u32_e32 v16, 320, v158
	v_mul_u32_u24_e32 v17, 0x3f81, v16
	v_lshrrev_b32_e32 v17, 21, v17
	v_mul_i32_i24_e32 v18, 0xffffff7f, v17
	v_add_u32_e32 v18, v18, v16
	v_cmp_eq_u32_e32 vcc, 0, v18
	v_lshlrev_b32_e32 v17, 1, v17
	v_lshlrev_b32_e32 v17, v17, v18
	v_sub_u32_e32 v20, v169, v17
	v_ashrrev_i32_e32 v21, 31, v20
	v_lshlrev_b64 v[20:21], 12, v[20:21]
	v_lshl_add_u64 v[20:21], s[80:81], 0, v[20:21]
	v_cndmask_b32_e32 v21, v21, v7, vcc
	v_cndmask_b32_e32 v20, v20, v6, vcc
	v_lshl_add_u64 v[20:21], v[20:21], 0, v[130:131]
	v_lshl_add_u64 v[20:21], v[20:21], 0, v[14:15]
	global_load_dwordx4 v[104:107], v[20:21], off nt
	ds_read_b32 v210, v156 offset:320
	v_add_u32_e32 v16, 336, v158
	v_mul_u32_u24_e32 v17, 0x3f81, v16
	v_lshrrev_b32_e32 v17, 21, v17
	v_mul_i32_i24_e32 v18, 0xffffff7f, v17
	v_add_u32_e32 v18, v18, v16
	v_cmp_eq_u32_e32 vcc, 0, v18
	v_lshlrev_b32_e32 v17, 1, v17
	v_lshlrev_b32_e32 v17, v17, v18
	v_sub_u32_e32 v20, v169, v17
	v_ashrrev_i32_e32 v21, 31, v20
	v_lshlrev_b64 v[20:21], 12, v[20:21]
	v_lshl_add_u64 v[20:21], s[80:81], 0, v[20:21]
	v_cndmask_b32_e32 v21, v21, v7, vcc
	v_cndmask_b32_e32 v20, v20, v6, vcc
	v_lshl_add_u64 v[20:21], v[20:21], 0, v[130:131]
	v_lshl_add_u64 v[20:21], v[20:21], 0, v[14:15]
	global_load_dwordx4 v[108:111], v[20:21], off nt
	ds_read_b32 v212, v156 offset:336
	v_add_u32_e32 v16, 352, v158
	v_mul_u32_u24_e32 v17, 0x3f81, v16
	v_lshrrev_b32_e32 v17, 21, v17
	v_mul_i32_i24_e32 v18, 0xffffff7f, v17
	v_add_u32_e32 v18, v18, v16
	v_cmp_eq_u32_e32 vcc, 0, v18
	v_lshlrev_b32_e32 v17, 1, v17
	v_lshlrev_b32_e32 v17, v17, v18
	v_sub_u32_e32 v20, v169, v17
	v_ashrrev_i32_e32 v21, 31, v20
	v_lshlrev_b64 v[20:21], 12, v[20:21]
	v_lshl_add_u64 v[20:21], s[80:81], 0, v[20:21]
	v_cndmask_b32_e32 v21, v21, v7, vcc
	v_cndmask_b32_e32 v20, v20, v6, vcc
	v_lshl_add_u64 v[20:21], v[20:21], 0, v[130:131]
	v_lshl_add_u64 v[20:21], v[20:21], 0, v[14:15]
	global_load_dwordx4 v[112:115], v[20:21], off nt
	ds_read_b32 v214, v156 offset:352
	v_add_u32_e32 v16, 368, v158
	v_mul_u32_u24_e32 v17, 0x3f81, v16
	v_lshrrev_b32_e32 v17, 21, v17
	v_mul_i32_i24_e32 v18, 0xffffff7f, v17
	v_add_u32_e32 v18, v18, v16
	v_cmp_eq_u32_e32 vcc, 0, v18
	v_lshlrev_b32_e32 v17, 1, v17
	v_lshlrev_b32_e32 v17, v17, v18
	v_sub_u32_e32 v20, v169, v17
	v_ashrrev_i32_e32 v21, 31, v20
	v_lshlrev_b64 v[20:21], 12, v[20:21]
	v_lshl_add_u64 v[20:21], s[80:81], 0, v[20:21]
	v_cndmask_b32_e32 v21, v21, v7, vcc
	v_cndmask_b32_e32 v20, v20, v6, vcc
	v_lshl_add_u64 v[20:21], v[20:21], 0, v[130:131]
	v_lshl_add_u64 v[20:21], v[20:21], 0, v[14:15]
	global_load_dwordx4 v[116:119], v[20:21], off nt
	ds_read_b32 v216, v156 offset:368
	v_cmp_gt_u32_e32 vcc, 3, v158
	s_and_saveexec_b64 s[18:19], vcc
	s_cbranch_execz .Ldv_skip_a
	v_add_u32_e32 v16, 384, v158
	v_mul_u32_u24_e32 v17, 0x3f81, v16
	v_lshrrev_b32_e32 v17, 21, v17
	v_mul_i32_i24_e32 v18, 0xffffff7f, v17
	v_add_u32_e32 v18, v18, v16
	v_cmp_eq_u32_e32 vcc, 0, v18
	v_lshlrev_b32_e32 v17, 1, v17
	v_lshlrev_b32_e32 v17, v17, v18
	v_sub_u32_e32 v20, v169, v17
	v_ashrrev_i32_e32 v21, 31, v20
	v_lshlrev_b64 v[20:21], 12, v[20:21]
	v_lshl_add_u64 v[20:21], s[80:81], 0, v[20:21]
	v_cndmask_b32_e32 v21, v21, v7, vcc
	v_cndmask_b32_e32 v20, v20, v6, vcc
	v_lshl_add_u64 v[20:21], v[20:21], 0, v[130:131]
	v_lshl_add_u64 v[20:21], v[20:21], 0, v[14:15]
	global_load_dwordx4 v[120:123], v[20:21], off nt
	ds_read_b32 v218, v156 offset:384
; #define LAS __attribute__((address_space(3)))
; DI void decode_pair(const Params& p, LAS float* L  , int pairidx, int wid, int lane) {
;     ...
;     for (int n = g; n < 97; n += 4) {
;         const int e = kq + 4 * n;
;         if (e < 387) {
;             const int pi = e / 129, j = e - pi * 129, d = 1 << (2 * pi), idx = 2048 - j * d;
;             const float* vr = (idx == 2048) ? vnew : cv + ((size_t)(b * 2048 + idx) * 16 + h) * 64;
;             acc += __builtin_nontemporal_load((const f32x4*)(vr + dq)) * pb[n];
;         }
;     }
; #pragma unroll
;     for (int k = 0; k < 4; ++k) { float t = acc[k]; t += __shfl_xor(t, 16); t += __shfl_xor(t, 32); acc[k] = t; }
;     if (lane < 16) *(LAS f32x4*)(ob + dq) = acc;
.Ldv_skip_a:
	s_or_b64 exec, exec, s[18:19]
	s_waitcnt lgkmcnt(0)
	s_waitcnt vmcnt(23)
	v_pk_fma_f32 v[2:3], v[26:27], v[170:171], v[2:3] op_sel_hi:[1,0,1]
	v_pk_fma_f32 v[4:5], v[24:25], v[170:171], v[4:5] op_sel_hi:[1,0,1]
	s_waitcnt vmcnt(22)
	v_pk_fma_f32 v[2:3], v[30:31], v[172:173], v[2:3] op_sel_hi:[1,0,1]
	v_pk_fma_f32 v[4:5], v[28:29], v[172:173], v[4:5] op_sel_hi:[1,0,1]
	s_waitcnt vmcnt(21)
	v_pk_fma_f32 v[2:3], v[34:35], v[174:175], v[2:3] op_sel_hi:[1,0,1]
	v_pk_fma_f32 v[4:5], v[32:33], v[174:175], v[4:5] op_sel_hi:[1,0,1]
	s_waitcnt vmcnt(20)
	v_pk_fma_f32 v[2:3], v[38:39], v[176:177], v[2:3] op_sel_hi:[1,0,1]
	v_pk_fma_f32 v[4:5], v[36:37], v[176:177], v[4:5] op_sel_hi:[1,0,1]
	s_waitcnt vmcnt(19)
	v_pk_fma_f32 v[2:3], v[42:43], v[178:179], v[2:3] op_sel_hi:[1,0,1]
	v_pk_fma_f32 v[4:5], v[40:41], v[178:179], v[4:5] op_sel_hi:[1,0,1]
	s_waitcnt vmcnt(18)
	v_pk_fma_f32 v[2:3], v[46:47], v[180:181], v[2:3] op_sel_hi:[1,0,1]
	v_pk_fma_f32 v[4:5], v[44:45], v[180:181], v[4:5] op_sel_hi:[1,0,1]
	s_waitcnt vmcnt(17)
	v_pk_fma_f32 v[2:3], v[50:51], v[182:183], v[2:3] op_sel_hi:[1,0,1]
	v_pk_fma_f32 v[4:5], v[48:49], v[182:183], v[4:5] op_sel_hi:[1,0,1]
	s_waitcnt vmcnt(16)
	v_pk_fma_f32 v[2:3], v[54:55], v[184:185], v[2:3] op_sel_hi:[1,0,1]
	v_pk_fma_f32 v[4:5], v[52:53], v[184:185], v[4:5] op_sel_hi:[1,0,1]
	s_waitcnt vmcnt(15)
	v_pk_fma_f32 v[2:3], v[58:59], v[186:187], v[2:3] op_sel_hi:[1,0,1]
	v_pk_fma_f32 v[4:5], v[56:57], v[186:187], v[4:5] op_sel_hi:[1,0,1]
	s_waitcnt vmcnt(14)
	v_pk_fma_f32 v[2:3], v[62:63], v[188:189], v[2:3] op_sel_hi:[1,0,1]
	v_pk_fma_f32 v[4:5], v[60:61], v[188:189], v[4:5] op_sel_hi:[1,0,1]
	s_waitcnt vmcnt(13)
	v_pk_fma_f32 v[2:3], v[66:67], v[190:191], v[2:3] op_sel_hi:[1,0,1]
	v_pk_fma_f32 v[4:5], v[64:65], v[190:191], v[4:5] op_sel_hi:[1,0,1]
	s_waitcnt vmcnt(12)
	v_pk_fma_f32 v[2:3], v[70:71], v[192:193], v[2:3] op_sel_hi:[1,0,1]
	v_pk_fma_f32 v[4:5], v[68:69], v[192:193], v[4:5] op_sel_hi:[1,0,1]
	s_waitcnt vmcnt(11)
	v_pk_fma_f32 v[2:3], v[74:75], v[194:195], v[2:3] op_sel_hi:[1,0,1]
	v_pk_fma_f32 v[4:5], v[72:73], v[194:195], v[4:5] op_sel_hi:[1,0,1]
	s_waitcnt vmcnt(10)
	v_pk_fma_f32 v[2:3], v[78:79], v[196:197], v[2:3] op_sel_hi:[1,0,1]
	v_pk_fma_f32 v[4:5], v[76:77], v[196:197], v[4:5] op_sel_hi:[1,0,1]
	s_waitcnt vmcnt(9)
	v_pk_fma_f32 v[2:3], v[82:83], v[198:199], v[2:3] op_sel_hi:[1,0,1]
	v_pk_fma_f32 v[4:5], v[80:81], v[198:199], v[4:5] op_sel_hi:[1,0,1]
	s_waitcnt vmcnt(8)
	v_pk_fma_f32 v[2:3], v[86:87], v[200:201], v[2:3] op_sel_hi:[1,0,1]
	v_pk_fma_f32 v[4:5], v[84:85], v[200:201], v[4:5] op_sel_hi:[1,0,1]
	s_waitcnt vmcnt(7)
	v_pk_fma_f32 v[2:3], v[90:91], v[202:203], v[2:3] op_sel_hi:[1,0,1]
	v_pk_fma_f32 v[4:5], v[88:89], v[202:203], v[4:5] op_sel_hi:[1,0,1]
	s_waitcnt vmcnt(6)
	v_pk_fma_f32 v[2:3], v[94:95], v[204:205], v[2:3] op_sel_hi:[1,0,1]
	v_pk_fma_f32 v[4:5], v[92:93], v[204:205], v[4:5] op_sel_hi:[1,0,1]
	s_waitcnt vmcnt(5)
	v_pk_fma_f32 v[2:3], v[98:99], v[206:207], v[2:3] op_sel_hi:[1,0,1]
	v_pk_fma_f32 v[4:5], v[96:97], v[206:207], v[4:5] op_sel_hi:[1,0,1]
	s_waitcnt vmcnt(4)
	v_pk_fma_f32 v[2:3], v[102:103], v[208:209], v[2:3] op_sel_hi:[1,0,1]
	v_pk_fma_f32 v[4:5], v[100:101], v[208:209], v[4:5] op_sel_hi:[1,0,1]
	s_waitcnt vmcnt(3)
	v_pk_fma_f32 v[2:3], v[106:107], v[210:211], v[2:3] op_sel_hi:[1,0,1]
	v_pk_fma_f32 v[4:5], v[104:105], v[210:211], v[4:5] op_sel_hi:[1,0,1]
	s_waitcnt vmcnt(2)
	v_pk_fma_f32 v[2:3], v[110:111], v[212:213], v[2:3] op_sel_hi:[1,0,1]
	v_pk_fma_f32 v[4:5], v[108:109], v[212:213], v[4:5] op_sel_hi:[1,0,1]
	s_waitcnt vmcnt(1)
	v_pk_fma_f32 v[2:3], v[114:115], v[214:215], v[2:3] op_sel_hi:[1,0,1]
	v_pk_fma_f32 v[4:5], v[112:113], v[214:215], v[4:5] op_sel_hi:[1,0,1]
	s_waitcnt vmcnt(0)
	v_pk_fma_f32 v[2:3], v[118:119], v[216:217], v[2:3] op_sel_hi:[1,0,1]
	v_pk_fma_f32 v[4:5], v[116:117], v[216:217], v[4:5] op_sel_hi:[1,0,1]
	v_cmp_gt_u32_e32 vcc, 3, v158
	s_and_saveexec_b64 s[18:19], vcc
	s_cbranch_execz .Ldv_skip_b
	s_waitcnt vmcnt(0)
	v_pk_fma_f32 v[2:3], v[122:123], v[218:219], v[2:3] op_sel_hi:[1,0,1]
	v_pk_fma_f32 v[4:5], v[120:121], v[218:219], v[4:5] op_sel_hi:[1,0,1]
.Ldv_skip_b:
	s_or_b64 exec, exec, s[18:19]
	ds_bpermute_b32 v6, v12, v4
	ds_bpermute_b32 v7, v12, v5
	ds_bpermute_b32 v8, v12, v2
	ds_bpermute_b32 v9, v12, v3
	s_waitcnt lgkmcnt(2)
	v_pk_add_f32 v[4:5], v[4:5], v[6:7]
	ds_bpermute_b32 v6, v1, v4
	s_waitcnt lgkmcnt(1)
	v_pk_add_f32 v[2:3], v[2:3], v[8:9]
	ds_bpermute_b32 v7, v1, v5
	ds_bpermute_b32 v8, v1, v2
	ds_bpermute_b32 v9, v1, v3
	s_and_saveexec_b64 s[0:1], s[6:7]
	s_cbranch_execz .LBB0_324
	s_waitcnt lgkmcnt(0)
	v_pk_add_f32 v[8:9], v[2:3], v[8:9]
	v_pk_add_f32 v[6:7], v[4:5], v[6:7]
	ds_write_b128 v153, v[6:9] offset:768

; DI void phase3(const Params& p, LAS unsigned char* lds) {
;     ...
;     if (G == 256) {
;         const int x = blockIdx.x & 7, lw = (blockIdx.x >> 3) * NWAVES + wid;
;         (void)lw; const int lb = blockIdx.x >> 3;
;         for (int k2 = 0; k2 < 4; ++k2) attn_block(p, lds, x * 8 + 2 * k2 + (lb >> 4), lb & 15, wid, lane);
;         __syncthreads();
;     } else
;         for (int it = gw; it < 16384; it += NGW) attn_item(p, wl, it, lane);
.LBB0_328:
	v_readlane_b32 s0, v251, 3
	s_cmpk_lg_i32 s22, 0x100
	s_cselect_b64 s[34:35], -1, 0
	v_add_u32_e32 v228, s0, v227
	s_cmpk_eq_i32 s22, 0x100
	s_mov_b64 s[0:1], -1
	s_cbranch_scc0 .LBB0_331
	s_andn2_b64 vcc, exec, s[0:1]
	v_lshlrev_b32_e32 v229, 3, v129
	v_readlane_b32 s0, v254, 1
	s_nop 3
	s_cmp_lg_u32 s0, 1
	s_cbranch_scc1 .Lp3_glue_cont
	v_writelane_b32 v254, 2, 1
	s_branch .LBB0_330

; #define LAS __attribute__((address_space(3)))
; DI void attn_block(const Params& p, LAS unsigned char* lds, int bh, int blk, int wid, int lane) {
;     const int b = bh >> 4, h = bh & 15, T0 = blk * 256;
;     const int c = lane & 15, quad = lane >> 4;
;     LAS float* st = (LAS float*)lds;
;     LAS unsigned char* vb = lds + AST_BYTES + wid * 9216;
;     const bf16_t* Zb = (const bf16_t*)(p.ws + WS_Z) + (size_t)b * SEQ * ZLD;
;     const float slope2 = exp2f(-0.5f * (float)(h + 1)) * LOG2E, sc2 = 0.125f * LOG2E;
;     const int lrow = lane >> 3, lch = (lane & 7) * 8;
;     const bf16_t* kbase = Zb + 5120 + h * 64 + lch;
;     const bf16_t* vbase = Zb + 6144 + h * 64 + lch;
;     LAS unsigned char* kb = vb + 32 * VROW;
;     LAS unsigned char* kw = kb + lrow * VROW + lch * 2;
;     LAS unsigned char* vw = vb + lrow * VROW + lch * 2;
;     const LAS unsigned char* kr = kb + c * VROW + quad * 16;
;     const LAS unsigned char* vr = vb + (4 * quad + (c >> 2)) * VROW + (c & 3) * 8;
;     u32x4 kfA[4], kfB[4], kfC[4], vfA[4], vfB[4], vfC[4];
;     bf16x8 qa0, qa1, qb0, qb1, qna0, qna1, qnb0, qnb1; u32x2 gate[4];
;     float mA = -1e30f, lA = 0.f, mB = -1e30f, lB = 0.f; f32x4 oA[4], oB[4];
; #pragma unroll
;     for (int i = 0; i < 4; ++i) { oA[i] = (f32x4){0.f, 0.f, 0.f, 0.f}; oB[i] = oA[i]; gate[i] = (u32x2){0u, 0u}; }
;     qb0 = (bf16x8){0, 0, 0, 0, 0, 0, 0, 0}; qb1 = qb0; qnb0 = qb0; qnb1 = qb0;
.LBB0_384:
	v_readlane_b32 s0, v251, 3
	s_and_b32 s3, s0, 56
	s_lshr_b32 s0, s2, 7
	s_add_i32 s3, s3, s0
	s_movk_i32 s0, 0x2400
	v_mul_lo_u32 v0, v227, s0
	s_add_i32 s0, 0, 0x11400
	v_lshlrev_b32_e32 v176, 2, v159
	v_bfe_u32 v4, v177, 2, 2
	s_lshl_b32 s6, s2, 5
	v_and_b32_e32 v230, 15, v177
	v_add_u32_e32 v0, s0, v0
	v_lshrrev_b32_e32 v231, 3, v129
	s_movk_i32 s0, 0x90
	v_or_b32_e32 v4, v176, v4
	s_and_b32 s12, s6, 0xf00
	v_lshlrev_b32_e32 v232, 5, v227
	v_mad_u32_u24 v5, v231, s0, v0
	v_mad_u32_u24 v22, v230, s0, v0
	v_mad_u32_u24 v23, v4, s0, v0
	v_add_u32_e32 v0, s12, v232
	v_or_b32_e32 v24, v0, v231
	v_mov_b32_e32 v233, 0xfff
	v_or_b32_e32 v4, v0, v230
	s_movk_i32 s41, 0x4100
	v_med3_i32 v0, v24, 0, v233
	v_or_b32_e32 v6, 8, v24
	v_or_b32_e32 v8, 16, v24
	v_or_b32_e32 v10, 24, v24
	v_subrev_u32_e32 v12, 32, v24
	v_subrev_u32_e32 v14, 24, v24
	v_add_u32_e32 v16, -16, v24
	v_add_u32_e32 v18, -8, v24
	v_subrev_u32_e32 v25, 64, v24
	v_and_b32_e32 v2, 56, v229
	v_mov_b32_e32 v1, 0
	v_mad_i64_i32 v[178:179], s[6:7], v4, s41, 0
	v_lshlrev_b32_e32 v4, 3, v159
	v_mul_u32_u24_e32 v0, 0x2080, v0
	v_med3_i32 v6, v6, 0, v233
	v_med3_i32 v8, v8, 0, v233
	v_med3_i32 v10, v10, 0, v233
	v_med3_i32 v12, v12, 0, v233
	v_med3_i32 v14, v14, 0, v233
	v_med3_i32 v16, v16, 0, v233
	v_med3_i32 v18, v18, 0, v233
	v_med3_i32 v234, v25, 0, v233
	v_subrev_u32_e32 v25, 56, v24
	s_mov_b32 s1, 0
	v_lshlrev_b32_e32 v3, 1, v2
	v_and_b32_e32 v20, 48, v177
	v_and_b32_e32 v21, 24, v229
	v_mul_u32_u24_e32 v6, 0x2080, v6
	v_mov_b32_e32 v7, v1
	v_mul_u32_u24_e32 v8, 0x2080, v8
	v_mov_b32_e32 v9, v1
	v_mul_u32_u24_e32 v10, 0x2080, v10
	v_mov_b32_e32 v11, v1
	v_mul_u32_u24_e32 v12, 0x2080, v12
	v_mov_b32_e32 v13, v1
	v_mul_u32_u24_e32 v14, 0x2080, v14
	v_mov_b32_e32 v15, v1
	v_mul_u32_u24_e32 v16, 0x2080, v16
	v_mov_b32_e32 v17, v1
	v_mul_u32_u24_e32 v18, 0x2080, v18
	v_mov_b32_e32 v19, v1
	v_med3_i32 v235, v25, 0, v233
	v_subrev_u32_e32 v25, 48, v24
	v_subrev_u32_e32 v24, 40, v24
	s_movk_i32 s0, 0xff80
	v_lshlrev_b32_e32 v182, 1, v4
	v_lshlrev_b64 v[184:185], 1, v[0:1]
	s_mov_b32 s42, 2.0
	s_mov_b32 s44, 0x41800000
	s_mov_b32 s48, 0x41900000
	v_mbcnt_lo_u32_b32 v0, -1, 0
	v_med3_i32 v236, v25, 0, v233
	v_med3_i32 v237, v24, 0, v233
	v_lshlrev_b32_e32 v238, 1, v227
	v_and_or_b32 v239, v232, s0, v157
	v_or_b32_e32 v240, 16, v230
	v_cmp_gt_u32_e64 s[6:7], 16, v129
	s_mov_b32 s13, s1
	v_lshlrev_b32_e32 v180, 1, v2
	s_mov_b64 s[14:15], 0x2800
	s_mov_b64 s[16:17], 0x2000
	s_movk_i32 s80, 0x2000
	s_mov_b32 s81, 0x43000
	v_lshlrev_b64 v[186:187], 1, v[6:7]
	v_lshlrev_b64 v[188:189], 1, v[8:9]
	v_lshlrev_b64 v[190:191], 1, v[10:11]
	v_lshlrev_b64 v[192:193], 1, v[12:13]
	v_lshlrev_b64 v[194:195], 1, v[14:15]
	v_lshlrev_b64 v[196:197], 1, v[16:17]
	v_lshlrev_b64 v[198:199], 1, v[18:19]
	s_movk_i32 s84, 0x110
	s_mov_b64 s[18:19], 0x3800
	s_mov_b32 s40, 0x3e38aa3b
	s_mov_b32 s43, 0x40400000
	s_mov_b32 s45, 0x41880000
	s_mov_b32 s49, 0x41980000
	s_mov_b32 s85, 0xff800000
	s_mov_b64 s[54:55], 0x4a00800
	v_mov_b32_e32 v200, 1.0
	s_mov_b32 s86, 0x4a00000
	v_mov_b32_e32 v241, 0x42800000
	v_mov_b32_e32 v181, v1
	v_mov_b32_e32 v202, v182
	v_mov_b32_e32 v203, v1
	v_add_u32_e32 v242, v5, v3
	v_add_u32_e32 v243, v22, v20
	v_add_u32_e32 v244, v23, v21
	v_mov_b32_e32 v245, 0xff800000
	v_mbcnt_hi_u32_b32 v246, -1, v0
	v_readlane_b32 s87, v254, 2
	s_nop 3
	s_branch .LBB0_386
.Ldc_do:
	v_writelane_b32 v254, s87, 2
	v_writelane_b32 v254, 1, 1
	s_waitcnt vmcnt(0) lgkmcnt(0)
	s_barrier
	v_readlane_b32 s78, v254, 3
	v_readlane_b32 s79, v254, 4
	v_readlane_b32 s80, v254, 5
	v_readlane_b32 s81, v254, 6
	s_mov_b64 s[6:7], -1
	s_nop 7
	s_branch .Lp3_reentry

; DI void phase3(const Params& p, LAS unsigned char* lds) {
;     ...
;         for (int k2 = 0; k2 < 4; ++k2) attn_block(p, lds, x * 8 + 2 * k2 + (lb >> 4), lb & 15, wid, lane);
.LBB0_386:
	v_readlane_b32 s0, v254, 1
	v_readlane_b32 s8, v254, 0
	s_nop 3
	s_cmp_lg_u32 s0, 0
	s_cbranch_scc1 .Ldc_no
	s_cmp_lg_u32 s8, s87
	s_cbranch_scc1 .Ldc_no
	s_branch .Ldc_do

; DI void phase3(const Params& p, LAS unsigned char* lds) {
;     ...
;         for (int k2 = 0; k2 < 4; ++k2) attn_block(p, lds, x * 8 + 2 * k2 + (lb >> 4), lb & 15, wid, lane);
;         __syncthreads();
.LBB0_539:
	s_waitcnt lgkmcnt(0)
	s_barrier
	v_readlane_b32 s0, v254, 1
	s_nop 3
	s_cmp_eq_u32 s0, 3
	s_cbranch_scc1 .Lp3_skip_c
	s_cmp_eq_u32 s0, 0
	s_cbranch_scc0 .Lp3_orig_c
	s_branch .Ldc_do

; DI void phase3(const Params& p, LAS unsigned char* lds) {
;     ...
;         for (int k2 = 0; k2 < 4; ++k2) attn_block(p, lds, x * 8 + 2 * k2 + (lb >> 4), lb & 15, wid, lane);
;         __syncthreads();
;     } else
;         for (int it = gw; it < 16384; it += NGW) attn_item(p, wl, it, lane);
;     for (int it = gw; it < 4096; it += NGW) conv_item(p, it, lane);
.LBB0_546:
	s_or_b64 exec, exec, s[0:1]
	v_readlane_b32 s80, v254, 1
	s_nop 3
	s_cmp_lg_u32 s80, 2
	s_cbranch_scc1 .Lp3_c_cont
	v_writelane_b32 v254, 3, 1
	v_readlane_b32 s80, v254, 2
	s_nop 3
	s_cmp_ge_u32 s80, 4
	s_cbranch_scc1 .Lp3_c_cont
	v_and_b32_e32 v129, 63, v177
	v_ashrrev_i32_e32 v227, 6, v177
	v_bfe_u32 v157, v177, 6, 2
	v_lshrrev_b32_e32 v159, 4, v129
	v_lshlrev_b32_e32 v229, 3, v129
	s_branch .LBB0_384
